# row1 wave sum: DPP row rotates plus four readlanes instead of a six-step ds_bpermute butterfly
# baseline (speedup 1.0000x reference)
; DI void row1_phase(const Params& P, int combine_l, int norm_l, int r_begin) {
;     ...
;   auto load_row = [&](int r, float4 (&xv)[4], h4 (&ya)[4], h4 (&yb)[4]) {
;     if (combine_l < 0) {
;       const float* src = r < TC ? P.ctx + (size_t)r * D : P.x + (size_t)(r - TC) * D;
; #pragma unroll
;       for (int i = 0; i < 4; i++) xv[i] = *(const float4*)(src + i * 256 + lane * 4);
;     } else {
;       const float* xm = r < TC ? P.xcbuf + (size_t)r * D : P.out + (size_t)(r - TC) * D;
;       const half_t* y0 = P.yA + (size_t)(2 * r) * D; const half_t* y1 = y0 + D;
; #pragma unroll
;       for (int i = 0; i < 4; i++) { int c = i * 256 + lane * 4; xv[i] = *(const float4*)(xm + c); ya[i] = *(const h4*)(y0 + c); yb[i] = *(const h4*)(y1 + c); }
;     }
;   };
;   auto process = [&](int r, float4 (&xv)[4], h4 (&ya)[4], h4 (&yb)[4]) {
;     const int n = row_mod(r);
;     if (combine_l >= 0) {
;       float* xm = r < TC ? P.xcbuf + (size_t)r * D : P.out + (size_t)(r - TC) * D;
;       const float* g2 = P.mod + (size_t)(combine_l * 9 + n) * 6144 + 5 * 1024;
; #pragma unroll
;       for (int i = 0; i < 4; i++) {
;         int c = i * 256 + lane * 4;
;         float4 g = *(const float4*)(g2 + c); float4 t = xv[i];
;         t.x += g.x * ((float)ya[i][0] + (float)yb[i][0]); t.y += g.y * ((float)ya[i][1] + (float)yb[i][1]);
;         t.z += g.z * ((float)ya[i][2] + (float)yb[i][2]); t.w += g.w * ((float)ya[i][3] + (float)yb[i][3]);
;         *(float4*)(xm + c) = t; xv[i] = t;
;       }
;     }
;     if (norm_l >= 0) {
;       float ss = 0.f;
; #pragma unroll
;       for (int i = 0; i < 4; i++) ss += xv[i].x * xv[i].x + xv[i].y * xv[i].y + xv[i].z * xv[i].z + xv[i].w * xv[i].w;
.Lr1b_nr1:
	s_waitcnt vmcnt(44)
	v_accvgpr_read_b32 v54, a0
	v_accvgpr_read_b32 v55, a1
	v_accvgpr_read_b32 v56, a2
	v_accvgpr_read_b32 v57, a3
	v_accvgpr_read_b32 v58, a4
	v_accvgpr_read_b32 v59, a5
	v_accvgpr_read_b32 v60, a6
	v_accvgpr_read_b32 v61, a7
	v_accvgpr_read_b32 v62, a8
	v_accvgpr_read_b32 v63, a9
	v_accvgpr_read_b32 v64, a10
	v_accvgpr_read_b32 v65, a11
	v_accvgpr_read_b32 v66, a12
	v_accvgpr_read_b32 v67, a13
	v_accvgpr_read_b32 v68, a14
	v_accvgpr_read_b32 v69, a15
	v_accvgpr_read_b32 v70, a16
	v_accvgpr_read_b32 v71, a17
	v_accvgpr_read_b32 v72, a18
	v_accvgpr_read_b32 v73, a19
	v_accvgpr_read_b32 v74, a20
	v_accvgpr_read_b32 v75, a21
	v_accvgpr_read_b32 v76, a22
	v_accvgpr_read_b32 v77, a23
	v_accvgpr_read_b32 v78, a24
	v_accvgpr_read_b32 v79, a25
	v_accvgpr_read_b32 v80, a26
	v_accvgpr_read_b32 v81, a27
	v_accvgpr_read_b32 v82, a28
	v_accvgpr_read_b32 v83, a29
	v_accvgpr_read_b32 v84, a30
	v_accvgpr_read_b32 v85, a31
	s_lshl_b32 s10, s5, 12
	s_cmp_lt_u32 s5, 0x800
	s_cselect_b64 s[34:35], s[48:49], s[50:51]
	s_add_u32 s34, s34, s10
	s_addc_u32 s35, s35, 0
	s_lshr_b32 s10, s10, 1
	s_add_u32 s36, s54, s10
	s_addc_u32 s37, s55, 0
	s_cmp_lt_u32 s7, 0x800
	s_cselect_b64 s[60:61], s[48:49], s[50:51]
	s_lshl_b32 s10, s7, 12
	s_add_u32 s60, s60, s10
	s_addc_u32 s61, s61, 0
	global_load_dwordx4 a[0:3], v150, s[60:61] offset:0 nt
	global_load_dwordx4 a[4:7], v150, s[60:61] offset:1024 nt
	global_load_dwordx4 a[8:11], v150, s[60:61] offset:2048 nt
	global_load_dwordx4 a[12:15], v150, s[60:61] offset:3072 nt
	s_add_u32 s62, s52, s10
	s_addc_u32 s63, s53, 0
	global_load_dwordx2 a[16:17], v151, s[62:63] offset:0 nt
	global_load_dwordx2 a[18:19], v151, s[62:63] offset:512 nt
	global_load_dwordx2 a[20:21], v151, s[62:63] offset:1024 nt
	global_load_dwordx2 a[22:23], v151, s[62:63] offset:1536 nt
	global_load_dwordx2 a[24:25], v151, s[62:63] offset:2048 nt
	global_load_dwordx2 a[26:27], v151, s[62:63] offset:2560 nt
	global_load_dwordx2 a[28:29], v151, s[62:63] offset:3072 nt
	global_load_dwordx2 a[30:31], v151, s[62:63] offset:3584 nt
	s_add_u32 s7, s7, 1
	v_cvt_f32_f16_e32 v154, v70
	v_cvt_f32_f16_e32 v155, v78
	v_add_f32_e32 v154, v154, v155
	v_fmac_f32_e32 v54, v32, v154
	v_cvt_f32_f16_sdwa v156, v70 dst_sel:DWORD dst_unused:UNUSED_PAD src0_sel:WORD_1
	v_cvt_f32_f16_sdwa v157, v78 dst_sel:DWORD dst_unused:UNUSED_PAD src0_sel:WORD_1
	v_add_f32_e32 v156, v156, v157
	v_fmac_f32_e32 v55, v33, v156
	v_cvt_f32_f16_e32 v154, v71
	v_cvt_f32_f16_e32 v155, v79
	v_add_f32_e32 v154, v154, v155
	v_fmac_f32_e32 v56, v34, v154
	v_cvt_f32_f16_sdwa v156, v71 dst_sel:DWORD dst_unused:UNUSED_PAD src0_sel:WORD_1
	v_cvt_f32_f16_sdwa v157, v79 dst_sel:DWORD dst_unused:UNUSED_PAD src0_sel:WORD_1
	v_add_f32_e32 v156, v156, v157
	v_fmac_f32_e32 v57, v35, v156
	v_cvt_f32_f16_e32 v154, v72
	v_cvt_f32_f16_e32 v155, v80
	v_add_f32_e32 v154, v154, v155
	v_fmac_f32_e32 v58, v36, v154
	v_cvt_f32_f16_sdwa v156, v72 dst_sel:DWORD dst_unused:UNUSED_PAD src0_sel:WORD_1
	v_cvt_f32_f16_sdwa v157, v80 dst_sel:DWORD dst_unused:UNUSED_PAD src0_sel:WORD_1
	v_add_f32_e32 v156, v156, v157
	v_fmac_f32_e32 v59, v37, v156
	v_cvt_f32_f16_e32 v154, v73
	v_cvt_f32_f16_e32 v155, v81
	v_add_f32_e32 v154, v154, v155
	v_fmac_f32_e32 v60, v38, v154
	v_cvt_f32_f16_sdwa v156, v73 dst_sel:DWORD dst_unused:UNUSED_PAD src0_sel:WORD_1
	v_cvt_f32_f16_sdwa v157, v81 dst_sel:DWORD dst_unused:UNUSED_PAD src0_sel:WORD_1
	v_add_f32_e32 v156, v156, v157
	v_fmac_f32_e32 v61, v39, v156
	v_cvt_f32_f16_e32 v154, v74
	v_cvt_f32_f16_e32 v155, v82
	v_add_f32_e32 v154, v154, v155
	v_fmac_f32_e32 v62, v40, v154
	v_cvt_f32_f16_sdwa v156, v74 dst_sel:DWORD dst_unused:UNUSED_PAD src0_sel:WORD_1
	v_cvt_f32_f16_sdwa v157, v82 dst_sel:DWORD dst_unused:UNUSED_PAD src0_sel:WORD_1
	v_add_f32_e32 v156, v156, v157
	v_fmac_f32_e32 v63, v41, v156
	v_cvt_f32_f16_e32 v154, v75
	v_cvt_f32_f16_e32 v155, v83
	v_add_f32_e32 v154, v154, v155
	v_fmac_f32_e32 v64, v42, v154
	v_cvt_f32_f16_sdwa v156, v75 dst_sel:DWORD dst_unused:UNUSED_PAD src0_sel:WORD_1
	v_cvt_f32_f16_sdwa v157, v83 dst_sel:DWORD dst_unused:UNUSED_PAD src0_sel:WORD_1
	v_add_f32_e32 v156, v156, v157
	v_fmac_f32_e32 v65, v43, v156
	v_cvt_f32_f16_e32 v154, v76
	v_cvt_f32_f16_e32 v155, v84
	v_add_f32_e32 v154, v154, v155
	v_fmac_f32_e32 v66, v44, v154
	v_cvt_f32_f16_sdwa v156, v76 dst_sel:DWORD dst_unused:UNUSED_PAD src0_sel:WORD_1
	v_cvt_f32_f16_sdwa v157, v84 dst_sel:DWORD dst_unused:UNUSED_PAD src0_sel:WORD_1
	v_add_f32_e32 v156, v156, v157
	v_fmac_f32_e32 v67, v45, v156
	v_cvt_f32_f16_e32 v154, v77
	v_cvt_f32_f16_e32 v155, v85
	v_add_f32_e32 v154, v154, v155
	v_fmac_f32_e32 v68, v46, v154
	v_cvt_f32_f16_sdwa v156, v77 dst_sel:DWORD dst_unused:UNUSED_PAD src0_sel:WORD_1
	v_cvt_f32_f16_sdwa v157, v85 dst_sel:DWORD dst_unused:UNUSED_PAD src0_sel:WORD_1
	v_add_f32_e32 v156, v156, v157
	v_fmac_f32_e32 v69, v47, v156
	global_store_dwordx4 v150, v[54:57], s[34:35] offset:0
	global_store_dwordx4 v150, v[58:61], s[34:35] offset:1024
	global_store_dwordx4 v150, v[62:65], s[34:35] offset:2048
	global_store_dwordx4 v150, v[66:69], s[34:35] offset:3072
	v_mul_f32_e32 v152, v54, v54
	v_mul_f32_e32 v153, v55, v55
	v_fmac_f32_e32 v152, v56, v56
	v_fmac_f32_e32 v153, v57, v57
	v_fmac_f32_e32 v152, v58, v58
	v_fmac_f32_e32 v153, v59, v59
	v_fmac_f32_e32 v152, v60, v60
	v_fmac_f32_e32 v153, v61, v61
	v_fmac_f32_e32 v152, v62, v62
	v_fmac_f32_e32 v153, v63, v63
	v_fmac_f32_e32 v152, v64, v64
	v_fmac_f32_e32 v153, v65, v65
	v_fmac_f32_e32 v152, v66, v66
	v_fmac_f32_e32 v153, v67, v67
	v_fmac_f32_e32 v152, v68, v68
	v_fmac_f32_e32 v153, v69, v69
	v_add_f32_e32 v152, v152, v153
; DI float shx(float v, int o) { int ln = TIDX & 63; return __builtin_bit_cast(float, __builtin_amdgcn_ds_bpermute((ln ^ o) << 2, __builtin_bit_cast(int, v))); }
; DI float wave_sum(float v) {
; #pragma unroll
;   for (int o = 32; o; o >>= 1) v += shx(v, o);
;   return v;
; }
; DI void row1_phase(const Params& P, int combine_l, int norm_l, int r_begin) {
;     ...
;     if (norm_l >= 0) {
;       float ss = 0.f;
; #pragma unroll
;       for (int i = 0; i < 4; i++) ss += xv[i].x * xv[i].x + xv[i].y * xv[i].y + xv[i].z * xv[i].z + xv[i].w * xv[i].w;
;       ss = wave_sum(ss);
;       const float rstd = rsqrtf(ss * (1.f / 1024.f) + EPS);
;       const float* g = P.norm1_g + norm_l * 1024;
;       const float* sh = P.mod + (size_t)(norm_l * 9 + n) * 6144; const float* sc = sh + 1024;
; #pragma unroll
;       for (int i = 0; i < 4; i++) {
;         int c = i * 256 + lane * 4;
;         float4 gg = *(const float4*)(g + c), s1 = *(const float4*)(sc + c), s0 = *(const float4*)(sh + c);
;         h4 o;
;         o[0] = (half_t)(xv[i].x * rstd * gg.x * (1.f + s1.x) + s0.x); o[1] = (half_t)(xv[i].y * rstd * gg.y * (1.f + s1.y) + s0.y);
;         o[2] = (half_t)(xv[i].z * rstd * gg.z * (1.f + s1.z) + s0.z); o[3] = (half_t)(xv[i].w * rstd * gg.w * (1.f + s1.w) + s0.w);
;         *(h4*)(P.hx + (size_t)r * D + c) = o;
;       }
;     }
	s_nop 1
	v_add_f32_dpp v152, v152, v152 row_ror:8 row_mask:0xf bank_mask:0xf
	s_nop 1
	v_add_f32_dpp v152, v152, v152 row_ror:4 row_mask:0xf bank_mask:0xf
	s_nop 1
	v_add_f32_dpp v152, v152, v152 row_ror:2 row_mask:0xf bank_mask:0xf
	s_nop 1
	v_add_f32_dpp v152, v152, v152 row_ror:1 row_mask:0xf bank_mask:0xf
	s_nop 1
	v_readlane_b32 s22, v152, 0
	v_readlane_b32 s23, v152, 16
	v_readlane_b32 s32, v152, 32
	v_readlane_b32 s99, v152, 48
	v_mov_b32_e32 v152, s22
	v_add_f32_e32 v152, s23, v152
	v_add_f32_e32 v152, s32, v152
	v_add_f32_e32 v152, s99, v152
	v_mov_b32_e32 v153, 0x358637bd
	v_fmamk_f32 v152, v152, 0x3a800000, v153
	v_rsq_f32_e32 v152, v152
	s_nop 1
	v_mul_f32_e32 v54, v54, v152
	v_mul_f32_e32 v55, v55, v152
	v_mul_f32_e32 v56, v56, v152
	v_mul_f32_e32 v57, v57, v152
	v_mul_f32_e32 v58, v58, v152
	v_mul_f32_e32 v59, v59, v152
	v_mul_f32_e32 v60, v60, v152
	v_mul_f32_e32 v61, v61, v152
	v_mul_f32_e32 v62, v62, v152
	v_mul_f32_e32 v63, v63, v152
	v_mul_f32_e32 v64, v64, v152
	v_mul_f32_e32 v65, v65, v152
	v_mul_f32_e32 v66, v66, v152
	v_mul_f32_e32 v67, v67, v152
	v_mul_f32_e32 v68, v68, v152
	v_mul_f32_e32 v69, v69, v152
	v_fma_f32 v54, v54, v0, v16
	v_fma_f32 v55, v55, v1, v17
	v_fma_f32 v56, v56, v2, v18
	v_fma_f32 v57, v57, v3, v19
	v_fma_f32 v58, v58, v4, v20
	v_fma_f32 v59, v59, v5, v21
	v_fma_f32 v60, v60, v6, v22
	v_fma_f32 v61, v61, v7, v23
	v_fma_f32 v62, v62, v8, v24
	v_fma_f32 v63, v63, v9, v25
	v_fma_f32 v64, v64, v10, v26
	v_fma_f32 v65, v65, v11, v27
	v_fma_f32 v66, v66, v12, v28
	v_fma_f32 v67, v67, v13, v29
	v_fma_f32 v68, v68, v14, v30
	v_fma_f32 v69, v69, v15, v31
	v_cvt_pk_f16_f32 v70, v54, v55
	v_cvt_pk_f16_f32 v71, v56, v57
	v_cvt_pk_f16_f32 v72, v58, v59
	v_cvt_pk_f16_f32 v73, v60, v61
	v_cvt_pk_f16_f32 v74, v62, v63
	v_cvt_pk_f16_f32 v75, v64, v65
	v_cvt_pk_f16_f32 v76, v66, v67
	v_cvt_pk_f16_f32 v77, v68, v69
	global_store_dwordx2 v151, v[70:71], s[36:37] offset:0
	global_store_dwordx2 v151, v[72:73], s[36:37] offset:512
	global_store_dwordx2 v151, v[74:75], s[36:37] offset:1024
	global_store_dwordx2 v151, v[76:77], s[36:37] offset:1536
	s_add_u32 s5, s5, 1
	s_sub_u32 s9, s5, 0x800
	s_lshr_b32 s9, s9, 13
	s_cmp_lt_u32 s5, 0x800
	s_cselect_b32 s9, 8, s9
	s_cmp_eq_u32 s9, s8
	s_cbranch_scc1 .Lr1b_nr2
	s_mov_b32 s8, s9
	s_waitcnt vmcnt(0)
	s_add_u32 s10, s9, 9
	s_mul_i32 s10, s10, 0x6000
	s_add_u32 s38, s56, s10
	s_addc_u32 s39, s57, 0
	global_load_dwordx4 v[54:57], v150, s[58:59] offset:0
	global_load_dwordx4 v[58:61], v150, s[58:59] offset:1024
	global_load_dwordx4 v[62:65], v150, s[58:59] offset:2048
	global_load_dwordx4 v[66:69], v150, s[58:59] offset:3072
	s_add_u32 s44, s38, 0x1000
	s_addc_u32 s45, s39, 0
	global_load_dwordx4 v[70:73], v150, s[44:45] offset:0
	global_load_dwordx4 v[74:77], v150, s[44:45] offset:1024
	global_load_dwordx4 v[78:81], v150, s[44:45] offset:2048
	global_load_dwordx4 v[82:85], v150, s[44:45] offset:3072
	global_load_dwordx4 v[16:19], v150, s[38:39] offset:0
	global_load_dwordx4 v[20:23], v150, s[38:39] offset:1024
	global_load_dwordx4 v[24:27], v150, s[38:39] offset:2048
	global_load_dwordx4 v[28:31], v150, s[38:39] offset:3072
	s_add_u32 s10, s9, 0
	s_mul_i32 s10, s10, 0x6000
	s_add_u32 s10, s10, 0x5000
	s_add_u32 s38, s56, s10
	s_addc_u32 s39, s57, 0
	global_load_dwordx4 v[32:35], v150, s[38:39] offset:0
	global_load_dwordx4 v[36:39], v150, s[38:39] offset:1024
	global_load_dwordx4 v[40:43], v150, s[38:39] offset:2048
	global_load_dwordx4 v[44:47], v150, s[38:39] offset:3072
	s_waitcnt vmcnt(0)
	v_add_f32_e32 v70, 1.0, v70
	v_add_f32_e32 v71, 1.0, v71
	v_add_f32_e32 v72, 1.0, v72
	v_add_f32_e32 v73, 1.0, v73
	v_add_f32_e32 v74, 1.0, v74
	v_add_f32_e32 v75, 1.0, v75
	v_add_f32_e32 v76, 1.0, v76
	v_add_f32_e32 v77, 1.0, v77
	v_add_f32_e32 v78, 1.0, v78
	v_add_f32_e32 v79, 1.0, v79
	v_add_f32_e32 v80, 1.0, v80
	v_add_f32_e32 v81, 1.0, v81
	v_add_f32_e32 v82, 1.0, v82
	v_add_f32_e32 v83, 1.0, v83
	v_add_f32_e32 v84, 1.0, v84
	v_add_f32_e32 v85, 1.0, v85
	v_mul_f32_e32 v0, v54, v70
	v_mul_f32_e32 v1, v55, v71
	v_mul_f32_e32 v2, v56, v72
	v_mul_f32_e32 v3, v57, v73
	v_mul_f32_e32 v4, v58, v74
	v_mul_f32_e32 v5, v59, v75
	v_mul_f32_e32 v6, v60, v76
	v_mul_f32_e32 v7, v61, v77
	v_mul_f32_e32 v8, v62, v78
	v_mul_f32_e32 v9, v63, v79
	v_mul_f32_e32 v10, v64, v80
	v_mul_f32_e32 v11, v65, v81
	v_mul_f32_e32 v12, v66, v82
	v_mul_f32_e32 v13, v67, v83
	v_mul_f32_e32 v14, v68, v84
	v_mul_f32_e32 v15, v69, v85
; DI void row1_phase(const Params& P, int combine_l, int norm_l, int r_begin) {
;     ...
;   auto load_row = [&](int r, float4 (&xv)[4], h4 (&ya)[4], h4 (&yb)[4]) {
;     if (combine_l < 0) {
;       const float* src = r < TC ? P.ctx + (size_t)r * D : P.x + (size_t)(r - TC) * D;
; #pragma unroll
;       for (int i = 0; i < 4; i++) xv[i] = *(const float4*)(src + i * 256 + lane * 4);
;     } else {
;       const float* xm = r < TC ? P.xcbuf + (size_t)r * D : P.out + (size_t)(r - TC) * D;
;       const half_t* y0 = P.yA + (size_t)(2 * r) * D; const half_t* y1 = y0 + D;
; #pragma unroll
;       for (int i = 0; i < 4; i++) { int c = i * 256 + lane * 4; xv[i] = *(const float4*)(xm + c); ya[i] = *(const h4*)(y0 + c); yb[i] = *(const h4*)(y1 + c); }
;     }
;   };
;   auto process = [&](int r, float4 (&xv)[4], h4 (&ya)[4], h4 (&yb)[4]) {
;     const int n = row_mod(r);
;     if (combine_l >= 0) {
;       float* xm = r < TC ? P.xcbuf + (size_t)r * D : P.out + (size_t)(r - TC) * D;
;       const float* g2 = P.mod + (size_t)(combine_l * 9 + n) * 6144 + 5 * 1024;
; #pragma unroll
;       for (int i = 0; i < 4; i++) {
;         int c = i * 256 + lane * 4;
;         float4 g = *(const float4*)(g2 + c); float4 t = xv[i];
;         t.x += g.x * ((float)ya[i][0] + (float)yb[i][0]); t.y += g.y * ((float)ya[i][1] + (float)yb[i][1]);
;         t.z += g.z * ((float)ya[i][2] + (float)yb[i][2]); t.w += g.w * ((float)ya[i][3] + (float)yb[i][3]);
;         *(float4*)(xm + c) = t; xv[i] = t;
;       }
;     }
;     if (norm_l >= 0) {
;       float ss = 0.f;
; #pragma unroll
;       for (int i = 0; i < 4; i++) ss += xv[i].x * xv[i].x + xv[i].y * xv[i].y + xv[i].z * xv[i].z + xv[i].w * xv[i].w;
.Lr1b_nr2:
	s_waitcnt vmcnt(44)
	v_accvgpr_read_b32 v54, a32
	v_accvgpr_read_b32 v55, a33
	v_accvgpr_read_b32 v56, a34
	v_accvgpr_read_b32 v57, a35
	v_accvgpr_read_b32 v58, a36
	v_accvgpr_read_b32 v59, a37
	v_accvgpr_read_b32 v60, a38
	v_accvgpr_read_b32 v61, a39
	v_accvgpr_read_b32 v62, a40
	v_accvgpr_read_b32 v63, a41
	v_accvgpr_read_b32 v64, a42
	v_accvgpr_read_b32 v65, a43
	v_accvgpr_read_b32 v66, a44
	v_accvgpr_read_b32 v67, a45
	v_accvgpr_read_b32 v68, a46
	v_accvgpr_read_b32 v69, a47
	v_accvgpr_read_b32 v70, a48
	v_accvgpr_read_b32 v71, a49
	v_accvgpr_read_b32 v72, a50
	v_accvgpr_read_b32 v73, a51
	v_accvgpr_read_b32 v74, a52
	v_accvgpr_read_b32 v75, a53
	v_accvgpr_read_b32 v76, a54
	v_accvgpr_read_b32 v77, a55
	v_accvgpr_read_b32 v78, a56
	v_accvgpr_read_b32 v79, a57
	v_accvgpr_read_b32 v80, a58
	v_accvgpr_read_b32 v81, a59
	v_accvgpr_read_b32 v82, a60
	v_accvgpr_read_b32 v83, a61
	v_accvgpr_read_b32 v84, a62
	v_accvgpr_read_b32 v85, a63
	s_lshl_b32 s10, s5, 12
	s_cmp_lt_u32 s5, 0x800
	s_cselect_b64 s[34:35], s[48:49], s[50:51]
	s_add_u32 s34, s34, s10
	s_addc_u32 s35, s35, 0
	s_lshr_b32 s10, s10, 1
	s_add_u32 s36, s54, s10
	s_addc_u32 s37, s55, 0
	s_cmp_lt_u32 s7, 0x800
	s_cselect_b64 s[60:61], s[48:49], s[50:51]
	s_lshl_b32 s10, s7, 12
	s_add_u32 s60, s60, s10
	s_addc_u32 s61, s61, 0
	global_load_dwordx4 a[32:35], v150, s[60:61] offset:0 nt
	global_load_dwordx4 a[36:39], v150, s[60:61] offset:1024 nt
	global_load_dwordx4 a[40:43], v150, s[60:61] offset:2048 nt
	global_load_dwordx4 a[44:47], v150, s[60:61] offset:3072 nt
	s_add_u32 s62, s52, s10
	s_addc_u32 s63, s53, 0
	global_load_dwordx2 a[48:49], v151, s[62:63] offset:0 nt
	global_load_dwordx2 a[50:51], v151, s[62:63] offset:512 nt
	global_load_dwordx2 a[52:53], v151, s[62:63] offset:1024 nt
	global_load_dwordx2 a[54:55], v151, s[62:63] offset:1536 nt
	global_load_dwordx2 a[56:57], v151, s[62:63] offset:2048 nt
	global_load_dwordx2 a[58:59], v151, s[62:63] offset:2560 nt
	global_load_dwordx2 a[60:61], v151, s[62:63] offset:3072 nt
	global_load_dwordx2 a[62:63], v151, s[62:63] offset:3584 nt
	s_add_u32 s7, s7, 1
	v_cvt_f32_f16_e32 v154, v70
	v_cvt_f32_f16_e32 v155, v78
	v_add_f32_e32 v154, v154, v155
	v_fmac_f32_e32 v54, v32, v154
	v_cvt_f32_f16_sdwa v156, v70 dst_sel:DWORD dst_unused:UNUSED_PAD src0_sel:WORD_1
	v_cvt_f32_f16_sdwa v157, v78 dst_sel:DWORD dst_unused:UNUSED_PAD src0_sel:WORD_1
	v_add_f32_e32 v156, v156, v157
	v_fmac_f32_e32 v55, v33, v156
	v_cvt_f32_f16_e32 v154, v71
	v_cvt_f32_f16_e32 v155, v79
	v_add_f32_e32 v154, v154, v155
	v_fmac_f32_e32 v56, v34, v154
	v_cvt_f32_f16_sdwa v156, v71 dst_sel:DWORD dst_unused:UNUSED_PAD src0_sel:WORD_1
	v_cvt_f32_f16_sdwa v157, v79 dst_sel:DWORD dst_unused:UNUSED_PAD src0_sel:WORD_1
	v_add_f32_e32 v156, v156, v157
	v_fmac_f32_e32 v57, v35, v156
	v_cvt_f32_f16_e32 v154, v72
	v_cvt_f32_f16_e32 v155, v80
	v_add_f32_e32 v154, v154, v155
	v_fmac_f32_e32 v58, v36, v154
	v_cvt_f32_f16_sdwa v156, v72 dst_sel:DWORD dst_unused:UNUSED_PAD src0_sel:WORD_1
	v_cvt_f32_f16_sdwa v157, v80 dst_sel:DWORD dst_unused:UNUSED_PAD src0_sel:WORD_1
	v_add_f32_e32 v156, v156, v157
	v_fmac_f32_e32 v59, v37, v156
	v_cvt_f32_f16_e32 v154, v73
	v_cvt_f32_f16_e32 v155, v81
	v_add_f32_e32 v154, v154, v155
	v_fmac_f32_e32 v60, v38, v154
	v_cvt_f32_f16_sdwa v156, v73 dst_sel:DWORD dst_unused:UNUSED_PAD src0_sel:WORD_1
	v_cvt_f32_f16_sdwa v157, v81 dst_sel:DWORD dst_unused:UNUSED_PAD src0_sel:WORD_1
	v_add_f32_e32 v156, v156, v157
	v_fmac_f32_e32 v61, v39, v156
	v_cvt_f32_f16_e32 v154, v74
	v_cvt_f32_f16_e32 v155, v82
	v_add_f32_e32 v154, v154, v155
	v_fmac_f32_e32 v62, v40, v154
	v_cvt_f32_f16_sdwa v156, v74 dst_sel:DWORD dst_unused:UNUSED_PAD src0_sel:WORD_1
	v_cvt_f32_f16_sdwa v157, v82 dst_sel:DWORD dst_unused:UNUSED_PAD src0_sel:WORD_1
	v_add_f32_e32 v156, v156, v157
	v_fmac_f32_e32 v63, v41, v156
	v_cvt_f32_f16_e32 v154, v75
	v_cvt_f32_f16_e32 v155, v83
	v_add_f32_e32 v154, v154, v155
	v_fmac_f32_e32 v64, v42, v154
	v_cvt_f32_f16_sdwa v156, v75 dst_sel:DWORD dst_unused:UNUSED_PAD src0_sel:WORD_1
	v_cvt_f32_f16_sdwa v157, v83 dst_sel:DWORD dst_unused:UNUSED_PAD src0_sel:WORD_1
	v_add_f32_e32 v156, v156, v157
	v_fmac_f32_e32 v65, v43, v156
	v_cvt_f32_f16_e32 v154, v76
	v_cvt_f32_f16_e32 v155, v84
	v_add_f32_e32 v154, v154, v155
	v_fmac_f32_e32 v66, v44, v154
	v_cvt_f32_f16_sdwa v156, v76 dst_sel:DWORD dst_unused:UNUSED_PAD src0_sel:WORD_1
	v_cvt_f32_f16_sdwa v157, v84 dst_sel:DWORD dst_unused:UNUSED_PAD src0_sel:WORD_1
	v_add_f32_e32 v156, v156, v157
	v_fmac_f32_e32 v67, v45, v156
	v_cvt_f32_f16_e32 v154, v77
	v_cvt_f32_f16_e32 v155, v85
	v_add_f32_e32 v154, v154, v155
	v_fmac_f32_e32 v68, v46, v154
	v_cvt_f32_f16_sdwa v156, v77 dst_sel:DWORD dst_unused:UNUSED_PAD src0_sel:WORD_1
	v_cvt_f32_f16_sdwa v157, v85 dst_sel:DWORD dst_unused:UNUSED_PAD src0_sel:WORD_1
	v_add_f32_e32 v156, v156, v157
	v_fmac_f32_e32 v69, v47, v156
	global_store_dwordx4 v150, v[54:57], s[34:35] offset:0
	global_store_dwordx4 v150, v[58:61], s[34:35] offset:1024
	global_store_dwordx4 v150, v[62:65], s[34:35] offset:2048
	global_store_dwordx4 v150, v[66:69], s[34:35] offset:3072
	v_mul_f32_e32 v152, v54, v54
	v_mul_f32_e32 v153, v55, v55
	v_fmac_f32_e32 v152, v56, v56
	v_fmac_f32_e32 v153, v57, v57
	v_fmac_f32_e32 v152, v58, v58
	v_fmac_f32_e32 v153, v59, v59
	v_fmac_f32_e32 v152, v60, v60
	v_fmac_f32_e32 v153, v61, v61
	v_fmac_f32_e32 v152, v62, v62
	v_fmac_f32_e32 v153, v63, v63
	v_fmac_f32_e32 v152, v64, v64
	v_fmac_f32_e32 v153, v65, v65
	v_fmac_f32_e32 v152, v66, v66
	v_fmac_f32_e32 v153, v67, v67
	v_fmac_f32_e32 v152, v68, v68
	v_fmac_f32_e32 v153, v69, v69
	v_add_f32_e32 v152, v152, v153
; DI float shx(float v, int o) { int ln = TIDX & 63; return __builtin_bit_cast(float, __builtin_amdgcn_ds_bpermute((ln ^ o) << 2, __builtin_bit_cast(int, v))); }
; DI float wave_sum(float v) {
; #pragma unroll
;   for (int o = 32; o; o >>= 1) v += shx(v, o);
;   return v;
; }
; DI void row1_phase(const Params& P, int combine_l, int norm_l, int r_begin) {
;     ...
;     if (norm_l >= 0) {
;       float ss = 0.f;
; #pragma unroll
;       for (int i = 0; i < 4; i++) ss += xv[i].x * xv[i].x + xv[i].y * xv[i].y + xv[i].z * xv[i].z + xv[i].w * xv[i].w;
;       ss = wave_sum(ss);
;       const float rstd = rsqrtf(ss * (1.f / 1024.f) + EPS);
;       const float* g = P.norm1_g + norm_l * 1024;
;       const float* sh = P.mod + (size_t)(norm_l * 9 + n) * 6144; const float* sc = sh + 1024;
; #pragma unroll
;       for (int i = 0; i < 4; i++) {
;         int c = i * 256 + lane * 4;
;         float4 gg = *(const float4*)(g + c), s1 = *(const float4*)(sc + c), s0 = *(const float4*)(sh + c);
;         h4 o;
;         o[0] = (half_t)(xv[i].x * rstd * gg.x * (1.f + s1.x) + s0.x); o[1] = (half_t)(xv[i].y * rstd * gg.y * (1.f + s1.y) + s0.y);
;         o[2] = (half_t)(xv[i].z * rstd * gg.z * (1.f + s1.z) + s0.z); o[3] = (half_t)(xv[i].w * rstd * gg.w * (1.f + s1.w) + s0.w);
;         *(h4*)(P.hx + (size_t)r * D + c) = o;
;       }
;     }
	s_nop 1
	v_add_f32_dpp v152, v152, v152 row_ror:8 row_mask:0xf bank_mask:0xf
	s_nop 1
	v_add_f32_dpp v152, v152, v152 row_ror:4 row_mask:0xf bank_mask:0xf
	s_nop 1
	v_add_f32_dpp v152, v152, v152 row_ror:2 row_mask:0xf bank_mask:0xf
	s_nop 1
	v_add_f32_dpp v152, v152, v152 row_ror:1 row_mask:0xf bank_mask:0xf
	s_nop 1
	v_readlane_b32 s22, v152, 0
	v_readlane_b32 s23, v152, 16
	v_readlane_b32 s32, v152, 32
	v_readlane_b32 s99, v152, 48
	v_mov_b32_e32 v152, s22
	v_add_f32_e32 v152, s23, v152
	v_add_f32_e32 v152, s32, v152
	v_add_f32_e32 v152, s99, v152
	v_mov_b32_e32 v153, 0x358637bd
	v_fmamk_f32 v152, v152, 0x3a800000, v153
	v_rsq_f32_e32 v152, v152
	s_nop 1
	v_mul_f32_e32 v54, v54, v152
	v_mul_f32_e32 v55, v55, v152
	v_mul_f32_e32 v56, v56, v152
	v_mul_f32_e32 v57, v57, v152
	v_mul_f32_e32 v58, v58, v152
	v_mul_f32_e32 v59, v59, v152
	v_mul_f32_e32 v60, v60, v152
	v_mul_f32_e32 v61, v61, v152
	v_mul_f32_e32 v62, v62, v152
	v_mul_f32_e32 v63, v63, v152
	v_mul_f32_e32 v64, v64, v152
	v_mul_f32_e32 v65, v65, v152
	v_mul_f32_e32 v66, v66, v152
	v_mul_f32_e32 v67, v67, v152
	v_mul_f32_e32 v68, v68, v152
	v_mul_f32_e32 v69, v69, v152
	v_fma_f32 v54, v54, v0, v16
	v_fma_f32 v55, v55, v1, v17
	v_fma_f32 v56, v56, v2, v18
	v_fma_f32 v57, v57, v3, v19
	v_fma_f32 v58, v58, v4, v20
	v_fma_f32 v59, v59, v5, v21
	v_fma_f32 v60, v60, v6, v22
	v_fma_f32 v61, v61, v7, v23
	v_fma_f32 v62, v62, v8, v24
	v_fma_f32 v63, v63, v9, v25
	v_fma_f32 v64, v64, v10, v26
	v_fma_f32 v65, v65, v11, v27
	v_fma_f32 v66, v66, v12, v28
	v_fma_f32 v67, v67, v13, v29
	v_fma_f32 v68, v68, v14, v30
	v_fma_f32 v69, v69, v15, v31
	v_cvt_pk_f16_f32 v70, v54, v55
	v_cvt_pk_f16_f32 v71, v56, v57
	v_cvt_pk_f16_f32 v72, v58, v59
	v_cvt_pk_f16_f32 v73, v60, v61
	v_cvt_pk_f16_f32 v74, v62, v63
	v_cvt_pk_f16_f32 v75, v64, v65
	v_cvt_pk_f16_f32 v76, v66, v67
	v_cvt_pk_f16_f32 v77, v68, v69
	global_store_dwordx2 v151, v[70:71], s[36:37] offset:0
	global_store_dwordx2 v151, v[72:73], s[36:37] offset:512
	global_store_dwordx2 v151, v[74:75], s[36:37] offset:1024
	global_store_dwordx2 v151, v[76:77], s[36:37] offset:1536
	s_add_u32 s5, s5, 1
	s_sub_u32 s9, s5, 0x800
	s_lshr_b32 s9, s9, 13
	s_cmp_lt_u32 s5, 0x800
	s_cselect_b32 s9, 8, s9
	s_cmp_eq_u32 s9, s8
	s_cbranch_scc1 .Lr1b_nr3
	s_mov_b32 s8, s9
	s_waitcnt vmcnt(0)
	s_add_u32 s10, s9, 9
	s_mul_i32 s10, s10, 0x6000
	s_add_u32 s38, s56, s10
	s_addc_u32 s39, s57, 0
	global_load_dwordx4 v[54:57], v150, s[58:59] offset:0
	global_load_dwordx4 v[58:61], v150, s[58:59] offset:1024
	global_load_dwordx4 v[62:65], v150, s[58:59] offset:2048
	global_load_dwordx4 v[66:69], v150, s[58:59] offset:3072
	s_add_u32 s44, s38, 0x1000
	s_addc_u32 s45, s39, 0
	global_load_dwordx4 v[70:73], v150, s[44:45] offset:0
	global_load_dwordx4 v[74:77], v150, s[44:45] offset:1024
	global_load_dwordx4 v[78:81], v150, s[44:45] offset:2048
	global_load_dwordx4 v[82:85], v150, s[44:45] offset:3072
	global_load_dwordx4 v[16:19], v150, s[38:39] offset:0
	global_load_dwordx4 v[20:23], v150, s[38:39] offset:1024
	global_load_dwordx4 v[24:27], v150, s[38:39] offset:2048
	global_load_dwordx4 v[28:31], v150, s[38:39] offset:3072
	s_add_u32 s10, s9, 0
	s_mul_i32 s10, s10, 0x6000
	s_add_u32 s10, s10, 0x5000
	s_add_u32 s38, s56, s10
	s_addc_u32 s39, s57, 0
	global_load_dwordx4 v[32:35], v150, s[38:39] offset:0
	global_load_dwordx4 v[36:39], v150, s[38:39] offset:1024
	global_load_dwordx4 v[40:43], v150, s[38:39] offset:2048
	global_load_dwordx4 v[44:47], v150, s[38:39] offset:3072
	s_waitcnt vmcnt(0)
	v_add_f32_e32 v70, 1.0, v70
	v_add_f32_e32 v71, 1.0, v71
	v_add_f32_e32 v72, 1.0, v72
	v_add_f32_e32 v73, 1.0, v73
	v_add_f32_e32 v74, 1.0, v74
	v_add_f32_e32 v75, 1.0, v75
	v_add_f32_e32 v76, 1.0, v76
	v_add_f32_e32 v77, 1.0, v77
	v_add_f32_e32 v78, 1.0, v78
	v_add_f32_e32 v79, 1.0, v79
	v_add_f32_e32 v80, 1.0, v80
	v_add_f32_e32 v81, 1.0, v81
	v_add_f32_e32 v82, 1.0, v82
	v_add_f32_e32 v83, 1.0, v83
	v_add_f32_e32 v84, 1.0, v84
	v_add_f32_e32 v85, 1.0, v85
	v_mul_f32_e32 v0, v54, v70
	v_mul_f32_e32 v1, v55, v71
	v_mul_f32_e32 v2, v56, v72
	v_mul_f32_e32 v3, v57, v73
	v_mul_f32_e32 v4, v58, v74
	v_mul_f32_e32 v5, v59, v75
	v_mul_f32_e32 v6, v60, v76
	v_mul_f32_e32 v7, v61, v77
	v_mul_f32_e32 v8, v62, v78
	v_mul_f32_e32 v9, v63, v79
	v_mul_f32_e32 v10, v64, v80
	v_mul_f32_e32 v11, v65, v81
	v_mul_f32_e32 v12, v66, v82
	v_mul_f32_e32 v13, v67, v83
	v_mul_f32_e32 v14, v68, v84
	v_mul_f32_e32 v15, v69, v85
; DI void row1_phase(const Params& P, int combine_l, int norm_l, int r_begin) {
;     ...
;   auto load_row = [&](int r, float4 (&xv)[4], h4 (&ya)[4], h4 (&yb)[4]) {
;     if (combine_l < 0) {
;       const float* src = r < TC ? P.ctx + (size_t)r * D : P.x + (size_t)(r - TC) * D;
; #pragma unroll
;       for (int i = 0; i < 4; i++) xv[i] = *(const float4*)(src + i * 256 + lane * 4);
;     } else {
;       const float* xm = r < TC ? P.xcbuf + (size_t)r * D : P.out + (size_t)(r - TC) * D;
;       const half_t* y0 = P.yA + (size_t)(2 * r) * D; const half_t* y1 = y0 + D;
; #pragma unroll
;       for (int i = 0; i < 4; i++) { int c = i * 256 + lane * 4; xv[i] = *(const float4*)(xm + c); ya[i] = *(const h4*)(y0 + c); yb[i] = *(const h4*)(y1 + c); }
;     }
;   };
;   auto process = [&](int r, float4 (&xv)[4], h4 (&ya)[4], h4 (&yb)[4]) {
;     const int n = row_mod(r);
;     if (combine_l >= 0) {
;       float* xm = r < TC ? P.xcbuf + (size_t)r * D : P.out + (size_t)(r - TC) * D;
;       const float* g2 = P.mod + (size_t)(combine_l * 9 + n) * 6144 + 5 * 1024;
; #pragma unroll
;       for (int i = 0; i < 4; i++) {
;         int c = i * 256 + lane * 4;
;         float4 g = *(const float4*)(g2 + c); float4 t = xv[i];
;         t.x += g.x * ((float)ya[i][0] + (float)yb[i][0]); t.y += g.y * ((float)ya[i][1] + (float)yb[i][1]);
;         t.z += g.z * ((float)ya[i][2] + (float)yb[i][2]); t.w += g.w * ((float)ya[i][3] + (float)yb[i][3]);
;         *(float4*)(xm + c) = t; xv[i] = t;
;       }
;     }
;     if (norm_l >= 0) {
;       float ss = 0.f;
; #pragma unroll
;       for (int i = 0; i < 4; i++) ss += xv[i].x * xv[i].x + xv[i].y * xv[i].y + xv[i].z * xv[i].z + xv[i].w * xv[i].w;
.Lr1b_nr3:
	s_waitcnt vmcnt(44)
	v_accvgpr_read_b32 v54, a64
	v_accvgpr_read_b32 v55, a65
	v_accvgpr_read_b32 v56, a66
	v_accvgpr_read_b32 v57, a67
	v_accvgpr_read_b32 v58, a68
	v_accvgpr_read_b32 v59, a69
	v_accvgpr_read_b32 v60, a70
	v_accvgpr_read_b32 v61, a71
	v_accvgpr_read_b32 v62, a72
	v_accvgpr_read_b32 v63, a73
	v_accvgpr_read_b32 v64, a74
	v_accvgpr_read_b32 v65, a75
	v_accvgpr_read_b32 v66, a76
	v_accvgpr_read_b32 v67, a77
	v_accvgpr_read_b32 v68, a78
	v_accvgpr_read_b32 v69, a79
	v_accvgpr_read_b32 v70, a80
	v_accvgpr_read_b32 v71, a81
	v_accvgpr_read_b32 v72, a82
	v_accvgpr_read_b32 v73, a83
	v_accvgpr_read_b32 v74, a84
	v_accvgpr_read_b32 v75, a85
	v_accvgpr_read_b32 v76, a86
	v_accvgpr_read_b32 v77, a87
	v_accvgpr_read_b32 v78, a88
	v_accvgpr_read_b32 v79, a89
	v_accvgpr_read_b32 v80, a90
	v_accvgpr_read_b32 v81, a91
	v_accvgpr_read_b32 v82, a92
	v_accvgpr_read_b32 v83, a93
	v_accvgpr_read_b32 v84, a94
	v_accvgpr_read_b32 v85, a95
	s_lshl_b32 s10, s5, 12
	s_cmp_lt_u32 s5, 0x800
	s_cselect_b64 s[34:35], s[48:49], s[50:51]
	s_add_u32 s34, s34, s10
	s_addc_u32 s35, s35, 0
	s_lshr_b32 s10, s10, 1
	s_add_u32 s36, s54, s10
	s_addc_u32 s37, s55, 0
	s_cmp_lt_u32 s7, 0x800
	s_cselect_b64 s[60:61], s[48:49], s[50:51]
	s_lshl_b32 s10, s7, 12
	s_add_u32 s60, s60, s10
	s_addc_u32 s61, s61, 0
	global_load_dwordx4 a[64:67], v150, s[60:61] offset:0 nt
	global_load_dwordx4 a[68:71], v150, s[60:61] offset:1024 nt
	global_load_dwordx4 a[72:75], v150, s[60:61] offset:2048 nt
	global_load_dwordx4 a[76:79], v150, s[60:61] offset:3072 nt
	s_add_u32 s62, s52, s10
	s_addc_u32 s63, s53, 0
	global_load_dwordx2 a[80:81], v151, s[62:63] offset:0 nt
	global_load_dwordx2 a[82:83], v151, s[62:63] offset:512 nt
	global_load_dwordx2 a[84:85], v151, s[62:63] offset:1024 nt
	global_load_dwordx2 a[86:87], v151, s[62:63] offset:1536 nt
	global_load_dwordx2 a[88:89], v151, s[62:63] offset:2048 nt
	global_load_dwordx2 a[90:91], v151, s[62:63] offset:2560 nt
	global_load_dwordx2 a[92:93], v151, s[62:63] offset:3072 nt
	global_load_dwordx2 a[94:95], v151, s[62:63] offset:3584 nt
	s_add_u32 s7, s7, 1
	v_cvt_f32_f16_e32 v154, v70
	v_cvt_f32_f16_e32 v155, v78
	v_add_f32_e32 v154, v154, v155
	v_fmac_f32_e32 v54, v32, v154
	v_cvt_f32_f16_sdwa v156, v70 dst_sel:DWORD dst_unused:UNUSED_PAD src0_sel:WORD_1
	v_cvt_f32_f16_sdwa v157, v78 dst_sel:DWORD dst_unused:UNUSED_PAD src0_sel:WORD_1
	v_add_f32_e32 v156, v156, v157
	v_fmac_f32_e32 v55, v33, v156
	v_cvt_f32_f16_e32 v154, v71
	v_cvt_f32_f16_e32 v155, v79
	v_add_f32_e32 v154, v154, v155
	v_fmac_f32_e32 v56, v34, v154
	v_cvt_f32_f16_sdwa v156, v71 dst_sel:DWORD dst_unused:UNUSED_PAD src0_sel:WORD_1
	v_cvt_f32_f16_sdwa v157, v79 dst_sel:DWORD dst_unused:UNUSED_PAD src0_sel:WORD_1
	v_add_f32_e32 v156, v156, v157
	v_fmac_f32_e32 v57, v35, v156
	v_cvt_f32_f16_e32 v154, v72
	v_cvt_f32_f16_e32 v155, v80
	v_add_f32_e32 v154, v154, v155
	v_fmac_f32_e32 v58, v36, v154
	v_cvt_f32_f16_sdwa v156, v72 dst_sel:DWORD dst_unused:UNUSED_PAD src0_sel:WORD_1
	v_cvt_f32_f16_sdwa v157, v80 dst_sel:DWORD dst_unused:UNUSED_PAD src0_sel:WORD_1
	v_add_f32_e32 v156, v156, v157
	v_fmac_f32_e32 v59, v37, v156
	v_cvt_f32_f16_e32 v154, v73
	v_cvt_f32_f16_e32 v155, v81
	v_add_f32_e32 v154, v154, v155
	v_fmac_f32_e32 v60, v38, v154
	v_cvt_f32_f16_sdwa v156, v73 dst_sel:DWORD dst_unused:UNUSED_PAD src0_sel:WORD_1
	v_cvt_f32_f16_sdwa v157, v81 dst_sel:DWORD dst_unused:UNUSED_PAD src0_sel:WORD_1
	v_add_f32_e32 v156, v156, v157
	v_fmac_f32_e32 v61, v39, v156
	v_cvt_f32_f16_e32 v154, v74
	v_cvt_f32_f16_e32 v155, v82
	v_add_f32_e32 v154, v154, v155
	v_fmac_f32_e32 v62, v40, v154
	v_cvt_f32_f16_sdwa v156, v74 dst_sel:DWORD dst_unused:UNUSED_PAD src0_sel:WORD_1
	v_cvt_f32_f16_sdwa v157, v82 dst_sel:DWORD dst_unused:UNUSED_PAD src0_sel:WORD_1
	v_add_f32_e32 v156, v156, v157
	v_fmac_f32_e32 v63, v41, v156
	v_cvt_f32_f16_e32 v154, v75
	v_cvt_f32_f16_e32 v155, v83
	v_add_f32_e32 v154, v154, v155
	v_fmac_f32_e32 v64, v42, v154
	v_cvt_f32_f16_sdwa v156, v75 dst_sel:DWORD dst_unused:UNUSED_PAD src0_sel:WORD_1
	v_cvt_f32_f16_sdwa v157, v83 dst_sel:DWORD dst_unused:UNUSED_PAD src0_sel:WORD_1
	v_add_f32_e32 v156, v156, v157
	v_fmac_f32_e32 v65, v43, v156
	v_cvt_f32_f16_e32 v154, v76
	v_cvt_f32_f16_e32 v155, v84
	v_add_f32_e32 v154, v154, v155
	v_fmac_f32_e32 v66, v44, v154
	v_cvt_f32_f16_sdwa v156, v76 dst_sel:DWORD dst_unused:UNUSED_PAD src0_sel:WORD_1
	v_cvt_f32_f16_sdwa v157, v84 dst_sel:DWORD dst_unused:UNUSED_PAD src0_sel:WORD_1
	v_add_f32_e32 v156, v156, v157
	v_fmac_f32_e32 v67, v45, v156
	v_cvt_f32_f16_e32 v154, v77
	v_cvt_f32_f16_e32 v155, v85
	v_add_f32_e32 v154, v154, v155
	v_fmac_f32_e32 v68, v46, v154
	v_cvt_f32_f16_sdwa v156, v77 dst_sel:DWORD dst_unused:UNUSED_PAD src0_sel:WORD_1
	v_cvt_f32_f16_sdwa v157, v85 dst_sel:DWORD dst_unused:UNUSED_PAD src0_sel:WORD_1
	v_add_f32_e32 v156, v156, v157
	v_fmac_f32_e32 v69, v47, v156
	global_store_dwordx4 v150, v[54:57], s[34:35] offset:0
	global_store_dwordx4 v150, v[58:61], s[34:35] offset:1024
	global_store_dwordx4 v150, v[62:65], s[34:35] offset:2048
	global_store_dwordx4 v150, v[66:69], s[34:35] offset:3072
	v_mul_f32_e32 v152, v54, v54
	v_mul_f32_e32 v153, v55, v55
	v_fmac_f32_e32 v152, v56, v56
	v_fmac_f32_e32 v153, v57, v57
	v_fmac_f32_e32 v152, v58, v58
	v_fmac_f32_e32 v153, v59, v59
	v_fmac_f32_e32 v152, v60, v60
	v_fmac_f32_e32 v153, v61, v61
	v_fmac_f32_e32 v152, v62, v62
	v_fmac_f32_e32 v153, v63, v63
	v_fmac_f32_e32 v152, v64, v64
	v_fmac_f32_e32 v153, v65, v65
	v_fmac_f32_e32 v152, v66, v66
	v_fmac_f32_e32 v153, v67, v67
	v_fmac_f32_e32 v152, v68, v68
	v_fmac_f32_e32 v153, v69, v69
	v_add_f32_e32 v152, v152, v153
; DI float shx(float v, int o) { int ln = TIDX & 63; return __builtin_bit_cast(float, __builtin_amdgcn_ds_bpermute((ln ^ o) << 2, __builtin_bit_cast(int, v))); }
; DI float wave_sum(float v) {
; #pragma unroll
;   for (int o = 32; o; o >>= 1) v += shx(v, o);
;   return v;
; }
; DI void row1_phase(const Params& P, int combine_l, int norm_l, int r_begin) {
;     ...
;     if (norm_l >= 0) {
;       float ss = 0.f;
; #pragma unroll
;       for (int i = 0; i < 4; i++) ss += xv[i].x * xv[i].x + xv[i].y * xv[i].y + xv[i].z * xv[i].z + xv[i].w * xv[i].w;
;       ss = wave_sum(ss);
;       const float rstd = rsqrtf(ss * (1.f / 1024.f) + EPS);
;       const float* g = P.norm1_g + norm_l * 1024;
;       const float* sh = P.mod + (size_t)(norm_l * 9 + n) * 6144; const float* sc = sh + 1024;
; #pragma unroll
;       for (int i = 0; i < 4; i++) {
;         int c = i * 256 + lane * 4;
;         float4 gg = *(const float4*)(g + c), s1 = *(const float4*)(sc + c), s0 = *(const float4*)(sh + c);
;         h4 o;
;         o[0] = (half_t)(xv[i].x * rstd * gg.x * (1.f + s1.x) + s0.x); o[1] = (half_t)(xv[i].y * rstd * gg.y * (1.f + s1.y) + s0.y);
;         o[2] = (half_t)(xv[i].z * rstd * gg.z * (1.f + s1.z) + s0.z); o[3] = (half_t)(xv[i].w * rstd * gg.w * (1.f + s1.w) + s0.w);
;         *(h4*)(P.hx + (size_t)r * D + c) = o;
;       }
;     }
	s_nop 1
	v_add_f32_dpp v152, v152, v152 row_ror:8 row_mask:0xf bank_mask:0xf
	s_nop 1
	v_add_f32_dpp v152, v152, v152 row_ror:4 row_mask:0xf bank_mask:0xf
	s_nop 1
	v_add_f32_dpp v152, v152, v152 row_ror:2 row_mask:0xf bank_mask:0xf
	s_nop 1
	v_add_f32_dpp v152, v152, v152 row_ror:1 row_mask:0xf bank_mask:0xf
	s_nop 1
	v_readlane_b32 s22, v152, 0
	v_readlane_b32 s23, v152, 16
	v_readlane_b32 s32, v152, 32
	v_readlane_b32 s99, v152, 48
	v_mov_b32_e32 v152, s22
	v_add_f32_e32 v152, s23, v152
	v_add_f32_e32 v152, s32, v152
	v_add_f32_e32 v152, s99, v152
	v_mov_b32_e32 v153, 0x358637bd
	v_fmamk_f32 v152, v152, 0x3a800000, v153
	v_rsq_f32_e32 v152, v152
	s_nop 1
	v_mul_f32_e32 v54, v54, v152
	v_mul_f32_e32 v55, v55, v152
	v_mul_f32_e32 v56, v56, v152
	v_mul_f32_e32 v57, v57, v152
	v_mul_f32_e32 v58, v58, v152
	v_mul_f32_e32 v59, v59, v152
	v_mul_f32_e32 v60, v60, v152
	v_mul_f32_e32 v61, v61, v152
	v_mul_f32_e32 v62, v62, v152
	v_mul_f32_e32 v63, v63, v152
	v_mul_f32_e32 v64, v64, v152
	v_mul_f32_e32 v65, v65, v152
	v_mul_f32_e32 v66, v66, v152
	v_mul_f32_e32 v67, v67, v152
	v_mul_f32_e32 v68, v68, v152
	v_mul_f32_e32 v69, v69, v152
	v_fma_f32 v54, v54, v0, v16
	v_fma_f32 v55, v55, v1, v17
	v_fma_f32 v56, v56, v2, v18
	v_fma_f32 v57, v57, v3, v19
	v_fma_f32 v58, v58, v4, v20
	v_fma_f32 v59, v59, v5, v21
	v_fma_f32 v60, v60, v6, v22
	v_fma_f32 v61, v61, v7, v23
	v_fma_f32 v62, v62, v8, v24
	v_fma_f32 v63, v63, v9, v25
	v_fma_f32 v64, v64, v10, v26
	v_fma_f32 v65, v65, v11, v27
	v_fma_f32 v66, v66, v12, v28
	v_fma_f32 v67, v67, v13, v29
	v_fma_f32 v68, v68, v14, v30
	v_fma_f32 v69, v69, v15, v31
	v_cvt_pk_f16_f32 v70, v54, v55
	v_cvt_pk_f16_f32 v71, v56, v57
	v_cvt_pk_f16_f32 v72, v58, v59
	v_cvt_pk_f16_f32 v73, v60, v61
	v_cvt_pk_f16_f32 v74, v62, v63
	v_cvt_pk_f16_f32 v75, v64, v65
	v_cvt_pk_f16_f32 v76, v66, v67
	v_cvt_pk_f16_f32 v77, v68, v69
	global_store_dwordx2 v151, v[70:71], s[36:37] offset:0
	global_store_dwordx2 v151, v[72:73], s[36:37] offset:512
	global_store_dwordx2 v151, v[74:75], s[36:37] offset:1024
	global_store_dwordx2 v151, v[76:77], s[36:37] offset:1536
	s_add_u32 s5, s5, 1
	s_sub_u32 s9, s5, 0x800
	s_lshr_b32 s9, s9, 13
	s_cmp_lt_u32 s5, 0x800
	s_cselect_b32 s9, 8, s9
	s_cmp_eq_u32 s9, s8
	s_cbranch_scc1 .Lr1b_nr4
	s_mov_b32 s8, s9
	s_waitcnt vmcnt(0)
	s_add_u32 s10, s9, 9
	s_mul_i32 s10, s10, 0x6000
	s_add_u32 s38, s56, s10
	s_addc_u32 s39, s57, 0
	global_load_dwordx4 v[54:57], v150, s[58:59] offset:0
	global_load_dwordx4 v[58:61], v150, s[58:59] offset:1024
	global_load_dwordx4 v[62:65], v150, s[58:59] offset:2048
	global_load_dwordx4 v[66:69], v150, s[58:59] offset:3072
	s_add_u32 s44, s38, 0x1000
	s_addc_u32 s45, s39, 0
	global_load_dwordx4 v[70:73], v150, s[44:45] offset:0
	global_load_dwordx4 v[74:77], v150, s[44:45] offset:1024
	global_load_dwordx4 v[78:81], v150, s[44:45] offset:2048
	global_load_dwordx4 v[82:85], v150, s[44:45] offset:3072
	global_load_dwordx4 v[16:19], v150, s[38:39] offset:0
	global_load_dwordx4 v[20:23], v150, s[38:39] offset:1024
	global_load_dwordx4 v[24:27], v150, s[38:39] offset:2048
	global_load_dwordx4 v[28:31], v150, s[38:39] offset:3072
	s_add_u32 s10, s9, 0
	s_mul_i32 s10, s10, 0x6000
	s_add_u32 s10, s10, 0x5000
	s_add_u32 s38, s56, s10
	s_addc_u32 s39, s57, 0
	global_load_dwordx4 v[32:35], v150, s[38:39] offset:0
	global_load_dwordx4 v[36:39], v150, s[38:39] offset:1024
	global_load_dwordx4 v[40:43], v150, s[38:39] offset:2048
	global_load_dwordx4 v[44:47], v150, s[38:39] offset:3072
	s_waitcnt vmcnt(0)
	v_add_f32_e32 v70, 1.0, v70
	v_add_f32_e32 v71, 1.0, v71
	v_add_f32_e32 v72, 1.0, v72
	v_add_f32_e32 v73, 1.0, v73
	v_add_f32_e32 v74, 1.0, v74
	v_add_f32_e32 v75, 1.0, v75
	v_add_f32_e32 v76, 1.0, v76
	v_add_f32_e32 v77, 1.0, v77
	v_add_f32_e32 v78, 1.0, v78
	v_add_f32_e32 v79, 1.0, v79
	v_add_f32_e32 v80, 1.0, v80
	v_add_f32_e32 v81, 1.0, v81
	v_add_f32_e32 v82, 1.0, v82
	v_add_f32_e32 v83, 1.0, v83
	v_add_f32_e32 v84, 1.0, v84
	v_add_f32_e32 v85, 1.0, v85
	v_mul_f32_e32 v0, v54, v70
	v_mul_f32_e32 v1, v55, v71
	v_mul_f32_e32 v2, v56, v72
	v_mul_f32_e32 v3, v57, v73
	v_mul_f32_e32 v4, v58, v74
	v_mul_f32_e32 v5, v59, v75
	v_mul_f32_e32 v6, v60, v76
	v_mul_f32_e32 v7, v61, v77
	v_mul_f32_e32 v8, v62, v78
	v_mul_f32_e32 v9, v63, v79
	v_mul_f32_e32 v10, v64, v80
	v_mul_f32_e32 v11, v65, v81
	v_mul_f32_e32 v12, v66, v82
	v_mul_f32_e32 v13, v67, v83
	v_mul_f32_e32 v14, v68, v84
	v_mul_f32_e32 v15, v69, v85
; DI void row1_phase(const Params& P, int combine_l, int norm_l, int r_begin) {
;     ...
;   auto load_row = [&](int r, float4 (&xv)[4], h4 (&ya)[4], h4 (&yb)[4]) {
;     if (combine_l < 0) {
;       const float* src = r < TC ? P.ctx + (size_t)r * D : P.x + (size_t)(r - TC) * D;
; #pragma unroll
;       for (int i = 0; i < 4; i++) xv[i] = *(const float4*)(src + i * 256 + lane * 4);
;     } else {
;       const float* xm = r < TC ? P.xcbuf + (size_t)r * D : P.out + (size_t)(r - TC) * D;
;       const half_t* y0 = P.yA + (size_t)(2 * r) * D; const half_t* y1 = y0 + D;
; #pragma unroll
;       for (int i = 0; i < 4; i++) { int c = i * 256 + lane * 4; xv[i] = *(const float4*)(xm + c); ya[i] = *(const h4*)(y0 + c); yb[i] = *(const h4*)(y1 + c); }
;     }
;   };
;   auto process = [&](int r, float4 (&xv)[4], h4 (&ya)[4], h4 (&yb)[4]) {
;     const int n = row_mod(r);
;     if (combine_l >= 0) {
;       float* xm = r < TC ? P.xcbuf + (size_t)r * D : P.out + (size_t)(r - TC) * D;
;       const float* g2 = P.mod + (size_t)(combine_l * 9 + n) * 6144 + 5 * 1024;
; #pragma unroll
;       for (int i = 0; i < 4; i++) {
;         int c = i * 256 + lane * 4;
;         float4 g = *(const float4*)(g2 + c); float4 t = xv[i];
;         t.x += g.x * ((float)ya[i][0] + (float)yb[i][0]); t.y += g.y * ((float)ya[i][1] + (float)yb[i][1]);
;         t.z += g.z * ((float)ya[i][2] + (float)yb[i][2]); t.w += g.w * ((float)ya[i][3] + (float)yb[i][3]);
;         *(float4*)(xm + c) = t; xv[i] = t;
;       }
;     }
;     if (norm_l >= 0) {
;       float ss = 0.f;
; #pragma unroll
;       for (int i = 0; i < 4; i++) ss += xv[i].x * xv[i].x + xv[i].y * xv[i].y + xv[i].z * xv[i].z + xv[i].w * xv[i].w;
.Lr1b_nr4:
	s_waitcnt vmcnt(44)
	v_accvgpr_read_b32 v54, a96
	v_accvgpr_read_b32 v55, a97
	v_accvgpr_read_b32 v56, a98
	v_accvgpr_read_b32 v57, a99
	v_accvgpr_read_b32 v58, a100
	v_accvgpr_read_b32 v59, a101
	v_accvgpr_read_b32 v60, a102
	v_accvgpr_read_b32 v61, a103
	v_accvgpr_read_b32 v62, a104
	v_accvgpr_read_b32 v63, a105
	v_accvgpr_read_b32 v64, a106
	v_accvgpr_read_b32 v65, a107
	v_accvgpr_read_b32 v66, a108
	v_accvgpr_read_b32 v67, a109
	v_accvgpr_read_b32 v68, a110
	v_accvgpr_read_b32 v69, a111
	v_accvgpr_read_b32 v70, a112
	v_accvgpr_read_b32 v71, a113
	v_accvgpr_read_b32 v72, a114
	v_accvgpr_read_b32 v73, a115
	v_accvgpr_read_b32 v74, a116
	v_accvgpr_read_b32 v75, a117
	v_accvgpr_read_b32 v76, a118
	v_accvgpr_read_b32 v77, a119
	v_accvgpr_read_b32 v78, a120
	v_accvgpr_read_b32 v79, a121
	v_accvgpr_read_b32 v80, a122
	v_accvgpr_read_b32 v81, a123
	v_accvgpr_read_b32 v82, a124
	v_accvgpr_read_b32 v83, a125
	v_accvgpr_read_b32 v84, a126
	v_accvgpr_read_b32 v85, a127
	s_lshl_b32 s10, s5, 12
	s_cmp_lt_u32 s5, 0x800
	s_cselect_b64 s[34:35], s[48:49], s[50:51]
	s_add_u32 s34, s34, s10
	s_addc_u32 s35, s35, 0
	s_lshr_b32 s10, s10, 1
	s_add_u32 s36, s54, s10
	s_addc_u32 s37, s55, 0
	s_cmp_lt_u32 s7, 0x800
	s_cselect_b64 s[60:61], s[48:49], s[50:51]
	s_lshl_b32 s10, s7, 12
	s_add_u32 s60, s60, s10
	s_addc_u32 s61, s61, 0
	global_load_dwordx4 a[96:99], v150, s[60:61] offset:0 nt
	global_load_dwordx4 a[100:103], v150, s[60:61] offset:1024 nt
	global_load_dwordx4 a[104:107], v150, s[60:61] offset:2048 nt
	global_load_dwordx4 a[108:111], v150, s[60:61] offset:3072 nt
	s_add_u32 s62, s52, s10
	s_addc_u32 s63, s53, 0
	global_load_dwordx2 a[112:113], v151, s[62:63] offset:0 nt
	global_load_dwordx2 a[114:115], v151, s[62:63] offset:512 nt
	global_load_dwordx2 a[116:117], v151, s[62:63] offset:1024 nt
	global_load_dwordx2 a[118:119], v151, s[62:63] offset:1536 nt
	global_load_dwordx2 a[120:121], v151, s[62:63] offset:2048 nt
	global_load_dwordx2 a[122:123], v151, s[62:63] offset:2560 nt
	global_load_dwordx2 a[124:125], v151, s[62:63] offset:3072 nt
	global_load_dwordx2 a[126:127], v151, s[62:63] offset:3584 nt
	s_add_u32 s7, s7, 1
	v_cvt_f32_f16_e32 v154, v70
	v_cvt_f32_f16_e32 v155, v78
	v_add_f32_e32 v154, v154, v155
	v_fmac_f32_e32 v54, v32, v154
	v_cvt_f32_f16_sdwa v156, v70 dst_sel:DWORD dst_unused:UNUSED_PAD src0_sel:WORD_1
	v_cvt_f32_f16_sdwa v157, v78 dst_sel:DWORD dst_unused:UNUSED_PAD src0_sel:WORD_1
	v_add_f32_e32 v156, v156, v157
	v_fmac_f32_e32 v55, v33, v156
	v_cvt_f32_f16_e32 v154, v71
	v_cvt_f32_f16_e32 v155, v79
	v_add_f32_e32 v154, v154, v155
	v_fmac_f32_e32 v56, v34, v154
	v_cvt_f32_f16_sdwa v156, v71 dst_sel:DWORD dst_unused:UNUSED_PAD src0_sel:WORD_1
	v_cvt_f32_f16_sdwa v157, v79 dst_sel:DWORD dst_unused:UNUSED_PAD src0_sel:WORD_1
	v_add_f32_e32 v156, v156, v157
	v_fmac_f32_e32 v57, v35, v156
	v_cvt_f32_f16_e32 v154, v72
	v_cvt_f32_f16_e32 v155, v80
	v_add_f32_e32 v154, v154, v155
	v_fmac_f32_e32 v58, v36, v154
	v_cvt_f32_f16_sdwa v156, v72 dst_sel:DWORD dst_unused:UNUSED_PAD src0_sel:WORD_1
	v_cvt_f32_f16_sdwa v157, v80 dst_sel:DWORD dst_unused:UNUSED_PAD src0_sel:WORD_1
	v_add_f32_e32 v156, v156, v157
	v_fmac_f32_e32 v59, v37, v156
	v_cvt_f32_f16_e32 v154, v73
	v_cvt_f32_f16_e32 v155, v81
	v_add_f32_e32 v154, v154, v155
	v_fmac_f32_e32 v60, v38, v154
	v_cvt_f32_f16_sdwa v156, v73 dst_sel:DWORD dst_unused:UNUSED_PAD src0_sel:WORD_1
	v_cvt_f32_f16_sdwa v157, v81 dst_sel:DWORD dst_unused:UNUSED_PAD src0_sel:WORD_1
	v_add_f32_e32 v156, v156, v157
	v_fmac_f32_e32 v61, v39, v156
	v_cvt_f32_f16_e32 v154, v74
	v_cvt_f32_f16_e32 v155, v82
	v_add_f32_e32 v154, v154, v155
	v_fmac_f32_e32 v62, v40, v154
	v_cvt_f32_f16_sdwa v156, v74 dst_sel:DWORD dst_unused:UNUSED_PAD src0_sel:WORD_1
	v_cvt_f32_f16_sdwa v157, v82 dst_sel:DWORD dst_unused:UNUSED_PAD src0_sel:WORD_1
	v_add_f32_e32 v156, v156, v157
	v_fmac_f32_e32 v63, v41, v156
	v_cvt_f32_f16_e32 v154, v75
	v_cvt_f32_f16_e32 v155, v83
	v_add_f32_e32 v154, v154, v155
	v_fmac_f32_e32 v64, v42, v154
	v_cvt_f32_f16_sdwa v156, v75 dst_sel:DWORD dst_unused:UNUSED_PAD src0_sel:WORD_1
	v_cvt_f32_f16_sdwa v157, v83 dst_sel:DWORD dst_unused:UNUSED_PAD src0_sel:WORD_1
	v_add_f32_e32 v156, v156, v157
	v_fmac_f32_e32 v65, v43, v156
	v_cvt_f32_f16_e32 v154, v76
	v_cvt_f32_f16_e32 v155, v84
	v_add_f32_e32 v154, v154, v155
	v_fmac_f32_e32 v66, v44, v154
	v_cvt_f32_f16_sdwa v156, v76 dst_sel:DWORD dst_unused:UNUSED_PAD src0_sel:WORD_1
	v_cvt_f32_f16_sdwa v157, v84 dst_sel:DWORD dst_unused:UNUSED_PAD src0_sel:WORD_1
	v_add_f32_e32 v156, v156, v157
	v_fmac_f32_e32 v67, v45, v156
	v_cvt_f32_f16_e32 v154, v77
	v_cvt_f32_f16_e32 v155, v85
	v_add_f32_e32 v154, v154, v155
	v_fmac_f32_e32 v68, v46, v154
	v_cvt_f32_f16_sdwa v156, v77 dst_sel:DWORD dst_unused:UNUSED_PAD src0_sel:WORD_1
	v_cvt_f32_f16_sdwa v157, v85 dst_sel:DWORD dst_unused:UNUSED_PAD src0_sel:WORD_1
	v_add_f32_e32 v156, v156, v157
	v_fmac_f32_e32 v69, v47, v156
	global_store_dwordx4 v150, v[54:57], s[34:35] offset:0
	global_store_dwordx4 v150, v[58:61], s[34:35] offset:1024
	global_store_dwordx4 v150, v[62:65], s[34:35] offset:2048
; DI float shx(float v, int o) { int ln = TIDX & 63; return __builtin_bit_cast(float, __builtin_amdgcn_ds_bpermute((ln ^ o) << 2, __builtin_bit_cast(int, v))); }
; DI float wave_sum(float v) {
; #pragma unroll
;   for (int o = 32; o; o >>= 1) v += shx(v, o);
;   return v;
; }
; DI void row1_phase(const Params& P, int combine_l, int norm_l, int r_begin) {
;     ...
;       float ss = 0.f;
; #pragma unroll
;       for (int i = 0; i < 4; i++) ss += xv[i].x * xv[i].x + xv[i].y * xv[i].y + xv[i].z * xv[i].z + xv[i].w * xv[i].w;
;       ss = wave_sum(ss);
;       const float rstd = rsqrtf(ss * (1.f / 1024.f) + EPS);
;       const float* g = P.norm1_g + norm_l * 1024;
;       const float* sh = P.mod + (size_t)(norm_l * 9 + n) * 6144; const float* sc = sh + 1024;
; #pragma unroll
;       for (int i = 0; i < 4; i++) {
;         int c = i * 256 + lane * 4;
;         float4 gg = *(const float4*)(g + c), s1 = *(const float4*)(sc + c), s0 = *(const float4*)(sh + c);
;         h4 o;
;         o[0] = (half_t)(xv[i].x * rstd * gg.x * (1.f + s1.x) + s0.x); o[1] = (half_t)(xv[i].y * rstd * gg.y * (1.f + s1.y) + s0.y);
;         o[2] = (half_t)(xv[i].z * rstd * gg.z * (1.f + s1.z) + s0.z); o[3] = (half_t)(xv[i].w * rstd * gg.w * (1.f + s1.w) + s0.w);
;         *(h4*)(P.hx + (size_t)r * D + c) = o;
;       }
;     }
;   };
;   const int nrows = TA - r_begin;
;   const int r_lo = r_begin + (int)(((long long)gw * nrows) / nw), r_hi = r_begin + (int)(((long long)(gw + 1) * nrows) / nw);
; #pragma unroll 1
;   for (int r = r_lo; r < r_hi; r += 4) {
;     float4 x0[4], x1[4], x2[4], x3[4]; h4 a0[4], b0[4], a1[4], b1[4], a2[4], b2[4], a3[4], b3[4];
;     const int r1 = r + 1, r2 = r + 2, r3 = r + 3;
;     load_row(r, x0, a0, b0);
;     if (r1 < r_hi) load_row(r1, x1, a1, b1);
;     if (r2 < r_hi) load_row(r2, x2, a2, b2);
;     if (r3 < r_hi) load_row(r3, x3, a3, b3);
;     process(r, x0, a0, b0);
;     if (r1 < r_hi) process(r1, x1, a1, b1);
;     if (r2 < r_hi) process(r2, x2, a2, b2);
;     if (r3 < r_hi) process(r3, x3, a3, b3);
;   }
	global_store_dwordx4 v150, v[66:69], s[34:35] offset:3072
	v_mul_f32_e32 v152, v54, v54
	v_mul_f32_e32 v153, v55, v55
	v_fmac_f32_e32 v152, v56, v56
	v_fmac_f32_e32 v153, v57, v57
	v_fmac_f32_e32 v152, v58, v58
	v_fmac_f32_e32 v153, v59, v59
	v_fmac_f32_e32 v152, v60, v60
	v_fmac_f32_e32 v153, v61, v61
	v_fmac_f32_e32 v152, v62, v62
	v_fmac_f32_e32 v153, v63, v63
	v_fmac_f32_e32 v152, v64, v64
	v_fmac_f32_e32 v153, v65, v65
	v_fmac_f32_e32 v152, v66, v66
	v_fmac_f32_e32 v153, v67, v67
	v_fmac_f32_e32 v152, v68, v68
	v_fmac_f32_e32 v153, v69, v69
	v_add_f32_e32 v152, v152, v153
	s_nop 1
	v_add_f32_dpp v152, v152, v152 row_ror:8 row_mask:0xf bank_mask:0xf
	s_nop 1
	v_add_f32_dpp v152, v152, v152 row_ror:4 row_mask:0xf bank_mask:0xf
	s_nop 1
	v_add_f32_dpp v152, v152, v152 row_ror:2 row_mask:0xf bank_mask:0xf
	s_nop 1
	v_add_f32_dpp v152, v152, v152 row_ror:1 row_mask:0xf bank_mask:0xf
	s_nop 1
	v_readlane_b32 s22, v152, 0
	v_readlane_b32 s23, v152, 16
	v_readlane_b32 s32, v152, 32
	v_readlane_b32 s99, v152, 48
	v_mov_b32_e32 v152, s22
	v_add_f32_e32 v152, s23, v152
	v_add_f32_e32 v152, s32, v152
	v_add_f32_e32 v152, s99, v152
	v_mov_b32_e32 v153, 0x358637bd
	v_fmamk_f32 v152, v152, 0x3a800000, v153
	v_rsq_f32_e32 v152, v152
	s_nop 1
	v_mul_f32_e32 v54, v54, v152
	v_mul_f32_e32 v55, v55, v152
	v_mul_f32_e32 v56, v56, v152
	v_mul_f32_e32 v57, v57, v152
	v_mul_f32_e32 v58, v58, v152
	v_mul_f32_e32 v59, v59, v152
	v_mul_f32_e32 v60, v60, v152
	v_mul_f32_e32 v61, v61, v152
	v_mul_f32_e32 v62, v62, v152
	v_mul_f32_e32 v63, v63, v152
	v_mul_f32_e32 v64, v64, v152
	v_mul_f32_e32 v65, v65, v152
	v_mul_f32_e32 v66, v66, v152
	v_mul_f32_e32 v67, v67, v152
	v_mul_f32_e32 v68, v68, v152
	v_mul_f32_e32 v69, v69, v152
	v_fma_f32 v54, v54, v0, v16
	v_fma_f32 v55, v55, v1, v17
	v_fma_f32 v56, v56, v2, v18
	v_fma_f32 v57, v57, v3, v19
	v_fma_f32 v58, v58, v4, v20
	v_fma_f32 v59, v59, v5, v21
	v_fma_f32 v60, v60, v6, v22
	v_fma_f32 v61, v61, v7, v23
	v_fma_f32 v62, v62, v8, v24
	v_fma_f32 v63, v63, v9, v25
	v_fma_f32 v64, v64, v10, v26
	v_fma_f32 v65, v65, v11, v27
	v_fma_f32 v66, v66, v12, v28
	v_fma_f32 v67, v67, v13, v29
	v_fma_f32 v68, v68, v14, v30
	v_fma_f32 v69, v69, v15, v31
	v_cvt_pk_f16_f32 v70, v54, v55
	v_cvt_pk_f16_f32 v71, v56, v57
	v_cvt_pk_f16_f32 v72, v58, v59
	v_cvt_pk_f16_f32 v73, v60, v61
	v_cvt_pk_f16_f32 v74, v62, v63
	v_cvt_pk_f16_f32 v75, v64, v65
	v_cvt_pk_f16_f32 v76, v66, v67
	v_cvt_pk_f16_f32 v77, v68, v69
	global_store_dwordx2 v151, v[70:71], s[36:37] offset:0
	global_store_dwordx2 v151, v[72:73], s[36:37] offset:512
	global_store_dwordx2 v151, v[74:75], s[36:37] offset:1024
	global_store_dwordx2 v151, v[76:77], s[36:37] offset:1536
	s_add_u32 s5, s5, 1
	s_sub_u32 s98, s98, 1
	s_cmp_lg_u32 s98, 0
	s_cbranch_scc1 .Lr1b_loop
	s_sub_u32 s9, s5, 0x800
	s_lshr_b32 s9, s9, 13
	s_cmp_lt_u32 s5, 0x800
	s_cselect_b32 s9, 8, s9
	s_cmp_eq_u32 s9, s8
	s_cbranch_scc1 .Lr1b_nr5
	s_mov_b32 s8, s9
	s_waitcnt vmcnt(0)
	s_add_u32 s10, s9, 9
	s_mul_i32 s10, s10, 0x6000
	s_add_u32 s38, s56, s10
	s_addc_u32 s39, s57, 0
	global_load_dwordx4 v[54:57], v150, s[58:59] offset:0
	global_load_dwordx4 v[58:61], v150, s[58:59] offset:1024
	global_load_dwordx4 v[62:65], v150, s[58:59] offset:2048
	global_load_dwordx4 v[66:69], v150, s[58:59] offset:3072
	s_add_u32 s44, s38, 0x1000
	s_addc_u32 s45, s39, 0
	global_load_dwordx4 v[70:73], v150, s[44:45] offset:0
	global_load_dwordx4 v[74:77], v150, s[44:45] offset:1024
	global_load_dwordx4 v[78:81], v150, s[44:45] offset:2048
	global_load_dwordx4 v[82:85], v150, s[44:45] offset:3072
	global_load_dwordx4 v[16:19], v150, s[38:39] offset:0
	global_load_dwordx4 v[20:23], v150, s[38:39] offset:1024
	global_load_dwordx4 v[24:27], v150, s[38:39] offset:2048
	global_load_dwordx4 v[28:31], v150, s[38:39] offset:3072
	s_add_u32 s10, s9, 0
	s_mul_i32 s10, s10, 0x6000
	s_add_u32 s10, s10, 0x5000
	s_add_u32 s38, s56, s10
	s_addc_u32 s39, s57, 0
	global_load_dwordx4 v[32:35], v150, s[38:39] offset:0
	global_load_dwordx4 v[36:39], v150, s[38:39] offset:1024
	global_load_dwordx4 v[40:43], v150, s[38:39] offset:2048
	global_load_dwordx4 v[44:47], v150, s[38:39] offset:3072
	s_waitcnt vmcnt(0)
	v_add_f32_e32 v70, 1.0, v70
	v_add_f32_e32 v71, 1.0, v71
	v_add_f32_e32 v72, 1.0, v72
	v_add_f32_e32 v73, 1.0, v73
	v_add_f32_e32 v74, 1.0, v74
	v_add_f32_e32 v75, 1.0, v75
	v_add_f32_e32 v76, 1.0, v76
	v_add_f32_e32 v77, 1.0, v77
	v_add_f32_e32 v78, 1.0, v78
	v_add_f32_e32 v79, 1.0, v79
	v_add_f32_e32 v80, 1.0, v80
	v_add_f32_e32 v81, 1.0, v81
	v_add_f32_e32 v82, 1.0, v82
	v_add_f32_e32 v83, 1.0, v83
	v_add_f32_e32 v84, 1.0, v84
	v_add_f32_e32 v85, 1.0, v85
	v_mul_f32_e32 v0, v54, v70
	v_mul_f32_e32 v1, v55, v71
	v_mul_f32_e32 v2, v56, v72
	v_mul_f32_e32 v3, v57, v73
	v_mul_f32_e32 v4, v58, v74
	v_mul_f32_e32 v5, v59, v75
	v_mul_f32_e32 v6, v60, v76
	v_mul_f32_e32 v7, v61, v77
	v_mul_f32_e32 v8, v62, v78
	v_mul_f32_e32 v9, v63, v79
	v_mul_f32_e32 v10, v64, v80
	v_mul_f32_e32 v11, v65, v81
	v_mul_f32_e32 v12, v66, v82
	v_mul_f32_e32 v13, v67, v83
	v_mul_f32_e32 v14, v68, v84
	v_mul_f32_e32 v15, v69, v85

; DI void row1_phase(const Params& P, int combine_l, int norm_l, int r_begin) {
;     ...
;     if (combine_l >= 0) {
;       float* xm = r < TC ? P.xcbuf + (size_t)r * D : P.out + (size_t)(r - TC) * D;
;       const float* g2 = P.mod + (size_t)(combine_l * 9 + n) * 6144 + 5 * 1024;
; #pragma unroll
;       for (int i = 0; i < 4; i++) {
;         int c = i * 256 + lane * 4;
;         float4 g = *(const float4*)(g2 + c); float4 t = xv[i];
;         t.x += g.x * ((float)ya[i][0] + (float)yb[i][0]); t.y += g.y * ((float)ya[i][1] + (float)yb[i][1]);
;         t.z += g.z * ((float)ya[i][2] + (float)yb[i][2]); t.w += g.w * ((float)ya[i][3] + (float)yb[i][3]);
;         *(float4*)(xm + c) = t; xv[i] = t;
;       }
;     }
;     if (norm_l >= 0) {
;       float ss = 0.f;
; #pragma unroll
;       for (int i = 0; i < 4; i++) ss += xv[i].x * xv[i].x + xv[i].y * xv[i].y + xv[i].z * xv[i].z + xv[i].w * xv[i].w;
;       ss = wave_sum(ss);
;       const float rstd = rsqrtf(ss * (1.f / 1024.f) + EPS);
;       const float* g = P.norm1_g + norm_l * 1024;
;       const float* sh = P.mod + (size_t)(norm_l * 9 + n) * 6144; const float* sc = sh + 1024;
; #pragma unroll
;       for (int i = 0; i < 4; i++) {
;         int c = i * 256 + lane * 4;
;         float4 gg = *(const float4*)(g + c), s1 = *(const float4*)(sc + c), s0 = *(const float4*)(sh + c);
;         h4 o;
;         o[0] = (half_t)(xv[i].x * rstd * gg.x * (1.f + s1.x) + s0.x); o[1] = (half_t)(xv[i].y * rstd * gg.y * (1.f + s1.y) + s0.y);
;         o[2] = (half_t)(xv[i].z * rstd * gg.z * (1.f + s1.z) + s0.z); o[3] = (half_t)(xv[i].w * rstd * gg.w * (1.f + s1.w) + s0.w);
;         *(h4*)(P.hx + (size_t)r * D + c) = o;
;       }
.Lr1b_nr7:
	s_waitcnt vmcnt(44)
	v_accvgpr_read_b32 v54, a64
	v_accvgpr_read_b32 v55, a65
	v_accvgpr_read_b32 v56, a66
	v_accvgpr_read_b32 v57, a67
	v_accvgpr_read_b32 v58, a68
	v_accvgpr_read_b32 v59, a69
	v_accvgpr_read_b32 v60, a70
	v_accvgpr_read_b32 v61, a71
	v_accvgpr_read_b32 v62, a72
	v_accvgpr_read_b32 v63, a73
	v_accvgpr_read_b32 v64, a74
	v_accvgpr_read_b32 v65, a75
	v_accvgpr_read_b32 v66, a76
	v_accvgpr_read_b32 v67, a77
	v_accvgpr_read_b32 v68, a78
	v_accvgpr_read_b32 v69, a79
	v_accvgpr_read_b32 v70, a80
	v_accvgpr_read_b32 v71, a81
	v_accvgpr_read_b32 v72, a82
	v_accvgpr_read_b32 v73, a83
	v_accvgpr_read_b32 v74, a84
	v_accvgpr_read_b32 v75, a85
	v_accvgpr_read_b32 v76, a86
	v_accvgpr_read_b32 v77, a87
	v_accvgpr_read_b32 v78, a88
	v_accvgpr_read_b32 v79, a89
	v_accvgpr_read_b32 v80, a90
	v_accvgpr_read_b32 v81, a91
	v_accvgpr_read_b32 v82, a92
	v_accvgpr_read_b32 v83, a93
	v_accvgpr_read_b32 v84, a94
	v_accvgpr_read_b32 v85, a95
	s_lshl_b32 s10, s5, 12
	s_cmp_lt_u32 s5, 0x800
	s_cselect_b64 s[34:35], s[48:49], s[50:51]
	s_add_u32 s34, s34, s10
	s_addc_u32 s35, s35, 0
	s_lshr_b32 s10, s10, 1
	s_add_u32 s36, s54, s10
	s_addc_u32 s37, s55, 0
	v_cvt_f32_f16_e32 v154, v70
	v_cvt_f32_f16_e32 v155, v78
	v_add_f32_e32 v154, v154, v155
	v_fmac_f32_e32 v54, v32, v154
	v_cvt_f32_f16_sdwa v156, v70 dst_sel:DWORD dst_unused:UNUSED_PAD src0_sel:WORD_1
	v_cvt_f32_f16_sdwa v157, v78 dst_sel:DWORD dst_unused:UNUSED_PAD src0_sel:WORD_1
	v_add_f32_e32 v156, v156, v157
	v_fmac_f32_e32 v55, v33, v156
	v_cvt_f32_f16_e32 v154, v71
	v_cvt_f32_f16_e32 v155, v79
	v_add_f32_e32 v154, v154, v155
	v_fmac_f32_e32 v56, v34, v154
	v_cvt_f32_f16_sdwa v156, v71 dst_sel:DWORD dst_unused:UNUSED_PAD src0_sel:WORD_1
	v_cvt_f32_f16_sdwa v157, v79 dst_sel:DWORD dst_unused:UNUSED_PAD src0_sel:WORD_1
	v_add_f32_e32 v156, v156, v157
	v_fmac_f32_e32 v57, v35, v156
	v_cvt_f32_f16_e32 v154, v72
	v_cvt_f32_f16_e32 v155, v80
	v_add_f32_e32 v154, v154, v155
	v_fmac_f32_e32 v58, v36, v154
	v_cvt_f32_f16_sdwa v156, v72 dst_sel:DWORD dst_unused:UNUSED_PAD src0_sel:WORD_1
	v_cvt_f32_f16_sdwa v157, v80 dst_sel:DWORD dst_unused:UNUSED_PAD src0_sel:WORD_1
	v_add_f32_e32 v156, v156, v157
	v_fmac_f32_e32 v59, v37, v156
	v_cvt_f32_f16_e32 v154, v73
	v_cvt_f32_f16_e32 v155, v81
	v_add_f32_e32 v154, v154, v155
	v_fmac_f32_e32 v60, v38, v154
	v_cvt_f32_f16_sdwa v156, v73 dst_sel:DWORD dst_unused:UNUSED_PAD src0_sel:WORD_1
	v_cvt_f32_f16_sdwa v157, v81 dst_sel:DWORD dst_unused:UNUSED_PAD src0_sel:WORD_1
	v_add_f32_e32 v156, v156, v157
	v_fmac_f32_e32 v61, v39, v156
	v_cvt_f32_f16_e32 v154, v74
	v_cvt_f32_f16_e32 v155, v82
	v_add_f32_e32 v154, v154, v155
	v_fmac_f32_e32 v62, v40, v154
	v_cvt_f32_f16_sdwa v156, v74 dst_sel:DWORD dst_unused:UNUSED_PAD src0_sel:WORD_1
	v_cvt_f32_f16_sdwa v157, v82 dst_sel:DWORD dst_unused:UNUSED_PAD src0_sel:WORD_1
	v_add_f32_e32 v156, v156, v157
	v_fmac_f32_e32 v63, v41, v156
	v_cvt_f32_f16_e32 v154, v75
	v_cvt_f32_f16_e32 v155, v83
	v_add_f32_e32 v154, v154, v155
	v_fmac_f32_e32 v64, v42, v154
	v_cvt_f32_f16_sdwa v156, v75 dst_sel:DWORD dst_unused:UNUSED_PAD src0_sel:WORD_1
	v_cvt_f32_f16_sdwa v157, v83 dst_sel:DWORD dst_unused:UNUSED_PAD src0_sel:WORD_1
	v_add_f32_e32 v156, v156, v157
	v_fmac_f32_e32 v65, v43, v156
	v_cvt_f32_f16_e32 v154, v76
	v_cvt_f32_f16_e32 v155, v84
	v_add_f32_e32 v154, v154, v155
	v_fmac_f32_e32 v66, v44, v154
	v_cvt_f32_f16_sdwa v156, v76 dst_sel:DWORD dst_unused:UNUSED_PAD src0_sel:WORD_1
	v_cvt_f32_f16_sdwa v157, v84 dst_sel:DWORD dst_unused:UNUSED_PAD src0_sel:WORD_1
	v_add_f32_e32 v156, v156, v157
	v_fmac_f32_e32 v67, v45, v156
	v_cvt_f32_f16_e32 v154, v77
	v_cvt_f32_f16_e32 v155, v85
	v_add_f32_e32 v154, v154, v155
	v_fmac_f32_e32 v68, v46, v154
	v_cvt_f32_f16_sdwa v156, v77 dst_sel:DWORD dst_unused:UNUSED_PAD src0_sel:WORD_1
	v_cvt_f32_f16_sdwa v157, v85 dst_sel:DWORD dst_unused:UNUSED_PAD src0_sel:WORD_1
	v_add_f32_e32 v156, v156, v157
	v_fmac_f32_e32 v69, v47, v156
	global_store_dwordx4 v150, v[54:57], s[34:35] offset:0
	global_store_dwordx4 v150, v[58:61], s[34:35] offset:1024
	global_store_dwordx4 v150, v[62:65], s[34:35] offset:2048
	global_store_dwordx4 v150, v[66:69], s[34:35] offset:3072
	v_mul_f32_e32 v152, v54, v54
	v_mul_f32_e32 v153, v55, v55
	v_fmac_f32_e32 v152, v56, v56
	v_fmac_f32_e32 v153, v57, v57
	v_fmac_f32_e32 v152, v58, v58
	v_fmac_f32_e32 v153, v59, v59
	v_fmac_f32_e32 v152, v60, v60
	v_fmac_f32_e32 v153, v61, v61
	v_fmac_f32_e32 v152, v62, v62
	v_fmac_f32_e32 v153, v63, v63
	v_fmac_f32_e32 v152, v64, v64
	v_fmac_f32_e32 v153, v65, v65
	v_fmac_f32_e32 v152, v66, v66
	v_fmac_f32_e32 v153, v67, v67
	v_fmac_f32_e32 v152, v68, v68
	v_fmac_f32_e32 v153, v69, v69
	v_add_f32_e32 v152, v152, v153
	s_nop 1
	v_add_f32_dpp v152, v152, v152 row_ror:8 row_mask:0xf bank_mask:0xf
	s_nop 1
	v_add_f32_dpp v152, v152, v152 row_ror:4 row_mask:0xf bank_mask:0xf
	s_nop 1
	v_add_f32_dpp v152, v152, v152 row_ror:2 row_mask:0xf bank_mask:0xf
	s_nop 1
	v_add_f32_dpp v152, v152, v152 row_ror:1 row_mask:0xf bank_mask:0xf
	s_nop 1
	v_readlane_b32 s22, v152, 0
	v_readlane_b32 s23, v152, 16
	v_readlane_b32 s32, v152, 32
	v_readlane_b32 s99, v152, 48
	v_mov_b32_e32 v152, s22
	v_add_f32_e32 v152, s23, v152
	v_add_f32_e32 v152, s32, v152
	v_add_f32_e32 v152, s99, v152
	v_mov_b32_e32 v153, 0x358637bd
	v_fmamk_f32 v152, v152, 0x3a800000, v153
	v_rsq_f32_e32 v152, v152
	s_nop 1
	v_mul_f32_e32 v54, v54, v152
	v_mul_f32_e32 v55, v55, v152
	v_mul_f32_e32 v56, v56, v152
	v_mul_f32_e32 v57, v57, v152
	v_mul_f32_e32 v58, v58, v152
	v_mul_f32_e32 v59, v59, v152
	v_mul_f32_e32 v60, v60, v152
	v_mul_f32_e32 v61, v61, v152
	v_mul_f32_e32 v62, v62, v152
	v_mul_f32_e32 v63, v63, v152
	v_mul_f32_e32 v64, v64, v152
	v_mul_f32_e32 v65, v65, v152
	v_mul_f32_e32 v66, v66, v152
	v_mul_f32_e32 v67, v67, v152
	v_mul_f32_e32 v68, v68, v152
	v_mul_f32_e32 v69, v69, v152
	v_fma_f32 v54, v54, v0, v16
	v_fma_f32 v55, v55, v1, v17
	v_fma_f32 v56, v56, v2, v18
	v_fma_f32 v57, v57, v3, v19
	v_fma_f32 v58, v58, v4, v20
	v_fma_f32 v59, v59, v5, v21
	v_fma_f32 v60, v60, v6, v22
	v_fma_f32 v61, v61, v7, v23
	v_fma_f32 v62, v62, v8, v24
	v_fma_f32 v63, v63, v9, v25
	v_fma_f32 v64, v64, v10, v26
	v_fma_f32 v65, v65, v11, v27
	v_fma_f32 v66, v66, v12, v28
	v_fma_f32 v67, v67, v13, v29
	v_fma_f32 v68, v68, v14, v30
	v_fma_f32 v69, v69, v15, v31
	v_cvt_pk_f16_f32 v70, v54, v55
	v_cvt_pk_f16_f32 v71, v56, v57
	v_cvt_pk_f16_f32 v72, v58, v59
	v_cvt_pk_f16_f32 v73, v60, v61
	v_cvt_pk_f16_f32 v74, v62, v63
	v_cvt_pk_f16_f32 v75, v64, v65
	v_cvt_pk_f16_f32 v76, v66, v67
	v_cvt_pk_f16_f32 v77, v68, v69
	global_store_dwordx2 v151, v[70:71], s[36:37] offset:0
	global_store_dwordx2 v151, v[72:73], s[36:37] offset:512
	global_store_dwordx2 v151, v[74:75], s[36:37] offset:1024
	global_store_dwordx2 v151, v[76:77], s[36:37] offset:1536
	s_add_u32 s5, s5, 1
	s_sub_u32 s9, s5, 0x800
	s_lshr_b32 s9, s9, 13
	s_cmp_lt_u32 s5, 0x800
	s_cselect_b32 s9, 8, s9
	s_cmp_eq_u32 s9, s8
	s_cbranch_scc1 .Lr1b_nr8
; DI void row1_phase(const Params& P, int combine_l, int norm_l, int r_begin) {
;     ...
;       const float* g2 = P.mod + (size_t)(combine_l * 9 + n) * 6144 + 5 * 1024;
; #pragma unroll
;       for (int i = 0; i < 4; i++) {
;         int c = i * 256 + lane * 4;
;         float4 g = *(const float4*)(g2 + c); float4 t = xv[i];
;         t.x += g.x * ((float)ya[i][0] + (float)yb[i][0]); t.y += g.y * ((float)ya[i][1] + (float)yb[i][1]);
;         t.z += g.z * ((float)ya[i][2] + (float)yb[i][2]); t.w += g.w * ((float)ya[i][3] + (float)yb[i][3]);
;         *(float4*)(xm + c) = t; xv[i] = t;
;       }
;     }
;     if (norm_l >= 0) {
;       float ss = 0.f;
; #pragma unroll
;       for (int i = 0; i < 4; i++) ss += xv[i].x * xv[i].x + xv[i].y * xv[i].y + xv[i].z * xv[i].z + xv[i].w * xv[i].w;
;       ss = wave_sum(ss);
;       const float rstd = rsqrtf(ss * (1.f / 1024.f) + EPS);
;       const float* g = P.norm1_g + norm_l * 1024;
;       const float* sh = P.mod + (size_t)(norm_l * 9 + n) * 6144; const float* sc = sh + 1024;
; #pragma unroll
;       for (int i = 0; i < 4; i++) {
;         int c = i * 256 + lane * 4;
;         float4 gg = *(const float4*)(g + c), s1 = *(const float4*)(sc + c), s0 = *(const float4*)(sh + c);
	s_mov_b32 s8, s9
	s_waitcnt vmcnt(0)
	s_add_u32 s10, s9, 9
	s_mul_i32 s10, s10, 0x6000
	s_add_u32 s38, s56, s10
	s_addc_u32 s39, s57, 0
	global_load_dwordx4 v[54:57], v150, s[58:59] offset:0
	global_load_dwordx4 v[58:61], v150, s[58:59] offset:1024
	global_load_dwordx4 v[62:65], v150, s[58:59] offset:2048
	global_load_dwordx4 v[66:69], v150, s[58:59] offset:3072
	s_add_u32 s44, s38, 0x1000
	s_addc_u32 s45, s39, 0
	global_load_dwordx4 v[70:73], v150, s[44:45] offset:0
	global_load_dwordx4 v[74:77], v150, s[44:45] offset:1024
	global_load_dwordx4 v[78:81], v150, s[44:45] offset:2048
	global_load_dwordx4 v[82:85], v150, s[44:45] offset:3072
	global_load_dwordx4 v[16:19], v150, s[38:39] offset:0
	global_load_dwordx4 v[20:23], v150, s[38:39] offset:1024
	global_load_dwordx4 v[24:27], v150, s[38:39] offset:2048
	global_load_dwordx4 v[28:31], v150, s[38:39] offset:3072
	s_add_u32 s10, s9, 0
	s_mul_i32 s10, s10, 0x6000
	s_add_u32 s10, s10, 0x5000
	s_add_u32 s38, s56, s10
	s_addc_u32 s39, s57, 0
	global_load_dwordx4 v[32:35], v150, s[38:39] offset:0
	global_load_dwordx4 v[36:39], v150, s[38:39] offset:1024
	global_load_dwordx4 v[40:43], v150, s[38:39] offset:2048
	global_load_dwordx4 v[44:47], v150, s[38:39] offset:3072
	s_waitcnt vmcnt(0)
	v_add_f32_e32 v70, 1.0, v70
	v_add_f32_e32 v71, 1.0, v71
	v_add_f32_e32 v72, 1.0, v72
	v_add_f32_e32 v73, 1.0, v73
	v_add_f32_e32 v74, 1.0, v74
	v_add_f32_e32 v75, 1.0, v75
	v_add_f32_e32 v76, 1.0, v76
	v_add_f32_e32 v77, 1.0, v77
	v_add_f32_e32 v78, 1.0, v78
	v_add_f32_e32 v79, 1.0, v79
	v_add_f32_e32 v80, 1.0, v80
	v_add_f32_e32 v81, 1.0, v81
	v_add_f32_e32 v82, 1.0, v82
	v_add_f32_e32 v83, 1.0, v83
	v_add_f32_e32 v84, 1.0, v84
	v_add_f32_e32 v85, 1.0, v85
	v_mul_f32_e32 v0, v54, v70
	v_mul_f32_e32 v1, v55, v71
	v_mul_f32_e32 v2, v56, v72
	v_mul_f32_e32 v3, v57, v73
	v_mul_f32_e32 v4, v58, v74
	v_mul_f32_e32 v5, v59, v75
	v_mul_f32_e32 v6, v60, v76
	v_mul_f32_e32 v7, v61, v77
	v_mul_f32_e32 v8, v62, v78
	v_mul_f32_e32 v9, v63, v79
	v_mul_f32_e32 v10, v64, v80
	v_mul_f32_e32 v11, v65, v81
	v_mul_f32_e32 v12, v66, v82
	v_mul_f32_e32 v13, v67, v83
	v_mul_f32_e32 v14, v68, v84
	v_mul_f32_e32 v15, v69, v85
.Lr1b_nr8:
	s_waitcnt vmcnt(32)
	v_accvgpr_read_b32 v54, a96
	v_accvgpr_read_b32 v55, a97
	v_accvgpr_read_b32 v56, a98
	v_accvgpr_read_b32 v57, a99
	v_accvgpr_read_b32 v58, a100
	v_accvgpr_read_b32 v59, a101
	v_accvgpr_read_b32 v60, a102
	v_accvgpr_read_b32 v61, a103
	v_accvgpr_read_b32 v62, a104
	v_accvgpr_read_b32 v63, a105
	v_accvgpr_read_b32 v64, a106
	v_accvgpr_read_b32 v65, a107
	v_accvgpr_read_b32 v66, a108
	v_accvgpr_read_b32 v67, a109
	v_accvgpr_read_b32 v68, a110
	v_accvgpr_read_b32 v69, a111
	v_accvgpr_read_b32 v70, a112
	v_accvgpr_read_b32 v71, a113
	v_accvgpr_read_b32 v72, a114
	v_accvgpr_read_b32 v73, a115
	v_accvgpr_read_b32 v74, a116
	v_accvgpr_read_b32 v75, a117
	v_accvgpr_read_b32 v76, a118
	v_accvgpr_read_b32 v77, a119
	v_accvgpr_read_b32 v78, a120
	v_accvgpr_read_b32 v79, a121
	v_accvgpr_read_b32 v80, a122
	v_accvgpr_read_b32 v81, a123
	v_accvgpr_read_b32 v82, a124
	v_accvgpr_read_b32 v83, a125
	v_accvgpr_read_b32 v84, a126
	v_accvgpr_read_b32 v85, a127
	s_lshl_b32 s10, s5, 12
	s_cmp_lt_u32 s5, 0x800
	s_cselect_b64 s[34:35], s[48:49], s[50:51]
	s_add_u32 s34, s34, s10
	s_addc_u32 s35, s35, 0
	s_lshr_b32 s10, s10, 1
	s_add_u32 s36, s54, s10
	s_addc_u32 s37, s55, 0
	v_cvt_f32_f16_e32 v154, v70
	v_cvt_f32_f16_e32 v155, v78
	v_add_f32_e32 v154, v154, v155
	v_fmac_f32_e32 v54, v32, v154
	v_cvt_f32_f16_sdwa v156, v70 dst_sel:DWORD dst_unused:UNUSED_PAD src0_sel:WORD_1
	v_cvt_f32_f16_sdwa v157, v78 dst_sel:DWORD dst_unused:UNUSED_PAD src0_sel:WORD_1
	v_add_f32_e32 v156, v156, v157
	v_fmac_f32_e32 v55, v33, v156
	v_cvt_f32_f16_e32 v154, v71
	v_cvt_f32_f16_e32 v155, v79
	v_add_f32_e32 v154, v154, v155
	v_fmac_f32_e32 v56, v34, v154
	v_cvt_f32_f16_sdwa v156, v71 dst_sel:DWORD dst_unused:UNUSED_PAD src0_sel:WORD_1
	v_cvt_f32_f16_sdwa v157, v79 dst_sel:DWORD dst_unused:UNUSED_PAD src0_sel:WORD_1
	v_add_f32_e32 v156, v156, v157
	v_fmac_f32_e32 v57, v35, v156
	v_cvt_f32_f16_e32 v154, v72
	v_cvt_f32_f16_e32 v155, v80
	v_add_f32_e32 v154, v154, v155
	v_fmac_f32_e32 v58, v36, v154
	v_cvt_f32_f16_sdwa v156, v72 dst_sel:DWORD dst_unused:UNUSED_PAD src0_sel:WORD_1
	v_cvt_f32_f16_sdwa v157, v80 dst_sel:DWORD dst_unused:UNUSED_PAD src0_sel:WORD_1
	v_add_f32_e32 v156, v156, v157
	v_fmac_f32_e32 v59, v37, v156
	v_cvt_f32_f16_e32 v154, v73
	v_cvt_f32_f16_e32 v155, v81
	v_add_f32_e32 v154, v154, v155
	v_fmac_f32_e32 v60, v38, v154
	v_cvt_f32_f16_sdwa v156, v73 dst_sel:DWORD dst_unused:UNUSED_PAD src0_sel:WORD_1
	v_cvt_f32_f16_sdwa v157, v81 dst_sel:DWORD dst_unused:UNUSED_PAD src0_sel:WORD_1
	v_add_f32_e32 v156, v156, v157
	v_fmac_f32_e32 v61, v39, v156
	v_cvt_f32_f16_e32 v154, v74
	v_cvt_f32_f16_e32 v155, v82
	v_add_f32_e32 v154, v154, v155
	v_fmac_f32_e32 v62, v40, v154
	v_cvt_f32_f16_sdwa v156, v74 dst_sel:DWORD dst_unused:UNUSED_PAD src0_sel:WORD_1
	v_cvt_f32_f16_sdwa v157, v82 dst_sel:DWORD dst_unused:UNUSED_PAD src0_sel:WORD_1
	v_add_f32_e32 v156, v156, v157
	v_fmac_f32_e32 v63, v41, v156
	v_cvt_f32_f16_e32 v154, v75
	v_cvt_f32_f16_e32 v155, v83
	v_add_f32_e32 v154, v154, v155
	v_fmac_f32_e32 v64, v42, v154
	v_cvt_f32_f16_sdwa v156, v75 dst_sel:DWORD dst_unused:UNUSED_PAD src0_sel:WORD_1
	v_cvt_f32_f16_sdwa v157, v83 dst_sel:DWORD dst_unused:UNUSED_PAD src0_sel:WORD_1
	v_add_f32_e32 v156, v156, v157
	v_fmac_f32_e32 v65, v43, v156
	v_cvt_f32_f16_e32 v154, v76
	v_cvt_f32_f16_e32 v155, v84
	v_add_f32_e32 v154, v154, v155
	v_fmac_f32_e32 v66, v44, v154
	v_cvt_f32_f16_sdwa v156, v76 dst_sel:DWORD dst_unused:UNUSED_PAD src0_sel:WORD_1
; DI void row1_phase(const Params& P, int combine_l, int norm_l, int r_begin) {
;     ...
;     if (combine_l >= 0) {
;       float* xm = r < TC ? P.xcbuf + (size_t)r * D : P.out + (size_t)(r - TC) * D;
;       const float* g2 = P.mod + (size_t)(combine_l * 9 + n) * 6144 + 5 * 1024;
; #pragma unroll
;       for (int i = 0; i < 4; i++) {
;         int c = i * 256 + lane * 4;
;         float4 g = *(const float4*)(g2 + c); float4 t = xv[i];
;         t.x += g.x * ((float)ya[i][0] + (float)yb[i][0]); t.y += g.y * ((float)ya[i][1] + (float)yb[i][1]);
;         t.z += g.z * ((float)ya[i][2] + (float)yb[i][2]); t.w += g.w * ((float)ya[i][3] + (float)yb[i][3]);
;         *(float4*)(xm + c) = t; xv[i] = t;
;       }
;     }
;     if (norm_l >= 0) {
;       float ss = 0.f;
; #pragma unroll
;       for (int i = 0; i < 4; i++) ss += xv[i].x * xv[i].x + xv[i].y * xv[i].y + xv[i].z * xv[i].z + xv[i].w * xv[i].w;
;       ss = wave_sum(ss);
;       const float rstd = rsqrtf(ss * (1.f / 1024.f) + EPS);
;       const float* g = P.norm1_g + norm_l * 1024;
;       const float* sh = P.mod + (size_t)(norm_l * 9 + n) * 6144; const float* sc = sh + 1024;
; #pragma unroll
;       for (int i = 0; i < 4; i++) {
;         int c = i * 256 + lane * 4;
;         float4 gg = *(const float4*)(g + c), s1 = *(const float4*)(sc + c), s0 = *(const float4*)(sh + c);
;         h4 o;
;         o[0] = (half_t)(xv[i].x * rstd * gg.x * (1.f + s1.x) + s0.x); o[1] = (half_t)(xv[i].y * rstd * gg.y * (1.f + s1.y) + s0.y);
;         o[2] = (half_t)(xv[i].z * rstd * gg.z * (1.f + s1.z) + s0.z); o[3] = (half_t)(xv[i].w * rstd * gg.w * (1.f + s1.w) + s0.w);
;         *(h4*)(P.hx + (size_t)r * D + c) = o;
;       }
	v_cvt_f32_f16_sdwa v157, v84 dst_sel:DWORD dst_unused:UNUSED_PAD src0_sel:WORD_1
	v_add_f32_e32 v156, v156, v157
	v_fmac_f32_e32 v67, v45, v156
	v_cvt_f32_f16_e32 v154, v77
	v_cvt_f32_f16_e32 v155, v85
	v_add_f32_e32 v154, v154, v155
	v_fmac_f32_e32 v68, v46, v154
	v_cvt_f32_f16_sdwa v156, v77 dst_sel:DWORD dst_unused:UNUSED_PAD src0_sel:WORD_1
	v_cvt_f32_f16_sdwa v157, v85 dst_sel:DWORD dst_unused:UNUSED_PAD src0_sel:WORD_1
	v_add_f32_e32 v156, v156, v157
	v_fmac_f32_e32 v69, v47, v156
	global_store_dwordx4 v150, v[54:57], s[34:35] offset:0
	global_store_dwordx4 v150, v[58:61], s[34:35] offset:1024
	global_store_dwordx4 v150, v[62:65], s[34:35] offset:2048
	global_store_dwordx4 v150, v[66:69], s[34:35] offset:3072
	v_mul_f32_e32 v152, v54, v54
	v_mul_f32_e32 v153, v55, v55
	v_fmac_f32_e32 v152, v56, v56
	v_fmac_f32_e32 v153, v57, v57
	v_fmac_f32_e32 v152, v58, v58
	v_fmac_f32_e32 v153, v59, v59
	v_fmac_f32_e32 v152, v60, v60
	v_fmac_f32_e32 v153, v61, v61
	v_fmac_f32_e32 v152, v62, v62
	v_fmac_f32_e32 v153, v63, v63
	v_fmac_f32_e32 v152, v64, v64
	v_fmac_f32_e32 v153, v65, v65
	v_fmac_f32_e32 v152, v66, v66
	v_fmac_f32_e32 v153, v67, v67
	v_fmac_f32_e32 v152, v68, v68
	v_fmac_f32_e32 v153, v69, v69
	v_add_f32_e32 v152, v152, v153
	s_nop 1
	v_add_f32_dpp v152, v152, v152 row_ror:8 row_mask:0xf bank_mask:0xf
	s_nop 1
	v_add_f32_dpp v152, v152, v152 row_ror:4 row_mask:0xf bank_mask:0xf
	s_nop 1
	v_add_f32_dpp v152, v152, v152 row_ror:2 row_mask:0xf bank_mask:0xf
	s_nop 1
	v_add_f32_dpp v152, v152, v152 row_ror:1 row_mask:0xf bank_mask:0xf
	s_nop 1
	v_readlane_b32 s22, v152, 0
	v_readlane_b32 s23, v152, 16
	v_readlane_b32 s32, v152, 32
	v_readlane_b32 s99, v152, 48
	v_mov_b32_e32 v152, s22
	v_add_f32_e32 v152, s23, v152
	v_add_f32_e32 v152, s32, v152
	v_add_f32_e32 v152, s99, v152
	v_mov_b32_e32 v153, 0x358637bd
	v_fmamk_f32 v152, v152, 0x3a800000, v153
	v_rsq_f32_e32 v152, v152
	s_nop 1
	v_mul_f32_e32 v54, v54, v152
	v_mul_f32_e32 v55, v55, v152
	v_mul_f32_e32 v56, v56, v152
	v_mul_f32_e32 v57, v57, v152
	v_mul_f32_e32 v58, v58, v152
	v_mul_f32_e32 v59, v59, v152
	v_mul_f32_e32 v60, v60, v152
	v_mul_f32_e32 v61, v61, v152
	v_mul_f32_e32 v62, v62, v152
	v_mul_f32_e32 v63, v63, v152
	v_mul_f32_e32 v64, v64, v152
	v_mul_f32_e32 v65, v65, v152
	v_mul_f32_e32 v66, v66, v152
	v_mul_f32_e32 v67, v67, v152
	v_mul_f32_e32 v68, v68, v152
	v_mul_f32_e32 v69, v69, v152
	v_fma_f32 v54, v54, v0, v16
	v_fma_f32 v55, v55, v1, v17
	v_fma_f32 v56, v56, v2, v18
	v_fma_f32 v57, v57, v3, v19
	v_fma_f32 v58, v58, v4, v20
	v_fma_f32 v59, v59, v5, v21
	v_fma_f32 v60, v60, v6, v22
	v_fma_f32 v61, v61, v7, v23
	v_fma_f32 v62, v62, v8, v24
	v_fma_f32 v63, v63, v9, v25
	v_fma_f32 v64, v64, v10, v26
	v_fma_f32 v65, v65, v11, v27
	v_fma_f32 v66, v66, v12, v28
	v_fma_f32 v67, v67, v13, v29
	v_fma_f32 v68, v68, v14, v30
	v_fma_f32 v69, v69, v15, v31
	v_cvt_pk_f16_f32 v70, v54, v55
	v_cvt_pk_f16_f32 v71, v56, v57
	v_cvt_pk_f16_f32 v72, v58, v59
	v_cvt_pk_f16_f32 v73, v60, v61
	v_cvt_pk_f16_f32 v74, v62, v63
	v_cvt_pk_f16_f32 v75, v64, v65
	v_cvt_pk_f16_f32 v76, v66, v67
	v_cvt_pk_f16_f32 v77, v68, v69
	global_store_dwordx2 v151, v[70:71], s[36:37] offset:0
	global_store_dwordx2 v151, v[72:73], s[36:37] offset:512
	global_store_dwordx2 v151, v[74:75], s[36:37] offset:1024
	global_store_dwordx2 v151, v[76:77], s[36:37] offset:1536
	s_add_u32 s5, s5, 1
	s_sub_u32 s9, s5, 0x800
	s_lshr_b32 s9, s9, 13
	s_cmp_lt_u32 s5, 0x800
	s_cselect_b32 s9, 8, s9
	s_cmp_eq_u32 s9, s8
	s_cbranch_scc1 .Lr1b_nr9
	s_mov_b32 s8, s9
	s_waitcnt vmcnt(0)
	s_add_u32 s10, s9, 9
	s_mul_i32 s10, s10, 0x6000
	s_add_u32 s38, s56, s10
	s_addc_u32 s39, s57, 0
	global_load_dwordx4 v[54:57], v150, s[58:59] offset:0
	global_load_dwordx4 v[58:61], v150, s[58:59] offset:1024
	global_load_dwordx4 v[62:65], v150, s[58:59] offset:2048
	global_load_dwordx4 v[66:69], v150, s[58:59] offset:3072
	s_add_u32 s44, s38, 0x1000
	s_addc_u32 s45, s39, 0
	global_load_dwordx4 v[70:73], v150, s[44:45] offset:0
	global_load_dwordx4 v[74:77], v150, s[44:45] offset:1024
	global_load_dwordx4 v[78:81], v150, s[44:45] offset:2048
	global_load_dwordx4 v[82:85], v150, s[44:45] offset:3072
	global_load_dwordx4 v[16:19], v150, s[38:39] offset:0
	global_load_dwordx4 v[20:23], v150, s[38:39] offset:1024
	global_load_dwordx4 v[24:27], v150, s[38:39] offset:2048
	global_load_dwordx4 v[28:31], v150, s[38:39] offset:3072
	s_add_u32 s10, s9, 0
	s_mul_i32 s10, s10, 0x6000
	s_add_u32 s10, s10, 0x5000
	s_add_u32 s38, s56, s10
	s_addc_u32 s39, s57, 0
	global_load_dwordx4 v[32:35], v150, s[38:39] offset:0
	global_load_dwordx4 v[36:39], v150, s[38:39] offset:1024
	global_load_dwordx4 v[40:43], v150, s[38:39] offset:2048
	global_load_dwordx4 v[44:47], v150, s[38:39] offset:3072
	s_waitcnt vmcnt(0)
	v_add_f32_e32 v70, 1.0, v70
	v_add_f32_e32 v71, 1.0, v71
	v_add_f32_e32 v72, 1.0, v72
	v_add_f32_e32 v73, 1.0, v73
	v_add_f32_e32 v74, 1.0, v74
	v_add_f32_e32 v75, 1.0, v75
	v_add_f32_e32 v76, 1.0, v76
	v_add_f32_e32 v77, 1.0, v77
	v_add_f32_e32 v78, 1.0, v78
	v_add_f32_e32 v79, 1.0, v79
	v_add_f32_e32 v80, 1.0, v80
	v_add_f32_e32 v81, 1.0, v81
	v_add_f32_e32 v82, 1.0, v82
	v_add_f32_e32 v83, 1.0, v83
	v_add_f32_e32 v84, 1.0, v84
	v_add_f32_e32 v85, 1.0, v85
	v_mul_f32_e32 v0, v54, v70
	v_mul_f32_e32 v1, v55, v71
	v_mul_f32_e32 v2, v56, v72
	v_mul_f32_e32 v3, v57, v73
	v_mul_f32_e32 v4, v58, v74
	v_mul_f32_e32 v5, v59, v75
	v_mul_f32_e32 v6, v60, v76
	v_mul_f32_e32 v7, v61, v77
	v_mul_f32_e32 v8, v62, v78
	v_mul_f32_e32 v9, v63, v79
	v_mul_f32_e32 v10, v64, v80
	v_mul_f32_e32 v11, v65, v81
	v_mul_f32_e32 v12, v66, v82
	v_mul_f32_e32 v13, v67, v83
	v_mul_f32_e32 v14, v68, v84
	v_mul_f32_e32 v15, v69, v85
; DI void row1_phase(const Params& P, int combine_l, int norm_l, int r_begin) {
;     ...
;     if (combine_l >= 0) {
;       float* xm = r < TC ? P.xcbuf + (size_t)r * D : P.out + (size_t)(r - TC) * D;
;       const float* g2 = P.mod + (size_t)(combine_l * 9 + n) * 6144 + 5 * 1024;
; #pragma unroll
;       for (int i = 0; i < 4; i++) {
;         int c = i * 256 + lane * 4;
;         float4 g = *(const float4*)(g2 + c); float4 t = xv[i];
;         t.x += g.x * ((float)ya[i][0] + (float)yb[i][0]); t.y += g.y * ((float)ya[i][1] + (float)yb[i][1]);
;         t.z += g.z * ((float)ya[i][2] + (float)yb[i][2]); t.w += g.w * ((float)ya[i][3] + (float)yb[i][3]);
;         *(float4*)(xm + c) = t; xv[i] = t;
;       }
;     }
;     if (norm_l >= 0) {
;       float ss = 0.f;
; #pragma unroll
;       for (int i = 0; i < 4; i++) ss += xv[i].x * xv[i].x + xv[i].y * xv[i].y + xv[i].z * xv[i].z + xv[i].w * xv[i].w;
;       ss = wave_sum(ss);
;       const float rstd = rsqrtf(ss * (1.f / 1024.f) + EPS);
;       const float* g = P.norm1_g + norm_l * 1024;
;       const float* sh = P.mod + (size_t)(norm_l * 9 + n) * 6144; const float* sc = sh + 1024;
; #pragma unroll
;       for (int i = 0; i < 4; i++) {
;         int c = i * 256 + lane * 4;
;         float4 gg = *(const float4*)(g + c), s1 = *(const float4*)(sc + c), s0 = *(const float4*)(sh + c);
;         h4 o;
;         o[0] = (half_t)(xv[i].x * rstd * gg.x * (1.f + s1.x) + s0.x); o[1] = (half_t)(xv[i].y * rstd * gg.y * (1.f + s1.y) + s0.y);
;         o[2] = (half_t)(xv[i].z * rstd * gg.z * (1.f + s1.z) + s0.z); o[3] = (half_t)(xv[i].w * rstd * gg.w * (1.f + s1.w) + s0.w);
;         *(h4*)(P.hx + (size_t)r * D + c) = o;
;       }
.Lr1b_nr9:
	s_waitcnt vmcnt(20)
	v_accvgpr_read_b32 v54, a0
	v_accvgpr_read_b32 v55, a1
	v_accvgpr_read_b32 v56, a2
	v_accvgpr_read_b32 v57, a3
	v_accvgpr_read_b32 v58, a4
	v_accvgpr_read_b32 v59, a5
	v_accvgpr_read_b32 v60, a6
	v_accvgpr_read_b32 v61, a7
	v_accvgpr_read_b32 v62, a8
	v_accvgpr_read_b32 v63, a9
	v_accvgpr_read_b32 v64, a10
	v_accvgpr_read_b32 v65, a11
	v_accvgpr_read_b32 v66, a12
	v_accvgpr_read_b32 v67, a13
	v_accvgpr_read_b32 v68, a14
	v_accvgpr_read_b32 v69, a15
	v_accvgpr_read_b32 v70, a16
	v_accvgpr_read_b32 v71, a17
	v_accvgpr_read_b32 v72, a18
	v_accvgpr_read_b32 v73, a19
	v_accvgpr_read_b32 v74, a20
	v_accvgpr_read_b32 v75, a21
	v_accvgpr_read_b32 v76, a22
	v_accvgpr_read_b32 v77, a23
	v_accvgpr_read_b32 v78, a24
	v_accvgpr_read_b32 v79, a25
	v_accvgpr_read_b32 v80, a26
	v_accvgpr_read_b32 v81, a27
	v_accvgpr_read_b32 v82, a28
	v_accvgpr_read_b32 v83, a29
	v_accvgpr_read_b32 v84, a30
	v_accvgpr_read_b32 v85, a31
	s_lshl_b32 s10, s5, 12
	s_cmp_lt_u32 s5, 0x800
	s_cselect_b64 s[34:35], s[48:49], s[50:51]
	s_add_u32 s34, s34, s10
	s_addc_u32 s35, s35, 0
	s_lshr_b32 s10, s10, 1
	s_add_u32 s36, s54, s10
	s_addc_u32 s37, s55, 0
	v_cvt_f32_f16_e32 v154, v70
	v_cvt_f32_f16_e32 v155, v78
	v_add_f32_e32 v154, v154, v155
	v_fmac_f32_e32 v54, v32, v154
	v_cvt_f32_f16_sdwa v156, v70 dst_sel:DWORD dst_unused:UNUSED_PAD src0_sel:WORD_1
	v_cvt_f32_f16_sdwa v157, v78 dst_sel:DWORD dst_unused:UNUSED_PAD src0_sel:WORD_1
	v_add_f32_e32 v156, v156, v157
	v_fmac_f32_e32 v55, v33, v156
	v_cvt_f32_f16_e32 v154, v71
	v_cvt_f32_f16_e32 v155, v79
	v_add_f32_e32 v154, v154, v155
	v_fmac_f32_e32 v56, v34, v154
	v_cvt_f32_f16_sdwa v156, v71 dst_sel:DWORD dst_unused:UNUSED_PAD src0_sel:WORD_1
	v_cvt_f32_f16_sdwa v157, v79 dst_sel:DWORD dst_unused:UNUSED_PAD src0_sel:WORD_1
	v_add_f32_e32 v156, v156, v157
	v_fmac_f32_e32 v57, v35, v156
	v_cvt_f32_f16_e32 v154, v72
	v_cvt_f32_f16_e32 v155, v80
	v_add_f32_e32 v154, v154, v155
	v_fmac_f32_e32 v58, v36, v154
	v_cvt_f32_f16_sdwa v156, v72 dst_sel:DWORD dst_unused:UNUSED_PAD src0_sel:WORD_1
	v_cvt_f32_f16_sdwa v157, v80 dst_sel:DWORD dst_unused:UNUSED_PAD src0_sel:WORD_1
	v_add_f32_e32 v156, v156, v157
	v_fmac_f32_e32 v59, v37, v156
	v_cvt_f32_f16_e32 v154, v73
	v_cvt_f32_f16_e32 v155, v81
	v_add_f32_e32 v154, v154, v155
	v_fmac_f32_e32 v60, v38, v154
	v_cvt_f32_f16_sdwa v156, v73 dst_sel:DWORD dst_unused:UNUSED_PAD src0_sel:WORD_1
	v_cvt_f32_f16_sdwa v157, v81 dst_sel:DWORD dst_unused:UNUSED_PAD src0_sel:WORD_1
	v_add_f32_e32 v156, v156, v157
	v_fmac_f32_e32 v61, v39, v156
	v_cvt_f32_f16_e32 v154, v74
	v_cvt_f32_f16_e32 v155, v82
	v_add_f32_e32 v154, v154, v155
	v_fmac_f32_e32 v62, v40, v154
	v_cvt_f32_f16_sdwa v156, v74 dst_sel:DWORD dst_unused:UNUSED_PAD src0_sel:WORD_1
	v_cvt_f32_f16_sdwa v157, v82 dst_sel:DWORD dst_unused:UNUSED_PAD src0_sel:WORD_1
	v_add_f32_e32 v156, v156, v157
	v_fmac_f32_e32 v63, v41, v156
	v_cvt_f32_f16_e32 v154, v75
	v_cvt_f32_f16_e32 v155, v83
	v_add_f32_e32 v154, v154, v155
	v_fmac_f32_e32 v64, v42, v154
	v_cvt_f32_f16_sdwa v156, v75 dst_sel:DWORD dst_unused:UNUSED_PAD src0_sel:WORD_1
	v_cvt_f32_f16_sdwa v157, v83 dst_sel:DWORD dst_unused:UNUSED_PAD src0_sel:WORD_1
	v_add_f32_e32 v156, v156, v157
	v_fmac_f32_e32 v65, v43, v156
	v_cvt_f32_f16_e32 v154, v76
	v_cvt_f32_f16_e32 v155, v84
	v_add_f32_e32 v154, v154, v155
	v_fmac_f32_e32 v66, v44, v154
	v_cvt_f32_f16_sdwa v156, v76 dst_sel:DWORD dst_unused:UNUSED_PAD src0_sel:WORD_1
	v_cvt_f32_f16_sdwa v157, v84 dst_sel:DWORD dst_unused:UNUSED_PAD src0_sel:WORD_1
	v_add_f32_e32 v156, v156, v157
	v_fmac_f32_e32 v67, v45, v156
	v_cvt_f32_f16_e32 v154, v77
	v_cvt_f32_f16_e32 v155, v85
	v_add_f32_e32 v154, v154, v155
	v_fmac_f32_e32 v68, v46, v154
	v_cvt_f32_f16_sdwa v156, v77 dst_sel:DWORD dst_unused:UNUSED_PAD src0_sel:WORD_1
	v_cvt_f32_f16_sdwa v157, v85 dst_sel:DWORD dst_unused:UNUSED_PAD src0_sel:WORD_1
	v_add_f32_e32 v156, v156, v157
	v_fmac_f32_e32 v69, v47, v156
	global_store_dwordx4 v150, v[54:57], s[34:35] offset:0
	global_store_dwordx4 v150, v[58:61], s[34:35] offset:1024
	global_store_dwordx4 v150, v[62:65], s[34:35] offset:2048
	global_store_dwordx4 v150, v[66:69], s[34:35] offset:3072
	v_mul_f32_e32 v152, v54, v54
	v_mul_f32_e32 v153, v55, v55
	v_fmac_f32_e32 v152, v56, v56
	v_fmac_f32_e32 v153, v57, v57
	v_fmac_f32_e32 v152, v58, v58
	v_fmac_f32_e32 v153, v59, v59
	v_fmac_f32_e32 v152, v60, v60
	v_fmac_f32_e32 v153, v61, v61
	v_fmac_f32_e32 v152, v62, v62
	v_fmac_f32_e32 v153, v63, v63
	v_fmac_f32_e32 v152, v64, v64
	v_fmac_f32_e32 v153, v65, v65
	v_fmac_f32_e32 v152, v66, v66
	v_fmac_f32_e32 v153, v67, v67
	v_fmac_f32_e32 v152, v68, v68
	v_fmac_f32_e32 v153, v69, v69
	v_add_f32_e32 v152, v152, v153
	s_nop 1
	v_add_f32_dpp v152, v152, v152 row_ror:8 row_mask:0xf bank_mask:0xf
	s_nop 1
	v_add_f32_dpp v152, v152, v152 row_ror:4 row_mask:0xf bank_mask:0xf
	s_nop 1
	v_add_f32_dpp v152, v152, v152 row_ror:2 row_mask:0xf bank_mask:0xf
	s_nop 1
	v_add_f32_dpp v152, v152, v152 row_ror:1 row_mask:0xf bank_mask:0xf
	s_nop 1
	v_readlane_b32 s22, v152, 0
	v_readlane_b32 s23, v152, 16
	v_readlane_b32 s32, v152, 32
	v_readlane_b32 s99, v152, 48
	v_mov_b32_e32 v152, s22
	v_add_f32_e32 v152, s23, v152
	v_add_f32_e32 v152, s32, v152
	v_add_f32_e32 v152, s99, v152
	v_mov_b32_e32 v153, 0x358637bd
	v_fmamk_f32 v152, v152, 0x3a800000, v153
	v_rsq_f32_e32 v152, v152
	s_nop 1
	v_mul_f32_e32 v54, v54, v152
	v_mul_f32_e32 v55, v55, v152
	v_mul_f32_e32 v56, v56, v152
	v_mul_f32_e32 v57, v57, v152
	v_mul_f32_e32 v58, v58, v152
	v_mul_f32_e32 v59, v59, v152
	v_mul_f32_e32 v60, v60, v152
	v_mul_f32_e32 v61, v61, v152
	v_mul_f32_e32 v62, v62, v152
	v_mul_f32_e32 v63, v63, v152
	v_mul_f32_e32 v64, v64, v152
	v_mul_f32_e32 v65, v65, v152
	v_mul_f32_e32 v66, v66, v152
	v_mul_f32_e32 v67, v67, v152
	v_mul_f32_e32 v68, v68, v152
	v_mul_f32_e32 v69, v69, v152
	v_fma_f32 v54, v54, v0, v16
	v_fma_f32 v55, v55, v1, v17
	v_fma_f32 v56, v56, v2, v18
	v_fma_f32 v57, v57, v3, v19
	v_fma_f32 v58, v58, v4, v20
	v_fma_f32 v59, v59, v5, v21
	v_fma_f32 v60, v60, v6, v22
	v_fma_f32 v61, v61, v7, v23
	v_fma_f32 v62, v62, v8, v24
	v_fma_f32 v63, v63, v9, v25
	v_fma_f32 v64, v64, v10, v26
	v_fma_f32 v65, v65, v11, v27
	v_fma_f32 v66, v66, v12, v28
	v_fma_f32 v67, v67, v13, v29
	v_fma_f32 v68, v68, v14, v30
	v_fma_f32 v69, v69, v15, v31
	v_cvt_pk_f16_f32 v70, v54, v55
	v_cvt_pk_f16_f32 v71, v56, v57
	v_cvt_pk_f16_f32 v72, v58, v59
	v_cvt_pk_f16_f32 v73, v60, v61
	v_cvt_pk_f16_f32 v74, v62, v63
	v_cvt_pk_f16_f32 v75, v64, v65
	v_cvt_pk_f16_f32 v76, v66, v67
	v_cvt_pk_f16_f32 v77, v68, v69
	global_store_dwordx2 v151, v[70:71], s[36:37] offset:0
	global_store_dwordx2 v151, v[72:73], s[36:37] offset:512
	global_store_dwordx2 v151, v[74:75], s[36:37] offset:1024
	global_store_dwordx2 v151, v[76:77], s[36:37] offset:1536
	s_add_u32 s5, s5, 1
	s_sub_u32 s9, s5, 0x800
	s_lshr_b32 s9, s9, 13
	s_cmp_lt_u32 s5, 0x800
	s_cselect_b32 s9, 8, s9
	s_cmp_eq_u32 s9, s8
	s_cbranch_scc1 .Lr1b_nr10
; DI void row1_phase(const Params& P, int combine_l, int norm_l, int r_begin) {
;     ...
;       const float* g2 = P.mod + (size_t)(combine_l * 9 + n) * 6144 + 5 * 1024;
; #pragma unroll
;       for (int i = 0; i < 4; i++) {
;         int c = i * 256 + lane * 4;
;         float4 g = *(const float4*)(g2 + c); float4 t = xv[i];
;         t.x += g.x * ((float)ya[i][0] + (float)yb[i][0]); t.y += g.y * ((float)ya[i][1] + (float)yb[i][1]);
;         t.z += g.z * ((float)ya[i][2] + (float)yb[i][2]); t.w += g.w * ((float)ya[i][3] + (float)yb[i][3]);
;         *(float4*)(xm + c) = t; xv[i] = t;
;       }
;     }
;     if (norm_l >= 0) {
;       float ss = 0.f;
; #pragma unroll
;       for (int i = 0; i < 4; i++) ss += xv[i].x * xv[i].x + xv[i].y * xv[i].y + xv[i].z * xv[i].z + xv[i].w * xv[i].w;
;       ss = wave_sum(ss);
;       const float rstd = rsqrtf(ss * (1.f / 1024.f) + EPS);
;       const float* g = P.norm1_g + norm_l * 1024;
;       const float* sh = P.mod + (size_t)(norm_l * 9 + n) * 6144; const float* sc = sh + 1024;
; #pragma unroll
;       for (int i = 0; i < 4; i++) {
;         int c = i * 256 + lane * 4;
;         float4 gg = *(const float4*)(g + c), s1 = *(const float4*)(sc + c), s0 = *(const float4*)(sh + c);
	s_mov_b32 s8, s9
	s_waitcnt vmcnt(0)
	s_add_u32 s10, s9, 9
	s_mul_i32 s10, s10, 0x6000
	s_add_u32 s38, s56, s10
	s_addc_u32 s39, s57, 0
	global_load_dwordx4 v[54:57], v150, s[58:59] offset:0
	global_load_dwordx4 v[58:61], v150, s[58:59] offset:1024
	global_load_dwordx4 v[62:65], v150, s[58:59] offset:2048
	global_load_dwordx4 v[66:69], v150, s[58:59] offset:3072
	s_add_u32 s44, s38, 0x1000
	s_addc_u32 s45, s39, 0
	global_load_dwordx4 v[70:73], v150, s[44:45] offset:0
	global_load_dwordx4 v[74:77], v150, s[44:45] offset:1024
	global_load_dwordx4 v[78:81], v150, s[44:45] offset:2048
	global_load_dwordx4 v[82:85], v150, s[44:45] offset:3072
	global_load_dwordx4 v[16:19], v150, s[38:39] offset:0
	global_load_dwordx4 v[20:23], v150, s[38:39] offset:1024
	global_load_dwordx4 v[24:27], v150, s[38:39] offset:2048
	global_load_dwordx4 v[28:31], v150, s[38:39] offset:3072
	s_add_u32 s10, s9, 0
	s_mul_i32 s10, s10, 0x6000
	s_add_u32 s10, s10, 0x5000
	s_add_u32 s38, s56, s10
	s_addc_u32 s39, s57, 0
	global_load_dwordx4 v[32:35], v150, s[38:39] offset:0
	global_load_dwordx4 v[36:39], v150, s[38:39] offset:1024
	global_load_dwordx4 v[40:43], v150, s[38:39] offset:2048
	global_load_dwordx4 v[44:47], v150, s[38:39] offset:3072
	s_waitcnt vmcnt(0)
	v_add_f32_e32 v70, 1.0, v70
	v_add_f32_e32 v71, 1.0, v71
	v_add_f32_e32 v72, 1.0, v72
	v_add_f32_e32 v73, 1.0, v73
	v_add_f32_e32 v74, 1.0, v74
	v_add_f32_e32 v75, 1.0, v75
	v_add_f32_e32 v76, 1.0, v76
	v_add_f32_e32 v77, 1.0, v77
	v_add_f32_e32 v78, 1.0, v78
	v_add_f32_e32 v79, 1.0, v79
	v_add_f32_e32 v80, 1.0, v80
	v_add_f32_e32 v81, 1.0, v81
	v_add_f32_e32 v82, 1.0, v82
	v_add_f32_e32 v83, 1.0, v83
	v_add_f32_e32 v84, 1.0, v84
	v_add_f32_e32 v85, 1.0, v85
	v_mul_f32_e32 v0, v54, v70
	v_mul_f32_e32 v1, v55, v71
	v_mul_f32_e32 v2, v56, v72
	v_mul_f32_e32 v3, v57, v73
	v_mul_f32_e32 v4, v58, v74
	v_mul_f32_e32 v5, v59, v75
	v_mul_f32_e32 v6, v60, v76
	v_mul_f32_e32 v7, v61, v77
	v_mul_f32_e32 v8, v62, v78
	v_mul_f32_e32 v9, v63, v79
	v_mul_f32_e32 v10, v64, v80
	v_mul_f32_e32 v11, v65, v81
	v_mul_f32_e32 v12, v66, v82
	v_mul_f32_e32 v13, v67, v83
	v_mul_f32_e32 v14, v68, v84
	v_mul_f32_e32 v15, v69, v85
; DI void row1_phase(const Params& P, int combine_l, int norm_l, int r_begin) {
;     ...
;     if (combine_l >= 0) {
;       float* xm = r < TC ? P.xcbuf + (size_t)r * D : P.out + (size_t)(r - TC) * D;
;       const float* g2 = P.mod + (size_t)(combine_l * 9 + n) * 6144 + 5 * 1024;
; #pragma unroll
;       for (int i = 0; i < 4; i++) {
;         int c = i * 256 + lane * 4;
;         float4 g = *(const float4*)(g2 + c); float4 t = xv[i];
;         t.x += g.x * ((float)ya[i][0] + (float)yb[i][0]); t.y += g.y * ((float)ya[i][1] + (float)yb[i][1]);
;         t.z += g.z * ((float)ya[i][2] + (float)yb[i][2]); t.w += g.w * ((float)ya[i][3] + (float)yb[i][3]);
;         *(float4*)(xm + c) = t; xv[i] = t;
;       }
;     }
;     if (norm_l >= 0) {
;       float ss = 0.f;
; #pragma unroll
;       for (int i = 0; i < 4; i++) ss += xv[i].x * xv[i].x + xv[i].y * xv[i].y + xv[i].z * xv[i].z + xv[i].w * xv[i].w;
;       ss = wave_sum(ss);
;       const float rstd = rsqrtf(ss * (1.f / 1024.f) + EPS);
;       const float* g = P.norm1_g + norm_l * 1024;
;       const float* sh = P.mod + (size_t)(norm_l * 9 + n) * 6144; const float* sc = sh + 1024;
; #pragma unroll
;       for (int i = 0; i < 4; i++) {
;         int c = i * 256 + lane * 4;
;         float4 gg = *(const float4*)(g + c), s1 = *(const float4*)(sc + c), s0 = *(const float4*)(sh + c);
;         h4 o;
;         o[0] = (half_t)(xv[i].x * rstd * gg.x * (1.f + s1.x) + s0.x); o[1] = (half_t)(xv[i].y * rstd * gg.y * (1.f + s1.y) + s0.y);
;         o[2] = (half_t)(xv[i].z * rstd * gg.z * (1.f + s1.z) + s0.z); o[3] = (half_t)(xv[i].w * rstd * gg.w * (1.f + s1.w) + s0.w);
;         *(h4*)(P.hx + (size_t)r * D + c) = o;
;       }
.Lr1b_nr10:
	s_waitcnt vmcnt(8)
	v_accvgpr_read_b32 v54, a32
	v_accvgpr_read_b32 v55, a33
	v_accvgpr_read_b32 v56, a34
	v_accvgpr_read_b32 v57, a35
	v_accvgpr_read_b32 v58, a36
	v_accvgpr_read_b32 v59, a37
	v_accvgpr_read_b32 v60, a38
	v_accvgpr_read_b32 v61, a39
	v_accvgpr_read_b32 v62, a40
	v_accvgpr_read_b32 v63, a41
	v_accvgpr_read_b32 v64, a42
	v_accvgpr_read_b32 v65, a43
	v_accvgpr_read_b32 v66, a44
	v_accvgpr_read_b32 v67, a45
	v_accvgpr_read_b32 v68, a46
	v_accvgpr_read_b32 v69, a47
	v_accvgpr_read_b32 v70, a48
	v_accvgpr_read_b32 v71, a49
	v_accvgpr_read_b32 v72, a50
	v_accvgpr_read_b32 v73, a51
	v_accvgpr_read_b32 v74, a52
	v_accvgpr_read_b32 v75, a53
	v_accvgpr_read_b32 v76, a54
	v_accvgpr_read_b32 v77, a55
	v_accvgpr_read_b32 v78, a56
	v_accvgpr_read_b32 v79, a57
	v_accvgpr_read_b32 v80, a58
	v_accvgpr_read_b32 v81, a59
	v_accvgpr_read_b32 v82, a60
	v_accvgpr_read_b32 v83, a61
	v_accvgpr_read_b32 v84, a62
	v_accvgpr_read_b32 v85, a63
	s_lshl_b32 s10, s5, 12
	s_cmp_lt_u32 s5, 0x800
	s_cselect_b64 s[34:35], s[48:49], s[50:51]
	s_add_u32 s34, s34, s10
	s_addc_u32 s35, s35, 0
	s_lshr_b32 s10, s10, 1
	s_add_u32 s36, s54, s10
	s_addc_u32 s37, s55, 0
	v_cvt_f32_f16_e32 v154, v70
	v_cvt_f32_f16_e32 v155, v78
	v_add_f32_e32 v154, v154, v155
	v_fmac_f32_e32 v54, v32, v154
	v_cvt_f32_f16_sdwa v156, v70 dst_sel:DWORD dst_unused:UNUSED_PAD src0_sel:WORD_1
	v_cvt_f32_f16_sdwa v157, v78 dst_sel:DWORD dst_unused:UNUSED_PAD src0_sel:WORD_1
	v_add_f32_e32 v156, v156, v157
	v_fmac_f32_e32 v55, v33, v156
	v_cvt_f32_f16_e32 v154, v71
	v_cvt_f32_f16_e32 v155, v79
	v_add_f32_e32 v154, v154, v155
	v_fmac_f32_e32 v56, v34, v154
	v_cvt_f32_f16_sdwa v156, v71 dst_sel:DWORD dst_unused:UNUSED_PAD src0_sel:WORD_1
	v_cvt_f32_f16_sdwa v157, v79 dst_sel:DWORD dst_unused:UNUSED_PAD src0_sel:WORD_1
	v_add_f32_e32 v156, v156, v157
	v_fmac_f32_e32 v57, v35, v156
	v_cvt_f32_f16_e32 v154, v72
	v_cvt_f32_f16_e32 v155, v80
	v_add_f32_e32 v154, v154, v155
	v_fmac_f32_e32 v58, v36, v154
	v_cvt_f32_f16_sdwa v156, v72 dst_sel:DWORD dst_unused:UNUSED_PAD src0_sel:WORD_1
	v_cvt_f32_f16_sdwa v157, v80 dst_sel:DWORD dst_unused:UNUSED_PAD src0_sel:WORD_1
	v_add_f32_e32 v156, v156, v157
	v_fmac_f32_e32 v59, v37, v156
	v_cvt_f32_f16_e32 v154, v73
	v_cvt_f32_f16_e32 v155, v81
	v_add_f32_e32 v154, v154, v155
	v_fmac_f32_e32 v60, v38, v154
	v_cvt_f32_f16_sdwa v156, v73 dst_sel:DWORD dst_unused:UNUSED_PAD src0_sel:WORD_1
	v_cvt_f32_f16_sdwa v157, v81 dst_sel:DWORD dst_unused:UNUSED_PAD src0_sel:WORD_1
	v_add_f32_e32 v156, v156, v157
	v_fmac_f32_e32 v61, v39, v156
	v_cvt_f32_f16_e32 v154, v74
	v_cvt_f32_f16_e32 v155, v82
	v_add_f32_e32 v154, v154, v155
	v_fmac_f32_e32 v62, v40, v154
	v_cvt_f32_f16_sdwa v156, v74 dst_sel:DWORD dst_unused:UNUSED_PAD src0_sel:WORD_1
	v_cvt_f32_f16_sdwa v157, v82 dst_sel:DWORD dst_unused:UNUSED_PAD src0_sel:WORD_1
	v_add_f32_e32 v156, v156, v157
	v_fmac_f32_e32 v63, v41, v156
	v_cvt_f32_f16_e32 v154, v75
	v_cvt_f32_f16_e32 v155, v83
	v_add_f32_e32 v154, v154, v155
	v_fmac_f32_e32 v64, v42, v154
	v_cvt_f32_f16_sdwa v156, v75 dst_sel:DWORD dst_unused:UNUSED_PAD src0_sel:WORD_1
	v_cvt_f32_f16_sdwa v157, v83 dst_sel:DWORD dst_unused:UNUSED_PAD src0_sel:WORD_1
	v_add_f32_e32 v156, v156, v157
	v_fmac_f32_e32 v65, v43, v156
	v_cvt_f32_f16_e32 v154, v76
	v_cvt_f32_f16_e32 v155, v84
	v_add_f32_e32 v154, v154, v155
	v_fmac_f32_e32 v66, v44, v154
	v_cvt_f32_f16_sdwa v156, v76 dst_sel:DWORD dst_unused:UNUSED_PAD src0_sel:WORD_1
	v_cvt_f32_f16_sdwa v157, v84 dst_sel:DWORD dst_unused:UNUSED_PAD src0_sel:WORD_1
	v_add_f32_e32 v156, v156, v157
	v_fmac_f32_e32 v67, v45, v156
	v_cvt_f32_f16_e32 v154, v77
	v_cvt_f32_f16_e32 v155, v85
	v_add_f32_e32 v154, v154, v155
	v_fmac_f32_e32 v68, v46, v154
	v_cvt_f32_f16_sdwa v156, v77 dst_sel:DWORD dst_unused:UNUSED_PAD src0_sel:WORD_1
	v_cvt_f32_f16_sdwa v157, v85 dst_sel:DWORD dst_unused:UNUSED_PAD src0_sel:WORD_1
	v_add_f32_e32 v156, v156, v157
	v_fmac_f32_e32 v69, v47, v156
	global_store_dwordx4 v150, v[54:57], s[34:35] offset:0
	global_store_dwordx4 v150, v[58:61], s[34:35] offset:1024
	global_store_dwordx4 v150, v[62:65], s[34:35] offset:2048
	global_store_dwordx4 v150, v[66:69], s[34:35] offset:3072
	v_mul_f32_e32 v152, v54, v54
	v_mul_f32_e32 v153, v55, v55
	v_fmac_f32_e32 v152, v56, v56
	v_fmac_f32_e32 v153, v57, v57
	v_fmac_f32_e32 v152, v58, v58
	v_fmac_f32_e32 v153, v59, v59
	v_fmac_f32_e32 v152, v60, v60
	v_fmac_f32_e32 v153, v61, v61
	v_fmac_f32_e32 v152, v62, v62
	v_fmac_f32_e32 v153, v63, v63
	v_fmac_f32_e32 v152, v64, v64
	v_fmac_f32_e32 v153, v65, v65
	v_fmac_f32_e32 v152, v66, v66
	v_fmac_f32_e32 v153, v67, v67
	v_fmac_f32_e32 v152, v68, v68
	v_fmac_f32_e32 v153, v69, v69
	v_add_f32_e32 v152, v152, v153
	s_nop 1
	v_add_f32_dpp v152, v152, v152 row_ror:8 row_mask:0xf bank_mask:0xf
	s_nop 1
	v_add_f32_dpp v152, v152, v152 row_ror:4 row_mask:0xf bank_mask:0xf
	s_nop 1
	v_add_f32_dpp v152, v152, v152 row_ror:2 row_mask:0xf bank_mask:0xf
	s_nop 1
	v_add_f32_dpp v152, v152, v152 row_ror:1 row_mask:0xf bank_mask:0xf
	s_nop 1
	v_readlane_b32 s22, v152, 0
	v_readlane_b32 s23, v152, 16
	v_readlane_b32 s32, v152, 32
	v_readlane_b32 s99, v152, 48
	v_mov_b32_e32 v152, s22
	v_add_f32_e32 v152, s23, v152
	v_add_f32_e32 v152, s32, v152
	v_add_f32_e32 v152, s99, v152
	v_mov_b32_e32 v153, 0x358637bd
	v_fmamk_f32 v152, v152, 0x3a800000, v153
	v_rsq_f32_e32 v152, v152
	s_nop 1
	v_mul_f32_e32 v54, v54, v152
	v_mul_f32_e32 v55, v55, v152
	v_mul_f32_e32 v56, v56, v152
	v_mul_f32_e32 v57, v57, v152
	v_mul_f32_e32 v58, v58, v152
	v_mul_f32_e32 v59, v59, v152
	v_mul_f32_e32 v60, v60, v152
	v_mul_f32_e32 v61, v61, v152
	v_mul_f32_e32 v62, v62, v152
	v_mul_f32_e32 v63, v63, v152
	v_mul_f32_e32 v64, v64, v152
	v_mul_f32_e32 v65, v65, v152
	v_mul_f32_e32 v66, v66, v152
	v_mul_f32_e32 v67, v67, v152
	v_mul_f32_e32 v68, v68, v152
	v_mul_f32_e32 v69, v69, v152
	v_fma_f32 v54, v54, v0, v16
	v_fma_f32 v55, v55, v1, v17
	v_fma_f32 v56, v56, v2, v18
	v_fma_f32 v57, v57, v3, v19
	v_fma_f32 v58, v58, v4, v20
	v_fma_f32 v59, v59, v5, v21
	v_fma_f32 v60, v60, v6, v22
	v_fma_f32 v61, v61, v7, v23
	v_fma_f32 v62, v62, v8, v24
	v_fma_f32 v63, v63, v9, v25
	v_fma_f32 v64, v64, v10, v26
	v_fma_f32 v65, v65, v11, v27
	v_fma_f32 v66, v66, v12, v28
	v_fma_f32 v67, v67, v13, v29
	v_fma_f32 v68, v68, v14, v30
	v_fma_f32 v69, v69, v15, v31
	v_cvt_pk_f16_f32 v70, v54, v55
	v_cvt_pk_f16_f32 v71, v56, v57
	v_cvt_pk_f16_f32 v72, v58, v59
	v_cvt_pk_f16_f32 v73, v60, v61
	v_cvt_pk_f16_f32 v74, v62, v63
	v_cvt_pk_f16_f32 v75, v64, v65
	v_cvt_pk_f16_f32 v76, v66, v67
	v_cvt_pk_f16_f32 v77, v68, v69
	global_store_dwordx2 v151, v[70:71], s[36:37] offset:0
	global_store_dwordx2 v151, v[72:73], s[36:37] offset:512
	global_store_dwordx2 v151, v[74:75], s[36:37] offset:1024
	global_store_dwordx2 v151, v[76:77], s[36:37] offset:1536
	s_add_u32 s5, s5, 1
	s_waitcnt vmcnt(0)
	s_branch .Lr1_done

; DI void row1_phase(const Params& P, int combine_l, int norm_l, int r_begin) {
;     ...
;       const float* src = r < TC ? P.ctx + (size_t)r * D : P.x + (size_t)(r - TC) * D;
; #pragma unroll
;       for (int i = 0; i < 4; i++) xv[i] = *(const float4*)(src + i * 256 + lane * 4);
;     ...
;     if (norm_l >= 0) {
;       float ss = 0.f;
; #pragma unroll
;       for (int i = 0; i < 4; i++) ss += xv[i].x * xv[i].x + xv[i].y * xv[i].y + xv[i].z * xv[i].z + xv[i].w * xv[i].w;
;       ss = wave_sum(ss);
;       const float rstd = rsqrtf(ss * (1.f / 1024.f) + EPS);
;       const float* g = P.norm1_g + norm_l * 1024;
;       const float* sh = P.mod + (size_t)(norm_l * 9 + n) * 6144; const float* sc = sh + 1024;
; #pragma unroll
;       for (int i = 0; i < 4; i++) {
;         int c = i * 256 + lane * 4;
;         float4 gg = *(const float4*)(g + c), s1 = *(const float4*)(sc + c), s0 = *(const float4*)(sh + c);
;         h4 o;
;         o[0] = (half_t)(xv[i].x * rstd * gg.x * (1.f + s1.x) + s0.x); o[1] = (half_t)(xv[i].y * rstd * gg.y * (1.f + s1.y) + s0.y);
;         o[2] = (half_t)(xv[i].z * rstd * gg.z * (1.f + s1.z) + s0.z); o[3] = (half_t)(xv[i].w * rstd * gg.w * (1.f + s1.w) + s0.w);
;         *(h4*)(P.hx + (size_t)r * D + c) = o;
;       }
.Lr1a_nr1:
	s_waitcnt vmcnt(16)
	v_accvgpr_read_b32 v54, a0
	v_accvgpr_read_b32 v55, a1
	v_accvgpr_read_b32 v56, a2
	v_accvgpr_read_b32 v57, a3
	v_accvgpr_read_b32 v58, a4
	v_accvgpr_read_b32 v59, a5
	v_accvgpr_read_b32 v60, a6
	v_accvgpr_read_b32 v61, a7
	v_accvgpr_read_b32 v62, a8
	v_accvgpr_read_b32 v63, a9
	v_accvgpr_read_b32 v64, a10
	v_accvgpr_read_b32 v65, a11
	v_accvgpr_read_b32 v66, a12
	v_accvgpr_read_b32 v67, a13
	v_accvgpr_read_b32 v68, a14
	v_accvgpr_read_b32 v69, a15
	s_lshl_b32 s10, s5, 12
	s_lshr_b32 s10, s10, 1
	s_add_u32 s36, s54, s10
	s_addc_u32 s37, s55, 0
	s_cmp_lt_u32 s7, 0x800
	s_cselect_b64 s[60:61], s[48:49], s[50:51]
	s_lshl_b32 s10, s7, 12
	s_add_u32 s60, s60, s10
	s_addc_u32 s61, s61, 0
	global_load_dwordx4 a[0:3], v150, s[60:61] offset:0 nt
	global_load_dwordx4 a[4:7], v150, s[60:61] offset:1024 nt
	global_load_dwordx4 a[8:11], v150, s[60:61] offset:2048 nt
	global_load_dwordx4 a[12:15], v150, s[60:61] offset:3072 nt
	s_add_u32 s7, s7, 1
	v_mul_f32_e32 v152, v54, v54
	v_mul_f32_e32 v153, v55, v55
	v_fmac_f32_e32 v152, v56, v56
	v_fmac_f32_e32 v153, v57, v57
	v_fmac_f32_e32 v152, v58, v58
	v_fmac_f32_e32 v153, v59, v59
	v_fmac_f32_e32 v152, v60, v60
	v_fmac_f32_e32 v153, v61, v61
	v_fmac_f32_e32 v152, v62, v62
	v_fmac_f32_e32 v153, v63, v63
	v_fmac_f32_e32 v152, v64, v64
	v_fmac_f32_e32 v153, v65, v65
	v_fmac_f32_e32 v152, v66, v66
	v_fmac_f32_e32 v153, v67, v67
	v_fmac_f32_e32 v152, v68, v68
	v_fmac_f32_e32 v153, v69, v69
	v_add_f32_e32 v152, v152, v153
	s_nop 1
	v_add_f32_dpp v152, v152, v152 row_ror:8 row_mask:0xf bank_mask:0xf
	s_nop 1
	v_add_f32_dpp v152, v152, v152 row_ror:4 row_mask:0xf bank_mask:0xf
	s_nop 1
	v_add_f32_dpp v152, v152, v152 row_ror:2 row_mask:0xf bank_mask:0xf
	s_nop 1
	v_add_f32_dpp v152, v152, v152 row_ror:1 row_mask:0xf bank_mask:0xf
	s_nop 1
	v_readlane_b32 s22, v152, 0
	v_readlane_b32 s23, v152, 16
	v_readlane_b32 s32, v152, 32
	v_readlane_b32 s99, v152, 48
	v_mov_b32_e32 v152, s22
	v_add_f32_e32 v152, s23, v152
	v_add_f32_e32 v152, s32, v152
	v_add_f32_e32 v152, s99, v152
	v_mov_b32_e32 v153, 0x358637bd
	v_fmamk_f32 v152, v152, 0x3a800000, v153
	v_rsq_f32_e32 v152, v152
	s_nop 1
	v_mul_f32_e32 v54, v54, v152
	v_mul_f32_e32 v55, v55, v152
	v_mul_f32_e32 v56, v56, v152
	v_mul_f32_e32 v57, v57, v152
	v_mul_f32_e32 v58, v58, v152
	v_mul_f32_e32 v59, v59, v152
	v_mul_f32_e32 v60, v60, v152
	v_mul_f32_e32 v61, v61, v152
	v_mul_f32_e32 v62, v62, v152
	v_mul_f32_e32 v63, v63, v152
	v_mul_f32_e32 v64, v64, v152
	v_mul_f32_e32 v65, v65, v152
	v_mul_f32_e32 v66, v66, v152
	v_mul_f32_e32 v67, v67, v152
	v_mul_f32_e32 v68, v68, v152
	v_mul_f32_e32 v69, v69, v152
	v_fma_f32 v54, v54, v0, v16
	v_fma_f32 v55, v55, v1, v17
	v_fma_f32 v56, v56, v2, v18
	v_fma_f32 v57, v57, v3, v19
	v_fma_f32 v58, v58, v4, v20
	v_fma_f32 v59, v59, v5, v21
	v_fma_f32 v60, v60, v6, v22
	v_fma_f32 v61, v61, v7, v23
	v_fma_f32 v62, v62, v8, v24
	v_fma_f32 v63, v63, v9, v25
	v_fma_f32 v64, v64, v10, v26
	v_fma_f32 v65, v65, v11, v27
	v_fma_f32 v66, v66, v12, v28
	v_fma_f32 v67, v67, v13, v29
	v_fma_f32 v68, v68, v14, v30
	v_fma_f32 v69, v69, v15, v31
	v_cvt_pk_f16_f32 v70, v54, v55
	v_cvt_pk_f16_f32 v71, v56, v57
	v_cvt_pk_f16_f32 v72, v58, v59
	v_cvt_pk_f16_f32 v73, v60, v61
	v_cvt_pk_f16_f32 v74, v62, v63
	v_cvt_pk_f16_f32 v75, v64, v65
	v_cvt_pk_f16_f32 v76, v66, v67
	v_cvt_pk_f16_f32 v77, v68, v69
	global_store_dwordx2 v151, v[70:71], s[36:37] offset:0
	global_store_dwordx2 v151, v[72:73], s[36:37] offset:512
	global_store_dwordx2 v151, v[74:75], s[36:37] offset:1024
	global_store_dwordx2 v151, v[76:77], s[36:37] offset:1536
	s_add_u32 s5, s5, 1
	s_sub_u32 s9, s5, 0x800
	s_lshr_b32 s9, s9, 13
	s_cmp_lt_u32 s5, 0x800
	s_cselect_b32 s9, 8, s9
	s_cmp_eq_u32 s9, s8
	s_cbranch_scc1 .Lr1a_nr2
	s_mov_b32 s8, s9
	s_waitcnt vmcnt(0)
	s_add_u32 s10, s9, 0
	s_mul_i32 s10, s10, 0x6000
	s_add_u32 s38, s56, s10
	s_addc_u32 s39, s57, 0
	global_load_dwordx4 v[54:57], v150, s[58:59] offset:0
	global_load_dwordx4 v[58:61], v150, s[58:59] offset:1024
	global_load_dwordx4 v[62:65], v150, s[58:59] offset:2048
	global_load_dwordx4 v[66:69], v150, s[58:59] offset:3072
	s_add_u32 s44, s38, 0x1000
	s_addc_u32 s45, s39, 0
	global_load_dwordx4 v[70:73], v150, s[44:45] offset:0
	global_load_dwordx4 v[74:77], v150, s[44:45] offset:1024
	global_load_dwordx4 v[78:81], v150, s[44:45] offset:2048
	global_load_dwordx4 v[82:85], v150, s[44:45] offset:3072
	global_load_dwordx4 v[16:19], v150, s[38:39] offset:0
	global_load_dwordx4 v[20:23], v150, s[38:39] offset:1024
	global_load_dwordx4 v[24:27], v150, s[38:39] offset:2048
	global_load_dwordx4 v[28:31], v150, s[38:39] offset:3072
	s_waitcnt vmcnt(0)
	v_add_f32_e32 v70, 1.0, v70
	v_add_f32_e32 v71, 1.0, v71
	v_add_f32_e32 v72, 1.0, v72
	v_add_f32_e32 v73, 1.0, v73
	v_add_f32_e32 v74, 1.0, v74
	v_add_f32_e32 v75, 1.0, v75
	v_add_f32_e32 v76, 1.0, v76
	v_add_f32_e32 v77, 1.0, v77
	v_add_f32_e32 v78, 1.0, v78
	v_add_f32_e32 v79, 1.0, v79
	v_add_f32_e32 v80, 1.0, v80
	v_add_f32_e32 v81, 1.0, v81
	v_add_f32_e32 v82, 1.0, v82
	v_add_f32_e32 v83, 1.0, v83
	v_add_f32_e32 v84, 1.0, v84
	v_add_f32_e32 v85, 1.0, v85
	v_mul_f32_e32 v0, v54, v70
	v_mul_f32_e32 v1, v55, v71
	v_mul_f32_e32 v2, v56, v72
	v_mul_f32_e32 v3, v57, v73
	v_mul_f32_e32 v4, v58, v74
	v_mul_f32_e32 v5, v59, v75
	v_mul_f32_e32 v6, v60, v76
	v_mul_f32_e32 v7, v61, v77
	v_mul_f32_e32 v8, v62, v78
	v_mul_f32_e32 v9, v63, v79
	v_mul_f32_e32 v10, v64, v80
	v_mul_f32_e32 v11, v65, v81
	v_mul_f32_e32 v12, v66, v82
	v_mul_f32_e32 v13, v67, v83
	v_mul_f32_e32 v14, v68, v84
	v_mul_f32_e32 v15, v69, v85
; DI void row1_phase(const Params& P, int combine_l, int norm_l, int r_begin) {
;     ...
;       const float* src = r < TC ? P.ctx + (size_t)r * D : P.x + (size_t)(r - TC) * D;
; #pragma unroll
;       for (int i = 0; i < 4; i++) xv[i] = *(const float4*)(src + i * 256 + lane * 4);
;     ...
;     if (norm_l >= 0) {
;       float ss = 0.f;
; #pragma unroll
;       for (int i = 0; i < 4; i++) ss += xv[i].x * xv[i].x + xv[i].y * xv[i].y + xv[i].z * xv[i].z + xv[i].w * xv[i].w;
;       ss = wave_sum(ss);
;       const float rstd = rsqrtf(ss * (1.f / 1024.f) + EPS);
;       const float* g = P.norm1_g + norm_l * 1024;
;       const float* sh = P.mod + (size_t)(norm_l * 9 + n) * 6144; const float* sc = sh + 1024;
; #pragma unroll
;       for (int i = 0; i < 4; i++) {
;         int c = i * 256 + lane * 4;
;         float4 gg = *(const float4*)(g + c), s1 = *(const float4*)(sc + c), s0 = *(const float4*)(sh + c);
;         h4 o;
;         o[0] = (half_t)(xv[i].x * rstd * gg.x * (1.f + s1.x) + s0.x); o[1] = (half_t)(xv[i].y * rstd * gg.y * (1.f + s1.y) + s0.y);
;         o[2] = (half_t)(xv[i].z * rstd * gg.z * (1.f + s1.z) + s0.z); o[3] = (half_t)(xv[i].w * rstd * gg.w * (1.f + s1.w) + s0.w);
;         *(h4*)(P.hx + (size_t)r * D + c) = o;
;       }
.Lr1a_nr2:
	s_waitcnt vmcnt(16)
	v_accvgpr_read_b32 v54, a32
	v_accvgpr_read_b32 v55, a33
	v_accvgpr_read_b32 v56, a34
	v_accvgpr_read_b32 v57, a35
	v_accvgpr_read_b32 v58, a36
	v_accvgpr_read_b32 v59, a37
	v_accvgpr_read_b32 v60, a38
	v_accvgpr_read_b32 v61, a39
	v_accvgpr_read_b32 v62, a40
	v_accvgpr_read_b32 v63, a41
	v_accvgpr_read_b32 v64, a42
	v_accvgpr_read_b32 v65, a43
	v_accvgpr_read_b32 v66, a44
	v_accvgpr_read_b32 v67, a45
	v_accvgpr_read_b32 v68, a46
	v_accvgpr_read_b32 v69, a47
	s_lshl_b32 s10, s5, 12
	s_lshr_b32 s10, s10, 1
	s_add_u32 s36, s54, s10
	s_addc_u32 s37, s55, 0
	s_cmp_lt_u32 s7, 0x800
	s_cselect_b64 s[60:61], s[48:49], s[50:51]
	s_lshl_b32 s10, s7, 12
	s_add_u32 s60, s60, s10
	s_addc_u32 s61, s61, 0
	global_load_dwordx4 a[32:35], v150, s[60:61] offset:0 nt
	global_load_dwordx4 a[36:39], v150, s[60:61] offset:1024 nt
	global_load_dwordx4 a[40:43], v150, s[60:61] offset:2048 nt
	global_load_dwordx4 a[44:47], v150, s[60:61] offset:3072 nt
	s_add_u32 s7, s7, 1
	v_mul_f32_e32 v152, v54, v54
	v_mul_f32_e32 v153, v55, v55
	v_fmac_f32_e32 v152, v56, v56
	v_fmac_f32_e32 v153, v57, v57
	v_fmac_f32_e32 v152, v58, v58
	v_fmac_f32_e32 v153, v59, v59
	v_fmac_f32_e32 v152, v60, v60
	v_fmac_f32_e32 v153, v61, v61
	v_fmac_f32_e32 v152, v62, v62
	v_fmac_f32_e32 v153, v63, v63
	v_fmac_f32_e32 v152, v64, v64
	v_fmac_f32_e32 v153, v65, v65
	v_fmac_f32_e32 v152, v66, v66
	v_fmac_f32_e32 v153, v67, v67
	v_fmac_f32_e32 v152, v68, v68
	v_fmac_f32_e32 v153, v69, v69
	v_add_f32_e32 v152, v152, v153
	s_nop 1
	v_add_f32_dpp v152, v152, v152 row_ror:8 row_mask:0xf bank_mask:0xf
	s_nop 1
	v_add_f32_dpp v152, v152, v152 row_ror:4 row_mask:0xf bank_mask:0xf
	s_nop 1
	v_add_f32_dpp v152, v152, v152 row_ror:2 row_mask:0xf bank_mask:0xf
	s_nop 1
	v_add_f32_dpp v152, v152, v152 row_ror:1 row_mask:0xf bank_mask:0xf
	s_nop 1
	v_readlane_b32 s22, v152, 0
	v_readlane_b32 s23, v152, 16
	v_readlane_b32 s32, v152, 32
	v_readlane_b32 s99, v152, 48
	v_mov_b32_e32 v152, s22
	v_add_f32_e32 v152, s23, v152
	v_add_f32_e32 v152, s32, v152
	v_add_f32_e32 v152, s99, v152
	v_mov_b32_e32 v153, 0x358637bd
	v_fmamk_f32 v152, v152, 0x3a800000, v153
	v_rsq_f32_e32 v152, v152
	s_nop 1
	v_mul_f32_e32 v54, v54, v152
	v_mul_f32_e32 v55, v55, v152
	v_mul_f32_e32 v56, v56, v152
	v_mul_f32_e32 v57, v57, v152
	v_mul_f32_e32 v58, v58, v152
	v_mul_f32_e32 v59, v59, v152
	v_mul_f32_e32 v60, v60, v152
	v_mul_f32_e32 v61, v61, v152
	v_mul_f32_e32 v62, v62, v152
	v_mul_f32_e32 v63, v63, v152
	v_mul_f32_e32 v64, v64, v152
	v_mul_f32_e32 v65, v65, v152
	v_mul_f32_e32 v66, v66, v152
	v_mul_f32_e32 v67, v67, v152
	v_mul_f32_e32 v68, v68, v152
	v_mul_f32_e32 v69, v69, v152
	v_fma_f32 v54, v54, v0, v16
	v_fma_f32 v55, v55, v1, v17
	v_fma_f32 v56, v56, v2, v18
	v_fma_f32 v57, v57, v3, v19
	v_fma_f32 v58, v58, v4, v20
	v_fma_f32 v59, v59, v5, v21
	v_fma_f32 v60, v60, v6, v22
	v_fma_f32 v61, v61, v7, v23
	v_fma_f32 v62, v62, v8, v24
	v_fma_f32 v63, v63, v9, v25
	v_fma_f32 v64, v64, v10, v26
	v_fma_f32 v65, v65, v11, v27
	v_fma_f32 v66, v66, v12, v28
	v_fma_f32 v67, v67, v13, v29
	v_fma_f32 v68, v68, v14, v30
	v_fma_f32 v69, v69, v15, v31
	v_cvt_pk_f16_f32 v70, v54, v55
	v_cvt_pk_f16_f32 v71, v56, v57
	v_cvt_pk_f16_f32 v72, v58, v59
	v_cvt_pk_f16_f32 v73, v60, v61
	v_cvt_pk_f16_f32 v74, v62, v63
	v_cvt_pk_f16_f32 v75, v64, v65
	v_cvt_pk_f16_f32 v76, v66, v67
	v_cvt_pk_f16_f32 v77, v68, v69
	global_store_dwordx2 v151, v[70:71], s[36:37] offset:0
	global_store_dwordx2 v151, v[72:73], s[36:37] offset:512
	global_store_dwordx2 v151, v[74:75], s[36:37] offset:1024
	global_store_dwordx2 v151, v[76:77], s[36:37] offset:1536
	s_add_u32 s5, s5, 1
	s_sub_u32 s9, s5, 0x800
	s_lshr_b32 s9, s9, 13
	s_cmp_lt_u32 s5, 0x800
	s_cselect_b32 s9, 8, s9
	s_cmp_eq_u32 s9, s8
	s_cbranch_scc1 .Lr1a_nr3
	s_mov_b32 s8, s9
	s_waitcnt vmcnt(0)
	s_add_u32 s10, s9, 0
	s_mul_i32 s10, s10, 0x6000
	s_add_u32 s38, s56, s10
	s_addc_u32 s39, s57, 0
	global_load_dwordx4 v[54:57], v150, s[58:59] offset:0
	global_load_dwordx4 v[58:61], v150, s[58:59] offset:1024
	global_load_dwordx4 v[62:65], v150, s[58:59] offset:2048
	global_load_dwordx4 v[66:69], v150, s[58:59] offset:3072
	s_add_u32 s44, s38, 0x1000
	s_addc_u32 s45, s39, 0
	global_load_dwordx4 v[70:73], v150, s[44:45] offset:0
	global_load_dwordx4 v[74:77], v150, s[44:45] offset:1024
	global_load_dwordx4 v[78:81], v150, s[44:45] offset:2048
	global_load_dwordx4 v[82:85], v150, s[44:45] offset:3072
	global_load_dwordx4 v[16:19], v150, s[38:39] offset:0
	global_load_dwordx4 v[20:23], v150, s[38:39] offset:1024
	global_load_dwordx4 v[24:27], v150, s[38:39] offset:2048
	global_load_dwordx4 v[28:31], v150, s[38:39] offset:3072
	s_waitcnt vmcnt(0)
	v_add_f32_e32 v70, 1.0, v70
	v_add_f32_e32 v71, 1.0, v71
	v_add_f32_e32 v72, 1.0, v72
	v_add_f32_e32 v73, 1.0, v73
	v_add_f32_e32 v74, 1.0, v74
	v_add_f32_e32 v75, 1.0, v75
	v_add_f32_e32 v76, 1.0, v76
	v_add_f32_e32 v77, 1.0, v77
	v_add_f32_e32 v78, 1.0, v78
	v_add_f32_e32 v79, 1.0, v79
	v_add_f32_e32 v80, 1.0, v80
	v_add_f32_e32 v81, 1.0, v81
	v_add_f32_e32 v82, 1.0, v82
	v_add_f32_e32 v83, 1.0, v83
	v_add_f32_e32 v84, 1.0, v84
	v_add_f32_e32 v85, 1.0, v85
	v_mul_f32_e32 v0, v54, v70
	v_mul_f32_e32 v1, v55, v71
	v_mul_f32_e32 v2, v56, v72
	v_mul_f32_e32 v3, v57, v73
	v_mul_f32_e32 v4, v58, v74
	v_mul_f32_e32 v5, v59, v75
	v_mul_f32_e32 v6, v60, v76
	v_mul_f32_e32 v7, v61, v77
	v_mul_f32_e32 v8, v62, v78
	v_mul_f32_e32 v9, v63, v79
	v_mul_f32_e32 v10, v64, v80
	v_mul_f32_e32 v11, v65, v81
	v_mul_f32_e32 v12, v66, v82
	v_mul_f32_e32 v13, v67, v83
	v_mul_f32_e32 v14, v68, v84
	v_mul_f32_e32 v15, v69, v85
; DI void row1_phase(const Params& P, int combine_l, int norm_l, int r_begin) {
;     ...
;       const float* src = r < TC ? P.ctx + (size_t)r * D : P.x + (size_t)(r - TC) * D;
; #pragma unroll
;       for (int i = 0; i < 4; i++) xv[i] = *(const float4*)(src + i * 256 + lane * 4);
;     ...
;     if (norm_l >= 0) {
;       float ss = 0.f;
; #pragma unroll
;       for (int i = 0; i < 4; i++) ss += xv[i].x * xv[i].x + xv[i].y * xv[i].y + xv[i].z * xv[i].z + xv[i].w * xv[i].w;
;       ss = wave_sum(ss);
;       const float rstd = rsqrtf(ss * (1.f / 1024.f) + EPS);
;       const float* g = P.norm1_g + norm_l * 1024;
;       const float* sh = P.mod + (size_t)(norm_l * 9 + n) * 6144; const float* sc = sh + 1024;
; #pragma unroll
;       for (int i = 0; i < 4; i++) {
;         int c = i * 256 + lane * 4;
;         float4 gg = *(const float4*)(g + c), s1 = *(const float4*)(sc + c), s0 = *(const float4*)(sh + c);
;         h4 o;
;         o[0] = (half_t)(xv[i].x * rstd * gg.x * (1.f + s1.x) + s0.x); o[1] = (half_t)(xv[i].y * rstd * gg.y * (1.f + s1.y) + s0.y);
;         o[2] = (half_t)(xv[i].z * rstd * gg.z * (1.f + s1.z) + s0.z); o[3] = (half_t)(xv[i].w * rstd * gg.w * (1.f + s1.w) + s0.w);
;         *(h4*)(P.hx + (size_t)r * D + c) = o;
;       }
.Lr1a_nr3:
	s_waitcnt vmcnt(16)
	v_accvgpr_read_b32 v54, a64
	v_accvgpr_read_b32 v55, a65
	v_accvgpr_read_b32 v56, a66
	v_accvgpr_read_b32 v57, a67
	v_accvgpr_read_b32 v58, a68
	v_accvgpr_read_b32 v59, a69
	v_accvgpr_read_b32 v60, a70
	v_accvgpr_read_b32 v61, a71
	v_accvgpr_read_b32 v62, a72
	v_accvgpr_read_b32 v63, a73
	v_accvgpr_read_b32 v64, a74
	v_accvgpr_read_b32 v65, a75
	v_accvgpr_read_b32 v66, a76
	v_accvgpr_read_b32 v67, a77
	v_accvgpr_read_b32 v68, a78
	v_accvgpr_read_b32 v69, a79
	s_lshl_b32 s10, s5, 12
	s_lshr_b32 s10, s10, 1
	s_add_u32 s36, s54, s10
	s_addc_u32 s37, s55, 0
	s_cmp_lt_u32 s7, 0x800
	s_cselect_b64 s[60:61], s[48:49], s[50:51]
	s_lshl_b32 s10, s7, 12
	s_add_u32 s60, s60, s10
	s_addc_u32 s61, s61, 0
	global_load_dwordx4 a[64:67], v150, s[60:61] offset:0 nt
	global_load_dwordx4 a[68:71], v150, s[60:61] offset:1024 nt
	global_load_dwordx4 a[72:75], v150, s[60:61] offset:2048 nt
	global_load_dwordx4 a[76:79], v150, s[60:61] offset:3072 nt
	s_add_u32 s7, s7, 1
	v_mul_f32_e32 v152, v54, v54
	v_mul_f32_e32 v153, v55, v55
	v_fmac_f32_e32 v152, v56, v56
	v_fmac_f32_e32 v153, v57, v57
	v_fmac_f32_e32 v152, v58, v58
	v_fmac_f32_e32 v153, v59, v59
	v_fmac_f32_e32 v152, v60, v60
	v_fmac_f32_e32 v153, v61, v61
	v_fmac_f32_e32 v152, v62, v62
	v_fmac_f32_e32 v153, v63, v63
	v_fmac_f32_e32 v152, v64, v64
	v_fmac_f32_e32 v153, v65, v65
	v_fmac_f32_e32 v152, v66, v66
	v_fmac_f32_e32 v153, v67, v67
	v_fmac_f32_e32 v152, v68, v68
	v_fmac_f32_e32 v153, v69, v69
	v_add_f32_e32 v152, v152, v153
	s_nop 1
	v_add_f32_dpp v152, v152, v152 row_ror:8 row_mask:0xf bank_mask:0xf
	s_nop 1
	v_add_f32_dpp v152, v152, v152 row_ror:4 row_mask:0xf bank_mask:0xf
	s_nop 1
	v_add_f32_dpp v152, v152, v152 row_ror:2 row_mask:0xf bank_mask:0xf
	s_nop 1
	v_add_f32_dpp v152, v152, v152 row_ror:1 row_mask:0xf bank_mask:0xf
	s_nop 1
	v_readlane_b32 s22, v152, 0
	v_readlane_b32 s23, v152, 16
	v_readlane_b32 s32, v152, 32
	v_readlane_b32 s99, v152, 48
	v_mov_b32_e32 v152, s22
	v_add_f32_e32 v152, s23, v152
	v_add_f32_e32 v152, s32, v152
	v_add_f32_e32 v152, s99, v152
	v_mov_b32_e32 v153, 0x358637bd
	v_fmamk_f32 v152, v152, 0x3a800000, v153
	v_rsq_f32_e32 v152, v152
	s_nop 1
	v_mul_f32_e32 v54, v54, v152
	v_mul_f32_e32 v55, v55, v152
	v_mul_f32_e32 v56, v56, v152
	v_mul_f32_e32 v57, v57, v152
	v_mul_f32_e32 v58, v58, v152
	v_mul_f32_e32 v59, v59, v152
	v_mul_f32_e32 v60, v60, v152
	v_mul_f32_e32 v61, v61, v152
	v_mul_f32_e32 v62, v62, v152
	v_mul_f32_e32 v63, v63, v152
	v_mul_f32_e32 v64, v64, v152
	v_mul_f32_e32 v65, v65, v152
	v_mul_f32_e32 v66, v66, v152
	v_mul_f32_e32 v67, v67, v152
	v_mul_f32_e32 v68, v68, v152
	v_mul_f32_e32 v69, v69, v152
	v_fma_f32 v54, v54, v0, v16
	v_fma_f32 v55, v55, v1, v17
	v_fma_f32 v56, v56, v2, v18
	v_fma_f32 v57, v57, v3, v19
	v_fma_f32 v58, v58, v4, v20
	v_fma_f32 v59, v59, v5, v21
	v_fma_f32 v60, v60, v6, v22
	v_fma_f32 v61, v61, v7, v23
	v_fma_f32 v62, v62, v8, v24
	v_fma_f32 v63, v63, v9, v25
	v_fma_f32 v64, v64, v10, v26
	v_fma_f32 v65, v65, v11, v27
	v_fma_f32 v66, v66, v12, v28
	v_fma_f32 v67, v67, v13, v29
	v_fma_f32 v68, v68, v14, v30
	v_fma_f32 v69, v69, v15, v31
	v_cvt_pk_f16_f32 v70, v54, v55
	v_cvt_pk_f16_f32 v71, v56, v57
	v_cvt_pk_f16_f32 v72, v58, v59
	v_cvt_pk_f16_f32 v73, v60, v61
	v_cvt_pk_f16_f32 v74, v62, v63
	v_cvt_pk_f16_f32 v75, v64, v65
	v_cvt_pk_f16_f32 v76, v66, v67
	v_cvt_pk_f16_f32 v77, v68, v69
	global_store_dwordx2 v151, v[70:71], s[36:37] offset:0
	global_store_dwordx2 v151, v[72:73], s[36:37] offset:512
	global_store_dwordx2 v151, v[74:75], s[36:37] offset:1024
	global_store_dwordx2 v151, v[76:77], s[36:37] offset:1536
	s_add_u32 s5, s5, 1
	s_sub_u32 s9, s5, 0x800
	s_lshr_b32 s9, s9, 13
	s_cmp_lt_u32 s5, 0x800
	s_cselect_b32 s9, 8, s9
	s_cmp_eq_u32 s9, s8
	s_cbranch_scc1 .Lr1a_nr4
	s_mov_b32 s8, s9
	s_waitcnt vmcnt(0)
	s_add_u32 s10, s9, 0
	s_mul_i32 s10, s10, 0x6000
	s_add_u32 s38, s56, s10
	s_addc_u32 s39, s57, 0
	global_load_dwordx4 v[54:57], v150, s[58:59] offset:0
	global_load_dwordx4 v[58:61], v150, s[58:59] offset:1024
	global_load_dwordx4 v[62:65], v150, s[58:59] offset:2048
	global_load_dwordx4 v[66:69], v150, s[58:59] offset:3072
	s_add_u32 s44, s38, 0x1000
	s_addc_u32 s45, s39, 0
	global_load_dwordx4 v[70:73], v150, s[44:45] offset:0
	global_load_dwordx4 v[74:77], v150, s[44:45] offset:1024
	global_load_dwordx4 v[78:81], v150, s[44:45] offset:2048
	global_load_dwordx4 v[82:85], v150, s[44:45] offset:3072
	global_load_dwordx4 v[16:19], v150, s[38:39] offset:0
	global_load_dwordx4 v[20:23], v150, s[38:39] offset:1024
	global_load_dwordx4 v[24:27], v150, s[38:39] offset:2048
	global_load_dwordx4 v[28:31], v150, s[38:39] offset:3072
	s_waitcnt vmcnt(0)
	v_add_f32_e32 v70, 1.0, v70
	v_add_f32_e32 v71, 1.0, v71
	v_add_f32_e32 v72, 1.0, v72
	v_add_f32_e32 v73, 1.0, v73
	v_add_f32_e32 v74, 1.0, v74
	v_add_f32_e32 v75, 1.0, v75
	v_add_f32_e32 v76, 1.0, v76
	v_add_f32_e32 v77, 1.0, v77
	v_add_f32_e32 v78, 1.0, v78
	v_add_f32_e32 v79, 1.0, v79
	v_add_f32_e32 v80, 1.0, v80
	v_add_f32_e32 v81, 1.0, v81
	v_add_f32_e32 v82, 1.0, v82
	v_add_f32_e32 v83, 1.0, v83
	v_add_f32_e32 v84, 1.0, v84
	v_add_f32_e32 v85, 1.0, v85
	v_mul_f32_e32 v0, v54, v70
	v_mul_f32_e32 v1, v55, v71
	v_mul_f32_e32 v2, v56, v72
	v_mul_f32_e32 v3, v57, v73
	v_mul_f32_e32 v4, v58, v74
	v_mul_f32_e32 v5, v59, v75
	v_mul_f32_e32 v6, v60, v76
	v_mul_f32_e32 v7, v61, v77
	v_mul_f32_e32 v8, v62, v78
	v_mul_f32_e32 v9, v63, v79
	v_mul_f32_e32 v10, v64, v80
	v_mul_f32_e32 v11, v65, v81
	v_mul_f32_e32 v12, v66, v82
	v_mul_f32_e32 v13, v67, v83
	v_mul_f32_e32 v14, v68, v84
	v_mul_f32_e32 v15, v69, v85
; DI void row1_phase(const Params& P, int combine_l, int norm_l, int r_begin) {
;     ...
;     if (norm_l >= 0) {
;       float ss = 0.f;
; #pragma unroll
;       for (int i = 0; i < 4; i++) ss += xv[i].x * xv[i].x + xv[i].y * xv[i].y + xv[i].z * xv[i].z + xv[i].w * xv[i].w;
;       ss = wave_sum(ss);
;       const float rstd = rsqrtf(ss * (1.f / 1024.f) + EPS);
;       const float* g = P.norm1_g + norm_l * 1024;
;       const float* sh = P.mod + (size_t)(norm_l * 9 + n) * 6144; const float* sc = sh + 1024;
; #pragma unroll
;       for (int i = 0; i < 4; i++) {
;         int c = i * 256 + lane * 4;
;         float4 gg = *(const float4*)(g + c), s1 = *(const float4*)(sc + c), s0 = *(const float4*)(sh + c);
;         h4 o;
;         o[0] = (half_t)(xv[i].x * rstd * gg.x * (1.f + s1.x) + s0.x); o[1] = (half_t)(xv[i].y * rstd * gg.y * (1.f + s1.y) + s0.y);
;         o[2] = (half_t)(xv[i].z * rstd * gg.z * (1.f + s1.z) + s0.z); o[3] = (half_t)(xv[i].w * rstd * gg.w * (1.f + s1.w) + s0.w);
;         *(h4*)(P.hx + (size_t)r * D + c) = o;
;       }
;     ...
; #pragma unroll 1
;   for (int r = r_lo; r < r_hi; r += 4) {
.Lr1a_nr4:
	s_waitcnt vmcnt(16)
	v_accvgpr_read_b32 v54, a96
	v_accvgpr_read_b32 v55, a97
	v_accvgpr_read_b32 v56, a98
	v_accvgpr_read_b32 v57, a99
	v_accvgpr_read_b32 v58, a100
	v_accvgpr_read_b32 v59, a101
	v_accvgpr_read_b32 v60, a102
	v_accvgpr_read_b32 v61, a103
	v_accvgpr_read_b32 v62, a104
	v_accvgpr_read_b32 v63, a105
	v_accvgpr_read_b32 v64, a106
	v_accvgpr_read_b32 v65, a107
	v_accvgpr_read_b32 v66, a108
	v_accvgpr_read_b32 v67, a109
	v_accvgpr_read_b32 v68, a110
	v_accvgpr_read_b32 v69, a111
	s_lshl_b32 s10, s5, 12
	s_lshr_b32 s10, s10, 1
	s_add_u32 s36, s54, s10
	s_addc_u32 s37, s55, 0
	s_cmp_lt_u32 s7, 0x800
	s_cselect_b64 s[60:61], s[48:49], s[50:51]
	s_lshl_b32 s10, s7, 12
	s_add_u32 s60, s60, s10
	s_addc_u32 s61, s61, 0
	global_load_dwordx4 a[96:99], v150, s[60:61] offset:0 nt
	global_load_dwordx4 a[100:103], v150, s[60:61] offset:1024 nt
	global_load_dwordx4 a[104:107], v150, s[60:61] offset:2048 nt
	global_load_dwordx4 a[108:111], v150, s[60:61] offset:3072 nt
	s_add_u32 s7, s7, 1
	v_mul_f32_e32 v152, v54, v54
	v_mul_f32_e32 v153, v55, v55
	v_fmac_f32_e32 v152, v56, v56
	v_fmac_f32_e32 v153, v57, v57
	v_fmac_f32_e32 v152, v58, v58
	v_fmac_f32_e32 v153, v59, v59
	v_fmac_f32_e32 v152, v60, v60
	v_fmac_f32_e32 v153, v61, v61
	v_fmac_f32_e32 v152, v62, v62
	v_fmac_f32_e32 v153, v63, v63
	v_fmac_f32_e32 v152, v64, v64
	v_fmac_f32_e32 v153, v65, v65
	v_fmac_f32_e32 v152, v66, v66
	v_fmac_f32_e32 v153, v67, v67
	v_fmac_f32_e32 v152, v68, v68
	v_fmac_f32_e32 v153, v69, v69
	v_add_f32_e32 v152, v152, v153
	s_nop 1
	v_add_f32_dpp v152, v152, v152 row_ror:8 row_mask:0xf bank_mask:0xf
	s_nop 1
	v_add_f32_dpp v152, v152, v152 row_ror:4 row_mask:0xf bank_mask:0xf
	s_nop 1
	v_add_f32_dpp v152, v152, v152 row_ror:2 row_mask:0xf bank_mask:0xf
	s_nop 1
	v_add_f32_dpp v152, v152, v152 row_ror:1 row_mask:0xf bank_mask:0xf
	s_nop 1
	v_readlane_b32 s22, v152, 0
	v_readlane_b32 s23, v152, 16
	v_readlane_b32 s32, v152, 32
	v_readlane_b32 s99, v152, 48
	v_mov_b32_e32 v152, s22
	v_add_f32_e32 v152, s23, v152
	v_add_f32_e32 v152, s32, v152
	v_add_f32_e32 v152, s99, v152
	v_mov_b32_e32 v153, 0x358637bd
	v_fmamk_f32 v152, v152, 0x3a800000, v153
	v_rsq_f32_e32 v152, v152
	s_nop 1
	v_mul_f32_e32 v54, v54, v152
	v_mul_f32_e32 v55, v55, v152
	v_mul_f32_e32 v56, v56, v152
	v_mul_f32_e32 v57, v57, v152
	v_mul_f32_e32 v58, v58, v152
	v_mul_f32_e32 v59, v59, v152
	v_mul_f32_e32 v60, v60, v152
	v_mul_f32_e32 v61, v61, v152
	v_mul_f32_e32 v62, v62, v152
	v_mul_f32_e32 v63, v63, v152
	v_mul_f32_e32 v64, v64, v152
	v_mul_f32_e32 v65, v65, v152
	v_mul_f32_e32 v66, v66, v152
	v_mul_f32_e32 v67, v67, v152
	v_mul_f32_e32 v68, v68, v152
	v_mul_f32_e32 v69, v69, v152
	v_fma_f32 v54, v54, v0, v16
	v_fma_f32 v55, v55, v1, v17
	v_fma_f32 v56, v56, v2, v18
	v_fma_f32 v57, v57, v3, v19
	v_fma_f32 v58, v58, v4, v20
	v_fma_f32 v59, v59, v5, v21
	v_fma_f32 v60, v60, v6, v22
	v_fma_f32 v61, v61, v7, v23
	v_fma_f32 v62, v62, v8, v24
	v_fma_f32 v63, v63, v9, v25
	v_fma_f32 v64, v64, v10, v26
	v_fma_f32 v65, v65, v11, v27
	v_fma_f32 v66, v66, v12, v28
	v_fma_f32 v67, v67, v13, v29
	v_fma_f32 v68, v68, v14, v30
	v_fma_f32 v69, v69, v15, v31
	v_cvt_pk_f16_f32 v70, v54, v55
	v_cvt_pk_f16_f32 v71, v56, v57
	v_cvt_pk_f16_f32 v72, v58, v59
	v_cvt_pk_f16_f32 v73, v60, v61
	v_cvt_pk_f16_f32 v74, v62, v63
	v_cvt_pk_f16_f32 v75, v64, v65
	v_cvt_pk_f16_f32 v76, v66, v67
	v_cvt_pk_f16_f32 v77, v68, v69
	global_store_dwordx2 v151, v[70:71], s[36:37] offset:0
	global_store_dwordx2 v151, v[72:73], s[36:37] offset:512
	global_store_dwordx2 v151, v[74:75], s[36:37] offset:1024
	global_store_dwordx2 v151, v[76:77], s[36:37] offset:1536
	s_add_u32 s5, s5, 1
	s_sub_u32 s98, s98, 1
	s_cmp_lg_u32 s98, 0
	s_cbranch_scc1 .Lr1a_loop
	s_sub_u32 s9, s5, 0x800
	s_lshr_b32 s9, s9, 13
	s_cmp_lt_u32 s5, 0x800
	s_cselect_b32 s9, 8, s9
	s_cmp_eq_u32 s9, s8
	s_cbranch_scc1 .Lr1a_nr5
	s_mov_b32 s8, s9
	s_waitcnt vmcnt(0)
	s_add_u32 s10, s9, 0
	s_mul_i32 s10, s10, 0x6000
	s_add_u32 s38, s56, s10
	s_addc_u32 s39, s57, 0
	global_load_dwordx4 v[54:57], v150, s[58:59] offset:0
	global_load_dwordx4 v[58:61], v150, s[58:59] offset:1024
	global_load_dwordx4 v[62:65], v150, s[58:59] offset:2048
	global_load_dwordx4 v[66:69], v150, s[58:59] offset:3072
	s_add_u32 s44, s38, 0x1000
	s_addc_u32 s45, s39, 0
	global_load_dwordx4 v[70:73], v150, s[44:45] offset:0
	global_load_dwordx4 v[74:77], v150, s[44:45] offset:1024
	global_load_dwordx4 v[78:81], v150, s[44:45] offset:2048
	global_load_dwordx4 v[82:85], v150, s[44:45] offset:3072
	global_load_dwordx4 v[16:19], v150, s[38:39] offset:0
	global_load_dwordx4 v[20:23], v150, s[38:39] offset:1024
	global_load_dwordx4 v[24:27], v150, s[38:39] offset:2048
	global_load_dwordx4 v[28:31], v150, s[38:39] offset:3072
	s_waitcnt vmcnt(0)
	v_add_f32_e32 v70, 1.0, v70
	v_add_f32_e32 v71, 1.0, v71
	v_add_f32_e32 v72, 1.0, v72
	v_add_f32_e32 v73, 1.0, v73
	v_add_f32_e32 v74, 1.0, v74
	v_add_f32_e32 v75, 1.0, v75
	v_add_f32_e32 v76, 1.0, v76
	v_add_f32_e32 v77, 1.0, v77
	v_add_f32_e32 v78, 1.0, v78
	v_add_f32_e32 v79, 1.0, v79
	v_add_f32_e32 v80, 1.0, v80
	v_add_f32_e32 v81, 1.0, v81
	v_add_f32_e32 v82, 1.0, v82
	v_add_f32_e32 v83, 1.0, v83
	v_add_f32_e32 v84, 1.0, v84
	v_add_f32_e32 v85, 1.0, v85
	v_mul_f32_e32 v0, v54, v70
	v_mul_f32_e32 v1, v55, v71
	v_mul_f32_e32 v2, v56, v72
	v_mul_f32_e32 v3, v57, v73
	v_mul_f32_e32 v4, v58, v74
	v_mul_f32_e32 v5, v59, v75
	v_mul_f32_e32 v6, v60, v76
	v_mul_f32_e32 v7, v61, v77
	v_mul_f32_e32 v8, v62, v78
	v_mul_f32_e32 v9, v63, v79
	v_mul_f32_e32 v10, v64, v80
	v_mul_f32_e32 v11, v65, v81
	v_mul_f32_e32 v12, v66, v82
	v_mul_f32_e32 v13, v67, v83
	v_mul_f32_e32 v14, v68, v84
	v_mul_f32_e32 v15, v69, v85

; DI void row1_phase(const Params& P, int combine_l, int norm_l, int r_begin) {
;     ...
;     if (norm_l >= 0) {
;       float ss = 0.f;
; #pragma unroll
;       for (int i = 0; i < 4; i++) ss += xv[i].x * xv[i].x + xv[i].y * xv[i].y + xv[i].z * xv[i].z + xv[i].w * xv[i].w;
;       ss = wave_sum(ss);
;       const float rstd = rsqrtf(ss * (1.f / 1024.f) + EPS);
;       const float* g = P.norm1_g + norm_l * 1024;
;       const float* sh = P.mod + (size_t)(norm_l * 9 + n) * 6144; const float* sc = sh + 1024;
; #pragma unroll
;       for (int i = 0; i < 4; i++) {
;         int c = i * 256 + lane * 4;
;         float4 gg = *(const float4*)(g + c), s1 = *(const float4*)(sc + c), s0 = *(const float4*)(sh + c);
;         h4 o;
;         o[0] = (half_t)(xv[i].x * rstd * gg.x * (1.f + s1.x) + s0.x); o[1] = (half_t)(xv[i].y * rstd * gg.y * (1.f + s1.y) + s0.y);
;         o[2] = (half_t)(xv[i].z * rstd * gg.z * (1.f + s1.z) + s0.z); o[3] = (half_t)(xv[i].w * rstd * gg.w * (1.f + s1.w) + s0.w);
;         *(h4*)(P.hx + (size_t)r * D + c) = o;
;       }
.Lr1a_nr7:
	s_waitcnt vmcnt(16)
	v_accvgpr_read_b32 v54, a64
	v_accvgpr_read_b32 v55, a65
	v_accvgpr_read_b32 v56, a66
	v_accvgpr_read_b32 v57, a67
	v_accvgpr_read_b32 v58, a68
	v_accvgpr_read_b32 v59, a69
	v_accvgpr_read_b32 v60, a70
	v_accvgpr_read_b32 v61, a71
	v_accvgpr_read_b32 v62, a72
	v_accvgpr_read_b32 v63, a73
	v_accvgpr_read_b32 v64, a74
	v_accvgpr_read_b32 v65, a75
	v_accvgpr_read_b32 v66, a76
	v_accvgpr_read_b32 v67, a77
	v_accvgpr_read_b32 v68, a78
	v_accvgpr_read_b32 v69, a79
	s_lshl_b32 s10, s5, 12
	s_lshr_b32 s10, s10, 1
	s_add_u32 s36, s54, s10
	s_addc_u32 s37, s55, 0
	v_mul_f32_e32 v152, v54, v54
	v_mul_f32_e32 v153, v55, v55
	v_fmac_f32_e32 v152, v56, v56
	v_fmac_f32_e32 v153, v57, v57
	v_fmac_f32_e32 v152, v58, v58
	v_fmac_f32_e32 v153, v59, v59
	v_fmac_f32_e32 v152, v60, v60
	v_fmac_f32_e32 v153, v61, v61
	v_fmac_f32_e32 v152, v62, v62
	v_fmac_f32_e32 v153, v63, v63
	v_fmac_f32_e32 v152, v64, v64
	v_fmac_f32_e32 v153, v65, v65
	v_fmac_f32_e32 v152, v66, v66
	v_fmac_f32_e32 v153, v67, v67
	v_fmac_f32_e32 v152, v68, v68
	v_fmac_f32_e32 v153, v69, v69
	v_add_f32_e32 v152, v152, v153
	s_nop 1
	v_add_f32_dpp v152, v152, v152 row_ror:8 row_mask:0xf bank_mask:0xf
	s_nop 1
	v_add_f32_dpp v152, v152, v152 row_ror:4 row_mask:0xf bank_mask:0xf
	s_nop 1
	v_add_f32_dpp v152, v152, v152 row_ror:2 row_mask:0xf bank_mask:0xf
	s_nop 1
	v_add_f32_dpp v152, v152, v152 row_ror:1 row_mask:0xf bank_mask:0xf
	s_nop 1
	v_readlane_b32 s22, v152, 0
	v_readlane_b32 s23, v152, 16
	v_readlane_b32 s32, v152, 32
	v_readlane_b32 s99, v152, 48
	v_mov_b32_e32 v152, s22
	v_add_f32_e32 v152, s23, v152
	v_add_f32_e32 v152, s32, v152
	v_add_f32_e32 v152, s99, v152
	v_mov_b32_e32 v153, 0x358637bd
	v_fmamk_f32 v152, v152, 0x3a800000, v153
	v_rsq_f32_e32 v152, v152
	s_nop 1
	v_mul_f32_e32 v54, v54, v152
	v_mul_f32_e32 v55, v55, v152
	v_mul_f32_e32 v56, v56, v152
	v_mul_f32_e32 v57, v57, v152
	v_mul_f32_e32 v58, v58, v152
	v_mul_f32_e32 v59, v59, v152
	v_mul_f32_e32 v60, v60, v152
	v_mul_f32_e32 v61, v61, v152
	v_mul_f32_e32 v62, v62, v152
	v_mul_f32_e32 v63, v63, v152
	v_mul_f32_e32 v64, v64, v152
	v_mul_f32_e32 v65, v65, v152
	v_mul_f32_e32 v66, v66, v152
	v_mul_f32_e32 v67, v67, v152
	v_mul_f32_e32 v68, v68, v152
	v_mul_f32_e32 v69, v69, v152
	v_fma_f32 v54, v54, v0, v16
	v_fma_f32 v55, v55, v1, v17
	v_fma_f32 v56, v56, v2, v18
	v_fma_f32 v57, v57, v3, v19
	v_fma_f32 v58, v58, v4, v20
	v_fma_f32 v59, v59, v5, v21
	v_fma_f32 v60, v60, v6, v22
	v_fma_f32 v61, v61, v7, v23
	v_fma_f32 v62, v62, v8, v24
	v_fma_f32 v63, v63, v9, v25
	v_fma_f32 v64, v64, v10, v26
	v_fma_f32 v65, v65, v11, v27
	v_fma_f32 v66, v66, v12, v28
	v_fma_f32 v67, v67, v13, v29
	v_fma_f32 v68, v68, v14, v30
	v_fma_f32 v69, v69, v15, v31
	v_cvt_pk_f16_f32 v70, v54, v55
	v_cvt_pk_f16_f32 v71, v56, v57
	v_cvt_pk_f16_f32 v72, v58, v59
	v_cvt_pk_f16_f32 v73, v60, v61
	v_cvt_pk_f16_f32 v74, v62, v63
	v_cvt_pk_f16_f32 v75, v64, v65
	v_cvt_pk_f16_f32 v76, v66, v67
	v_cvt_pk_f16_f32 v77, v68, v69
	global_store_dwordx2 v151, v[70:71], s[36:37] offset:0
	global_store_dwordx2 v151, v[72:73], s[36:37] offset:512
	global_store_dwordx2 v151, v[74:75], s[36:37] offset:1024
	global_store_dwordx2 v151, v[76:77], s[36:37] offset:1536
	s_add_u32 s5, s5, 1
	s_sub_u32 s9, s5, 0x800
	s_lshr_b32 s9, s9, 13
	s_cmp_lt_u32 s5, 0x800
	s_cselect_b32 s9, 8, s9
	s_cmp_eq_u32 s9, s8
	s_cbranch_scc1 .Lr1a_nr8
	s_mov_b32 s8, s9
	s_waitcnt vmcnt(0)
	s_add_u32 s10, s9, 0
	s_mul_i32 s10, s10, 0x6000
	s_add_u32 s38, s56, s10
	s_addc_u32 s39, s57, 0
	global_load_dwordx4 v[54:57], v150, s[58:59] offset:0
	global_load_dwordx4 v[58:61], v150, s[58:59] offset:1024
	global_load_dwordx4 v[62:65], v150, s[58:59] offset:2048
	global_load_dwordx4 v[66:69], v150, s[58:59] offset:3072
	s_add_u32 s44, s38, 0x1000
	s_addc_u32 s45, s39, 0
	global_load_dwordx4 v[70:73], v150, s[44:45] offset:0
	global_load_dwordx4 v[74:77], v150, s[44:45] offset:1024
	global_load_dwordx4 v[78:81], v150, s[44:45] offset:2048
	global_load_dwordx4 v[82:85], v150, s[44:45] offset:3072
	global_load_dwordx4 v[16:19], v150, s[38:39] offset:0
	global_load_dwordx4 v[20:23], v150, s[38:39] offset:1024
	global_load_dwordx4 v[24:27], v150, s[38:39] offset:2048
	global_load_dwordx4 v[28:31], v150, s[38:39] offset:3072
	s_waitcnt vmcnt(0)
	v_add_f32_e32 v70, 1.0, v70
	v_add_f32_e32 v71, 1.0, v71
	v_add_f32_e32 v72, 1.0, v72
	v_add_f32_e32 v73, 1.0, v73
	v_add_f32_e32 v74, 1.0, v74
	v_add_f32_e32 v75, 1.0, v75
	v_add_f32_e32 v76, 1.0, v76
	v_add_f32_e32 v77, 1.0, v77
	v_add_f32_e32 v78, 1.0, v78
	v_add_f32_e32 v79, 1.0, v79
	v_add_f32_e32 v80, 1.0, v80
	v_add_f32_e32 v81, 1.0, v81
	v_add_f32_e32 v82, 1.0, v82
	v_add_f32_e32 v83, 1.0, v83
	v_add_f32_e32 v84, 1.0, v84
	v_add_f32_e32 v85, 1.0, v85
	v_mul_f32_e32 v0, v54, v70
	v_mul_f32_e32 v1, v55, v71
	v_mul_f32_e32 v2, v56, v72
	v_mul_f32_e32 v3, v57, v73
	v_mul_f32_e32 v4, v58, v74
	v_mul_f32_e32 v5, v59, v75
	v_mul_f32_e32 v6, v60, v76
	v_mul_f32_e32 v7, v61, v77
	v_mul_f32_e32 v8, v62, v78
	v_mul_f32_e32 v9, v63, v79
	v_mul_f32_e32 v10, v64, v80
	v_mul_f32_e32 v11, v65, v81
	v_mul_f32_e32 v12, v66, v82
	v_mul_f32_e32 v13, v67, v83
	v_mul_f32_e32 v14, v68, v84
	v_mul_f32_e32 v15, v69, v85
; DI void row1_phase(const Params& P, int combine_l, int norm_l, int r_begin) {
;     ...
;     if (norm_l >= 0) {
;       float ss = 0.f;
; #pragma unroll
;       for (int i = 0; i < 4; i++) ss += xv[i].x * xv[i].x + xv[i].y * xv[i].y + xv[i].z * xv[i].z + xv[i].w * xv[i].w;
;       ss = wave_sum(ss);
;       const float rstd = rsqrtf(ss * (1.f / 1024.f) + EPS);
;       const float* g = P.norm1_g + norm_l * 1024;
;       const float* sh = P.mod + (size_t)(norm_l * 9 + n) * 6144; const float* sc = sh + 1024;
; #pragma unroll
;       for (int i = 0; i < 4; i++) {
;         int c = i * 256 + lane * 4;
;         float4 gg = *(const float4*)(g + c), s1 = *(const float4*)(sc + c), s0 = *(const float4*)(sh + c);
;         h4 o;
;         o[0] = (half_t)(xv[i].x * rstd * gg.x * (1.f + s1.x) + s0.x); o[1] = (half_t)(xv[i].y * rstd * gg.y * (1.f + s1.y) + s0.y);
;         o[2] = (half_t)(xv[i].z * rstd * gg.z * (1.f + s1.z) + s0.z); o[3] = (half_t)(xv[i].w * rstd * gg.w * (1.f + s1.w) + s0.w);
;         *(h4*)(P.hx + (size_t)r * D + c) = o;
;       }
.Lr1a_nr8:
	s_waitcnt vmcnt(12)
	v_accvgpr_read_b32 v54, a96
	v_accvgpr_read_b32 v55, a97
	v_accvgpr_read_b32 v56, a98
	v_accvgpr_read_b32 v57, a99
	v_accvgpr_read_b32 v58, a100
	v_accvgpr_read_b32 v59, a101
	v_accvgpr_read_b32 v60, a102
	v_accvgpr_read_b32 v61, a103
	v_accvgpr_read_b32 v62, a104
	v_accvgpr_read_b32 v63, a105
	v_accvgpr_read_b32 v64, a106
	v_accvgpr_read_b32 v65, a107
	v_accvgpr_read_b32 v66, a108
	v_accvgpr_read_b32 v67, a109
	v_accvgpr_read_b32 v68, a110
	v_accvgpr_read_b32 v69, a111
	s_lshl_b32 s10, s5, 12
	s_lshr_b32 s10, s10, 1
	s_add_u32 s36, s54, s10
	s_addc_u32 s37, s55, 0
	v_mul_f32_e32 v152, v54, v54
	v_mul_f32_e32 v153, v55, v55
	v_fmac_f32_e32 v152, v56, v56
	v_fmac_f32_e32 v153, v57, v57
	v_fmac_f32_e32 v152, v58, v58
	v_fmac_f32_e32 v153, v59, v59
	v_fmac_f32_e32 v152, v60, v60
	v_fmac_f32_e32 v153, v61, v61
	v_fmac_f32_e32 v152, v62, v62
	v_fmac_f32_e32 v153, v63, v63
	v_fmac_f32_e32 v152, v64, v64
	v_fmac_f32_e32 v153, v65, v65
	v_fmac_f32_e32 v152, v66, v66
	v_fmac_f32_e32 v153, v67, v67
	v_fmac_f32_e32 v152, v68, v68
	v_fmac_f32_e32 v153, v69, v69
	v_add_f32_e32 v152, v152, v153
	s_nop 1
	v_add_f32_dpp v152, v152, v152 row_ror:8 row_mask:0xf bank_mask:0xf
	s_nop 1
	v_add_f32_dpp v152, v152, v152 row_ror:4 row_mask:0xf bank_mask:0xf
	s_nop 1
	v_add_f32_dpp v152, v152, v152 row_ror:2 row_mask:0xf bank_mask:0xf
	s_nop 1
	v_add_f32_dpp v152, v152, v152 row_ror:1 row_mask:0xf bank_mask:0xf
	s_nop 1
	v_readlane_b32 s22, v152, 0
	v_readlane_b32 s23, v152, 16
	v_readlane_b32 s32, v152, 32
	v_readlane_b32 s99, v152, 48
	v_mov_b32_e32 v152, s22
	v_add_f32_e32 v152, s23, v152
	v_add_f32_e32 v152, s32, v152
	v_add_f32_e32 v152, s99, v152
	v_mov_b32_e32 v153, 0x358637bd
	v_fmamk_f32 v152, v152, 0x3a800000, v153
	v_rsq_f32_e32 v152, v152
	s_nop 1
	v_mul_f32_e32 v54, v54, v152
	v_mul_f32_e32 v55, v55, v152
	v_mul_f32_e32 v56, v56, v152
	v_mul_f32_e32 v57, v57, v152
	v_mul_f32_e32 v58, v58, v152
	v_mul_f32_e32 v59, v59, v152
	v_mul_f32_e32 v60, v60, v152
	v_mul_f32_e32 v61, v61, v152
	v_mul_f32_e32 v62, v62, v152
	v_mul_f32_e32 v63, v63, v152
	v_mul_f32_e32 v64, v64, v152
	v_mul_f32_e32 v65, v65, v152
	v_mul_f32_e32 v66, v66, v152
	v_mul_f32_e32 v67, v67, v152
	v_mul_f32_e32 v68, v68, v152
	v_mul_f32_e32 v69, v69, v152
	v_fma_f32 v54, v54, v0, v16
	v_fma_f32 v55, v55, v1, v17
	v_fma_f32 v56, v56, v2, v18
	v_fma_f32 v57, v57, v3, v19
	v_fma_f32 v58, v58, v4, v20
	v_fma_f32 v59, v59, v5, v21
	v_fma_f32 v60, v60, v6, v22
	v_fma_f32 v61, v61, v7, v23
	v_fma_f32 v62, v62, v8, v24
	v_fma_f32 v63, v63, v9, v25
	v_fma_f32 v64, v64, v10, v26
	v_fma_f32 v65, v65, v11, v27
	v_fma_f32 v66, v66, v12, v28
	v_fma_f32 v67, v67, v13, v29
	v_fma_f32 v68, v68, v14, v30
	v_fma_f32 v69, v69, v15, v31
	v_cvt_pk_f16_f32 v70, v54, v55
	v_cvt_pk_f16_f32 v71, v56, v57
	v_cvt_pk_f16_f32 v72, v58, v59
	v_cvt_pk_f16_f32 v73, v60, v61
	v_cvt_pk_f16_f32 v74, v62, v63
	v_cvt_pk_f16_f32 v75, v64, v65
	v_cvt_pk_f16_f32 v76, v66, v67
	v_cvt_pk_f16_f32 v77, v68, v69
	global_store_dwordx2 v151, v[70:71], s[36:37] offset:0
	global_store_dwordx2 v151, v[72:73], s[36:37] offset:512
	global_store_dwordx2 v151, v[74:75], s[36:37] offset:1024
	global_store_dwordx2 v151, v[76:77], s[36:37] offset:1536
	s_add_u32 s5, s5, 1
	s_sub_u32 s9, s5, 0x800
	s_lshr_b32 s9, s9, 13
	s_cmp_lt_u32 s5, 0x800
	s_cselect_b32 s9, 8, s9
	s_cmp_eq_u32 s9, s8
	s_cbranch_scc1 .Lr1a_nr9
	s_mov_b32 s8, s9
	s_waitcnt vmcnt(0)
	s_add_u32 s10, s9, 0
	s_mul_i32 s10, s10, 0x6000
	s_add_u32 s38, s56, s10
	s_addc_u32 s39, s57, 0
	global_load_dwordx4 v[54:57], v150, s[58:59] offset:0
	global_load_dwordx4 v[58:61], v150, s[58:59] offset:1024
	global_load_dwordx4 v[62:65], v150, s[58:59] offset:2048
	global_load_dwordx4 v[66:69], v150, s[58:59] offset:3072
	s_add_u32 s44, s38, 0x1000
	s_addc_u32 s45, s39, 0
	global_load_dwordx4 v[70:73], v150, s[44:45] offset:0
	global_load_dwordx4 v[74:77], v150, s[44:45] offset:1024
	global_load_dwordx4 v[78:81], v150, s[44:45] offset:2048
	global_load_dwordx4 v[82:85], v150, s[44:45] offset:3072
	global_load_dwordx4 v[16:19], v150, s[38:39] offset:0
	global_load_dwordx4 v[20:23], v150, s[38:39] offset:1024
	global_load_dwordx4 v[24:27], v150, s[38:39] offset:2048
	global_load_dwordx4 v[28:31], v150, s[38:39] offset:3072
	s_waitcnt vmcnt(0)
	v_add_f32_e32 v70, 1.0, v70
	v_add_f32_e32 v71, 1.0, v71
	v_add_f32_e32 v72, 1.0, v72
	v_add_f32_e32 v73, 1.0, v73
	v_add_f32_e32 v74, 1.0, v74
	v_add_f32_e32 v75, 1.0, v75
	v_add_f32_e32 v76, 1.0, v76
	v_add_f32_e32 v77, 1.0, v77
	v_add_f32_e32 v78, 1.0, v78
	v_add_f32_e32 v79, 1.0, v79
	v_add_f32_e32 v80, 1.0, v80
	v_add_f32_e32 v81, 1.0, v81
	v_add_f32_e32 v82, 1.0, v82
	v_add_f32_e32 v83, 1.0, v83
	v_add_f32_e32 v84, 1.0, v84
	v_add_f32_e32 v85, 1.0, v85
	v_mul_f32_e32 v0, v54, v70
	v_mul_f32_e32 v1, v55, v71
	v_mul_f32_e32 v2, v56, v72
	v_mul_f32_e32 v3, v57, v73
	v_mul_f32_e32 v4, v58, v74
	v_mul_f32_e32 v5, v59, v75
	v_mul_f32_e32 v6, v60, v76
	v_mul_f32_e32 v7, v61, v77
	v_mul_f32_e32 v8, v62, v78
	v_mul_f32_e32 v9, v63, v79
	v_mul_f32_e32 v10, v64, v80
	v_mul_f32_e32 v11, v65, v81
	v_mul_f32_e32 v12, v66, v82
	v_mul_f32_e32 v13, v67, v83
	v_mul_f32_e32 v14, v68, v84
	v_mul_f32_e32 v15, v69, v85
; DI void row1_phase(const Params& P, int combine_l, int norm_l, int r_begin) {
;     ...
;     if (norm_l >= 0) {
;       float ss = 0.f;
; #pragma unroll
;       for (int i = 0; i < 4; i++) ss += xv[i].x * xv[i].x + xv[i].y * xv[i].y + xv[i].z * xv[i].z + xv[i].w * xv[i].w;
;       ss = wave_sum(ss);
;       const float rstd = rsqrtf(ss * (1.f / 1024.f) + EPS);
;       const float* g = P.norm1_g + norm_l * 1024;
;       const float* sh = P.mod + (size_t)(norm_l * 9 + n) * 6144; const float* sc = sh + 1024;
; #pragma unroll
;       for (int i = 0; i < 4; i++) {
;         int c = i * 256 + lane * 4;
;         float4 gg = *(const float4*)(g + c), s1 = *(const float4*)(sc + c), s0 = *(const float4*)(sh + c);
;         h4 o;
;         o[0] = (half_t)(xv[i].x * rstd * gg.x * (1.f + s1.x) + s0.x); o[1] = (half_t)(xv[i].y * rstd * gg.y * (1.f + s1.y) + s0.y);
;         o[2] = (half_t)(xv[i].z * rstd * gg.z * (1.f + s1.z) + s0.z); o[3] = (half_t)(xv[i].w * rstd * gg.w * (1.f + s1.w) + s0.w);
;         *(h4*)(P.hx + (size_t)r * D + c) = o;
;       }
.Lr1a_nr9:
	s_waitcnt vmcnt(8)
	v_accvgpr_read_b32 v54, a0
	v_accvgpr_read_b32 v55, a1
	v_accvgpr_read_b32 v56, a2
	v_accvgpr_read_b32 v57, a3
	v_accvgpr_read_b32 v58, a4
	v_accvgpr_read_b32 v59, a5
	v_accvgpr_read_b32 v60, a6
	v_accvgpr_read_b32 v61, a7
	v_accvgpr_read_b32 v62, a8
	v_accvgpr_read_b32 v63, a9
	v_accvgpr_read_b32 v64, a10
	v_accvgpr_read_b32 v65, a11
	v_accvgpr_read_b32 v66, a12
	v_accvgpr_read_b32 v67, a13
	v_accvgpr_read_b32 v68, a14
	v_accvgpr_read_b32 v69, a15
	s_lshl_b32 s10, s5, 12
	s_lshr_b32 s10, s10, 1
	s_add_u32 s36, s54, s10
	s_addc_u32 s37, s55, 0
	v_mul_f32_e32 v152, v54, v54
	v_mul_f32_e32 v153, v55, v55
	v_fmac_f32_e32 v152, v56, v56
	v_fmac_f32_e32 v153, v57, v57
	v_fmac_f32_e32 v152, v58, v58
	v_fmac_f32_e32 v153, v59, v59
	v_fmac_f32_e32 v152, v60, v60
	v_fmac_f32_e32 v153, v61, v61
	v_fmac_f32_e32 v152, v62, v62
	v_fmac_f32_e32 v153, v63, v63
	v_fmac_f32_e32 v152, v64, v64
	v_fmac_f32_e32 v153, v65, v65
	v_fmac_f32_e32 v152, v66, v66
	v_fmac_f32_e32 v153, v67, v67
	v_fmac_f32_e32 v152, v68, v68
	v_fmac_f32_e32 v153, v69, v69
	v_add_f32_e32 v152, v152, v153
	s_nop 1
	v_add_f32_dpp v152, v152, v152 row_ror:8 row_mask:0xf bank_mask:0xf
	s_nop 1
	v_add_f32_dpp v152, v152, v152 row_ror:4 row_mask:0xf bank_mask:0xf
	s_nop 1
	v_add_f32_dpp v152, v152, v152 row_ror:2 row_mask:0xf bank_mask:0xf
	s_nop 1
	v_add_f32_dpp v152, v152, v152 row_ror:1 row_mask:0xf bank_mask:0xf
	s_nop 1
	v_readlane_b32 s22, v152, 0
	v_readlane_b32 s23, v152, 16
	v_readlane_b32 s32, v152, 32
	v_readlane_b32 s99, v152, 48
	v_mov_b32_e32 v152, s22
	v_add_f32_e32 v152, s23, v152
	v_add_f32_e32 v152, s32, v152
	v_add_f32_e32 v152, s99, v152
	v_mov_b32_e32 v153, 0x358637bd
	v_fmamk_f32 v152, v152, 0x3a800000, v153
	v_rsq_f32_e32 v152, v152
	s_nop 1
	v_mul_f32_e32 v54, v54, v152
	v_mul_f32_e32 v55, v55, v152
	v_mul_f32_e32 v56, v56, v152
	v_mul_f32_e32 v57, v57, v152
	v_mul_f32_e32 v58, v58, v152
	v_mul_f32_e32 v59, v59, v152
	v_mul_f32_e32 v60, v60, v152
	v_mul_f32_e32 v61, v61, v152
	v_mul_f32_e32 v62, v62, v152
	v_mul_f32_e32 v63, v63, v152
	v_mul_f32_e32 v64, v64, v152
	v_mul_f32_e32 v65, v65, v152
	v_mul_f32_e32 v66, v66, v152
	v_mul_f32_e32 v67, v67, v152
	v_mul_f32_e32 v68, v68, v152
	v_mul_f32_e32 v69, v69, v152
	v_fma_f32 v54, v54, v0, v16
	v_fma_f32 v55, v55, v1, v17
	v_fma_f32 v56, v56, v2, v18
	v_fma_f32 v57, v57, v3, v19
	v_fma_f32 v58, v58, v4, v20
	v_fma_f32 v59, v59, v5, v21
	v_fma_f32 v60, v60, v6, v22
	v_fma_f32 v61, v61, v7, v23
	v_fma_f32 v62, v62, v8, v24
	v_fma_f32 v63, v63, v9, v25
	v_fma_f32 v64, v64, v10, v26
	v_fma_f32 v65, v65, v11, v27
	v_fma_f32 v66, v66, v12, v28
	v_fma_f32 v67, v67, v13, v29
	v_fma_f32 v68, v68, v14, v30
	v_fma_f32 v69, v69, v15, v31
	v_cvt_pk_f16_f32 v70, v54, v55
	v_cvt_pk_f16_f32 v71, v56, v57
	v_cvt_pk_f16_f32 v72, v58, v59
	v_cvt_pk_f16_f32 v73, v60, v61
	v_cvt_pk_f16_f32 v74, v62, v63
	v_cvt_pk_f16_f32 v75, v64, v65
	v_cvt_pk_f16_f32 v76, v66, v67
	v_cvt_pk_f16_f32 v77, v68, v69
	global_store_dwordx2 v151, v[70:71], s[36:37] offset:0
	global_store_dwordx2 v151, v[72:73], s[36:37] offset:512
	global_store_dwordx2 v151, v[74:75], s[36:37] offset:1024
	global_store_dwordx2 v151, v[76:77], s[36:37] offset:1536
	s_add_u32 s5, s5, 1
	s_sub_u32 s9, s5, 0x800
	s_lshr_b32 s9, s9, 13
	s_cmp_lt_u32 s5, 0x800
	s_cselect_b32 s9, 8, s9
	s_cmp_eq_u32 s9, s8
	s_cbranch_scc1 .Lr1a_nr10
	s_mov_b32 s8, s9
	s_waitcnt vmcnt(0)
	s_add_u32 s10, s9, 0
	s_mul_i32 s10, s10, 0x6000
	s_add_u32 s38, s56, s10
	s_addc_u32 s39, s57, 0
	global_load_dwordx4 v[54:57], v150, s[58:59] offset:0
	global_load_dwordx4 v[58:61], v150, s[58:59] offset:1024
	global_load_dwordx4 v[62:65], v150, s[58:59] offset:2048
	global_load_dwordx4 v[66:69], v150, s[58:59] offset:3072
	s_add_u32 s44, s38, 0x1000
	s_addc_u32 s45, s39, 0
	global_load_dwordx4 v[70:73], v150, s[44:45] offset:0
	global_load_dwordx4 v[74:77], v150, s[44:45] offset:1024
	global_load_dwordx4 v[78:81], v150, s[44:45] offset:2048
	global_load_dwordx4 v[82:85], v150, s[44:45] offset:3072
	global_load_dwordx4 v[16:19], v150, s[38:39] offset:0
	global_load_dwordx4 v[20:23], v150, s[38:39] offset:1024
	global_load_dwordx4 v[24:27], v150, s[38:39] offset:2048
	global_load_dwordx4 v[28:31], v150, s[38:39] offset:3072
	s_waitcnt vmcnt(0)
	v_add_f32_e32 v70, 1.0, v70
	v_add_f32_e32 v71, 1.0, v71
	v_add_f32_e32 v72, 1.0, v72
	v_add_f32_e32 v73, 1.0, v73
	v_add_f32_e32 v74, 1.0, v74
	v_add_f32_e32 v75, 1.0, v75
	v_add_f32_e32 v76, 1.0, v76
	v_add_f32_e32 v77, 1.0, v77
	v_add_f32_e32 v78, 1.0, v78
	v_add_f32_e32 v79, 1.0, v79
	v_add_f32_e32 v80, 1.0, v80
	v_add_f32_e32 v81, 1.0, v81
	v_add_f32_e32 v82, 1.0, v82
	v_add_f32_e32 v83, 1.0, v83
	v_add_f32_e32 v84, 1.0, v84
	v_add_f32_e32 v85, 1.0, v85
	v_mul_f32_e32 v0, v54, v70
	v_mul_f32_e32 v1, v55, v71
	v_mul_f32_e32 v2, v56, v72
	v_mul_f32_e32 v3, v57, v73
	v_mul_f32_e32 v4, v58, v74
	v_mul_f32_e32 v5, v59, v75
	v_mul_f32_e32 v6, v60, v76
	v_mul_f32_e32 v7, v61, v77
	v_mul_f32_e32 v8, v62, v78
	v_mul_f32_e32 v9, v63, v79
	v_mul_f32_e32 v10, v64, v80
	v_mul_f32_e32 v11, v65, v81
	v_mul_f32_e32 v12, v66, v82
	v_mul_f32_e32 v13, v67, v83
	v_mul_f32_e32 v14, v68, v84
	v_mul_f32_e32 v15, v69, v85
; DI void row1_phase(const Params& P, int combine_l, int norm_l, int r_begin) {
;     ...
;     if (norm_l >= 0) {
;       float ss = 0.f;
; #pragma unroll
;       for (int i = 0; i < 4; i++) ss += xv[i].x * xv[i].x + xv[i].y * xv[i].y + xv[i].z * xv[i].z + xv[i].w * xv[i].w;
;       ss = wave_sum(ss);
;       const float rstd = rsqrtf(ss * (1.f / 1024.f) + EPS);
;       const float* g = P.norm1_g + norm_l * 1024;
;       const float* sh = P.mod + (size_t)(norm_l * 9 + n) * 6144; const float* sc = sh + 1024;
; #pragma unroll
;       for (int i = 0; i < 4; i++) {
;         int c = i * 256 + lane * 4;
;         float4 gg = *(const float4*)(g + c), s1 = *(const float4*)(sc + c), s0 = *(const float4*)(sh + c);
;         h4 o;
;         o[0] = (half_t)(xv[i].x * rstd * gg.x * (1.f + s1.x) + s0.x); o[1] = (half_t)(xv[i].y * rstd * gg.y * (1.f + s1.y) + s0.y);
;         o[2] = (half_t)(xv[i].z * rstd * gg.z * (1.f + s1.z) + s0.z); o[3] = (half_t)(xv[i].w * rstd * gg.w * (1.f + s1.w) + s0.w);
;         *(h4*)(P.hx + (size_t)r * D + c) = o;
;       }
.Lr1a_nr10:
	s_waitcnt vmcnt(4)
	v_accvgpr_read_b32 v54, a32
	v_accvgpr_read_b32 v55, a33
	v_accvgpr_read_b32 v56, a34
	v_accvgpr_read_b32 v57, a35
	v_accvgpr_read_b32 v58, a36
	v_accvgpr_read_b32 v59, a37
	v_accvgpr_read_b32 v60, a38
	v_accvgpr_read_b32 v61, a39
	v_accvgpr_read_b32 v62, a40
	v_accvgpr_read_b32 v63, a41
	v_accvgpr_read_b32 v64, a42
	v_accvgpr_read_b32 v65, a43
	v_accvgpr_read_b32 v66, a44
	v_accvgpr_read_b32 v67, a45
	v_accvgpr_read_b32 v68, a46
	v_accvgpr_read_b32 v69, a47
	s_lshl_b32 s10, s5, 12
	s_lshr_b32 s10, s10, 1
	s_add_u32 s36, s54, s10
	s_addc_u32 s37, s55, 0
	v_mul_f32_e32 v152, v54, v54
	v_mul_f32_e32 v153, v55, v55
	v_fmac_f32_e32 v152, v56, v56
	v_fmac_f32_e32 v153, v57, v57
	v_fmac_f32_e32 v152, v58, v58
	v_fmac_f32_e32 v153, v59, v59
	v_fmac_f32_e32 v152, v60, v60
	v_fmac_f32_e32 v153, v61, v61
	v_fmac_f32_e32 v152, v62, v62
	v_fmac_f32_e32 v153, v63, v63
	v_fmac_f32_e32 v152, v64, v64
	v_fmac_f32_e32 v153, v65, v65
	v_fmac_f32_e32 v152, v66, v66
	v_fmac_f32_e32 v153, v67, v67
	v_fmac_f32_e32 v152, v68, v68
	v_fmac_f32_e32 v153, v69, v69
	v_add_f32_e32 v152, v152, v153
	s_nop 1
	v_add_f32_dpp v152, v152, v152 row_ror:8 row_mask:0xf bank_mask:0xf
	s_nop 1
	v_add_f32_dpp v152, v152, v152 row_ror:4 row_mask:0xf bank_mask:0xf
	s_nop 1
	v_add_f32_dpp v152, v152, v152 row_ror:2 row_mask:0xf bank_mask:0xf
	s_nop 1
	v_add_f32_dpp v152, v152, v152 row_ror:1 row_mask:0xf bank_mask:0xf
	s_nop 1
	v_readlane_b32 s22, v152, 0
	v_readlane_b32 s23, v152, 16
	v_readlane_b32 s32, v152, 32
	v_readlane_b32 s99, v152, 48
	v_mov_b32_e32 v152, s22
	v_add_f32_e32 v152, s23, v152
	v_add_f32_e32 v152, s32, v152
	v_add_f32_e32 v152, s99, v152
	v_mov_b32_e32 v153, 0x358637bd
	v_fmamk_f32 v152, v152, 0x3a800000, v153
	v_rsq_f32_e32 v152, v152
	s_nop 1
	v_mul_f32_e32 v54, v54, v152
	v_mul_f32_e32 v55, v55, v152
	v_mul_f32_e32 v56, v56, v152
	v_mul_f32_e32 v57, v57, v152
	v_mul_f32_e32 v58, v58, v152
	v_mul_f32_e32 v59, v59, v152
	v_mul_f32_e32 v60, v60, v152
	v_mul_f32_e32 v61, v61, v152
	v_mul_f32_e32 v62, v62, v152
	v_mul_f32_e32 v63, v63, v152
	v_mul_f32_e32 v64, v64, v152
	v_mul_f32_e32 v65, v65, v152
	v_mul_f32_e32 v66, v66, v152
	v_mul_f32_e32 v67, v67, v152
	v_mul_f32_e32 v68, v68, v152
	v_mul_f32_e32 v69, v69, v152
	v_fma_f32 v54, v54, v0, v16
	v_fma_f32 v55, v55, v1, v17
	v_fma_f32 v56, v56, v2, v18
	v_fma_f32 v57, v57, v3, v19
	v_fma_f32 v58, v58, v4, v20
	v_fma_f32 v59, v59, v5, v21
	v_fma_f32 v60, v60, v6, v22
	v_fma_f32 v61, v61, v7, v23
	v_fma_f32 v62, v62, v8, v24
	v_fma_f32 v63, v63, v9, v25
	v_fma_f32 v64, v64, v10, v26
	v_fma_f32 v65, v65, v11, v27
	v_fma_f32 v66, v66, v12, v28
	v_fma_f32 v67, v67, v13, v29
	v_fma_f32 v68, v68, v14, v30
	v_fma_f32 v69, v69, v15, v31
	v_cvt_pk_f16_f32 v70, v54, v55
	v_cvt_pk_f16_f32 v71, v56, v57
	v_cvt_pk_f16_f32 v72, v58, v59
	v_cvt_pk_f16_f32 v73, v60, v61
	v_cvt_pk_f16_f32 v74, v62, v63
	v_cvt_pk_f16_f32 v75, v64, v65
	v_cvt_pk_f16_f32 v76, v66, v67
	v_cvt_pk_f16_f32 v77, v68, v69
	global_store_dwordx2 v151, v[70:71], s[36:37] offset:0
	global_store_dwordx2 v151, v[72:73], s[36:37] offset:512
	global_store_dwordx2 v151, v[74:75], s[36:37] offset:1024
	global_store_dwordx2 v151, v[76:77], s[36:37] offset:1536
	s_add_u32 s5, s5, 1
	s_waitcnt vmcnt(0)
